# static priority: all per-phase s_setprio flips in the GEMM loops removed, waves 4-7 raised to priority 1 once at kernel entry
# speedup vs baseline: 1.0125x; 1.0125x over previous
_Z14fwd_megakernel6Params:
	s_load_dwordx2 s[96:97], s[0:1], 0x128
	s_load_dword s52, s[0:1], 0x130
	s_add_u32 s54, s0, 0x128
	s_addc_u32 s55, s1, 0
	v_and_b32_e32 v171, 0x3ff, v0
	v_cmp_eq_u32_e64 s[6:7], 0, v171
	v_readfirstlane_b32 s3, v171
	s_nop 3
	s_lshr_b32 s3, s3, 6
	s_cmp_ge_u32 s3, 4
	s_cbranch_scc0 .Lprio_skip
	s_setprio 1
.Lprio_skip:
	s_mov_b64 s[4:5], exec
	s_nop 0
	v_writelane_b32 v252, s6, 0
	s_nop 1
	v_writelane_b32 v252, s7, 1
	s_and_b64 s[6:7], s[4:5], s[6:7]
	s_mov_b64 exec, s[6:7]
	s_cbranch_execz .LBB0_2
	s_add_i32 s3, 0, 0x22000
	v_mov_b32_e32 v1, 0
	v_mov_b32_e32 v2, s3
	s_add_i32 s3, 0, 0x22004
	ds_write_b32 v2, v1
	v_mov_b32_e32 v2, s3
	s_add_i32 s3, 0, 0x22008
	ds_write_b32 v2, v1
	v_mov_b32_e32 v2, s3
	s_add_i32 s3, 0, 0x2200c
	ds_write_b32 v2, v1
	v_mov_b32_e32 v2, s3
	ds_write_b32 v2, v1

.LBB0_191:
	s_add_u32 s36, s44, 0xfffc0080
	s_addc_u32 s37, s45, -1
	s_add_i32 s38, 0, 0x10000
	v_add_u32_e32 v152, s38, v142
	ds_read_b128 v[138:141], v152
	ds_read_b128 v[144:147], v152 offset:1024
	ds_read_b128 v[148:151], v152 offset:2048
	ds_read_b128 v[152:155], v152 offset:3072
	s_cmp_eq_u32 s61, 12
	s_cselect_b32 s49, s13, s37
	s_cselect_b32 s48, s34, s36
	s_cselect_b32 s47, s9, s60
	s_cselect_b32 s46, s35, s59
	v_lshl_add_u64 v[172:173], s[44:45], 0, v[134:135]
	s_add_i32 m0, s30, 0xc000
	ds_read_b128 v[156:159], v143
	ds_read_b128 v[160:163], v143 offset:1024
	ds_read_b128 v[164:167], v143 offset:2048
	ds_read_b128 v[180:183], v143 offset:3072
	ds_read_b128 v[184:187], v143 offset:4096
	ds_read_b128 v[188:191], v143 offset:5120
	ds_read_b128 v[192:195], v143 offset:6144
	ds_read_b128 v[196:199], v143 offset:7168
	global_load_lds_dwordx4 v[172:173], off
	v_lshl_add_u64 v[172:173], s[44:45], 0, v[136:137]
	s_add_i32 m0, s30, 0xe000
	s_nop 0
	global_load_lds_dwordx4 v[172:173], off
	s_waitcnt lgkmcnt(8)
	s_barrier
	s_waitcnt lgkmcnt(0)
	s_waitcnt lgkmcnt(0)
	v_mfma_f32_16x16x32_bf16 v[124:127], v[138:141], v[156:159], v[124:127]
	v_mfma_f32_16x16x32_bf16 v[116:119], v[148:151], v[156:159], v[116:119]
	v_mfma_f32_16x16x32_bf16 v[108:111], v[138:141], v[164:167], v[108:111]
	v_mfma_f32_16x16x32_bf16 v[100:103], v[148:151], v[164:167], v[100:103]
	v_mfma_f32_16x16x32_bf16 v[92:95], v[138:141], v[184:187], v[92:95]
	v_mfma_f32_16x16x32_bf16 v[84:87], v[148:151], v[184:187], v[84:87]
	v_mfma_f32_16x16x32_bf16 v[76:79], v[138:141], v[192:195], v[76:79]
	v_mfma_f32_16x16x32_bf16 v[68:71], v[148:151], v[192:195], v[68:71]
	v_mfma_f32_16x16x32_bf16 v[124:127], v[144:147], v[160:163], v[124:127]
	v_mfma_f32_16x16x32_bf16 v[116:119], v[152:155], v[160:163], v[116:119]
	v_mfma_f32_16x16x32_bf16 v[108:111], v[144:147], v[180:183], v[108:111]
	v_mfma_f32_16x16x32_bf16 v[100:103], v[152:155], v[180:183], v[100:103]
	v_mfma_f32_16x16x32_bf16 v[92:95], v[144:147], v[188:191], v[92:95]
	v_mfma_f32_16x16x32_bf16 v[84:87], v[152:155], v[188:191], v[84:87]
	v_mfma_f32_16x16x32_bf16 v[76:79], v[144:147], v[196:199], v[76:79]
	v_mfma_f32_16x16x32_bf16 v[68:71], v[152:155], v[196:199], v[68:71]
	s_barrier
	s_add_i32 s39, 0, 0x14000
	v_add_u32_e32 v172, s39, v142
	s_add_i32 s36, s38, s29
	ds_read_b128 v[200:203], v172
	ds_read_b128 v[204:207], v172 offset:1024
	ds_read_b128 v[208:211], v172 offset:2048
	ds_read_b128 v[212:215], v172 offset:3072
	v_lshl_add_u64 v[172:173], s[46:47], 0, v[168:169]
	s_mov_b32 m0, s36
	v_lshl_add_u64 v[174:175], s[46:47], 0, v[128:129]
	global_load_lds_dwordx4 v[172:173], off
	s_add_i32 m0, s36, 0x2000
	s_nop 0
	global_load_lds_dwordx4 v[174:175], off
	s_barrier
	s_waitcnt lgkmcnt(0)
	s_waitcnt lgkmcnt(0)
	v_mfma_f32_16x16x32_bf16 v[120:123], v[200:203], v[156:159], v[120:123]
	v_mfma_f32_16x16x32_bf16 v[112:115], v[208:211], v[156:159], v[112:115]
	v_mfma_f32_16x16x32_bf16 v[104:107], v[200:203], v[164:167], v[104:107]
	v_mfma_f32_16x16x32_bf16 v[96:99], v[208:211], v[164:167], v[96:99]
	v_mfma_f32_16x16x32_bf16 v[88:91], v[200:203], v[184:187], v[88:91]
	v_mfma_f32_16x16x32_bf16 v[80:83], v[208:211], v[184:187], v[80:83]
	v_mfma_f32_16x16x32_bf16 v[72:75], v[200:203], v[192:195], v[72:75]
	v_mfma_f32_16x16x32_bf16 v[64:67], v[208:211], v[192:195], v[64:67]
	v_mfma_f32_16x16x32_bf16 v[120:123], v[204:207], v[160:163], v[120:123]
	v_mfma_f32_16x16x32_bf16 v[112:115], v[212:215], v[160:163], v[112:115]
	v_mfma_f32_16x16x32_bf16 v[104:107], v[204:207], v[180:183], v[104:107]
	v_mfma_f32_16x16x32_bf16 v[96:99], v[212:215], v[180:183], v[96:99]
	v_mfma_f32_16x16x32_bf16 v[88:91], v[204:207], v[188:191], v[88:91]
	v_mfma_f32_16x16x32_bf16 v[80:83], v[212:215], v[188:191], v[80:83]
	v_mfma_f32_16x16x32_bf16 v[72:75], v[204:207], v[196:199], v[72:75]
	v_mfma_f32_16x16x32_bf16 v[64:67], v[212:215], v[196:199], v[64:67]
	s_mov_b32 m0, s30
	v_lshl_add_u64 v[176:177], s[48:49], 0, v[132:133]
	s_barrier
	ds_read_b128 v[156:159], v143 offset:16384
	ds_read_b128 v[160:163], v143 offset:17408
	ds_read_b128 v[164:167], v143 offset:18432
	ds_read_b128 v[180:183], v143 offset:19456
	ds_read_b128 v[184:187], v143 offset:20480
	ds_read_b128 v[188:191], v143 offset:21504
	ds_read_b128 v[192:195], v143 offset:22528
	ds_read_b128 v[196:199], v143 offset:23552
	global_load_lds_dwordx4 v[176:177], off
	v_lshl_add_u64 v[178:179], s[48:49], 0, v[130:131]
	s_mov_b32 m0, s31
	s_nop 0
	global_load_lds_dwordx4 v[178:179], off
	s_barrier
	s_waitcnt lgkmcnt(0)
	s_waitcnt lgkmcnt(0)
	v_mfma_f32_16x16x32_bf16 v[60:63], v[138:141], v[156:159], v[60:63]
	v_mfma_f32_16x16x32_bf16 v[52:55], v[148:151], v[156:159], v[52:55]
	v_mfma_f32_16x16x32_bf16 v[44:47], v[138:141], v[164:167], v[44:47]
	v_mfma_f32_16x16x32_bf16 v[36:39], v[148:151], v[164:167], v[36:39]
	v_mfma_f32_16x16x32_bf16 v[28:31], v[138:141], v[184:187], v[28:31]
	v_mfma_f32_16x16x32_bf16 v[20:23], v[148:151], v[184:187], v[20:23]
	v_mfma_f32_16x16x32_bf16 v[12:15], v[138:141], v[192:195], v[12:15]
	v_mfma_f32_16x16x32_bf16 v[4:7], v[148:151], v[192:195], v[4:7]
	v_mfma_f32_16x16x32_bf16 v[60:63], v[144:147], v[160:163], v[60:63]
	v_mfma_f32_16x16x32_bf16 v[52:55], v[152:155], v[160:163], v[52:55]
	v_mfma_f32_16x16x32_bf16 v[44:47], v[144:147], v[180:183], v[44:47]
	v_mfma_f32_16x16x32_bf16 v[36:39], v[152:155], v[180:183], v[36:39]
	v_mfma_f32_16x16x32_bf16 v[28:31], v[144:147], v[188:191], v[28:31]
	v_mfma_f32_16x16x32_bf16 v[20:23], v[152:155], v[188:191], v[20:23]
	v_mfma_f32_16x16x32_bf16 v[12:15], v[144:147], v[196:199], v[12:15]
	v_mfma_f32_16x16x32_bf16 v[4:7], v[152:155], v[196:199], v[4:7]
	s_barrier
	s_add_u32 s36, s46, 0x40000
	s_addc_u32 s37, s47, 0
	s_add_i32 s38, s39, s29
	v_lshl_add_u64 v[138:139], s[36:37], 0, v[168:169]
	s_mov_b32 m0, s38
	s_nop 0
	global_load_lds_dwordx4 v[138:139], off
	v_lshl_add_u64 v[138:139], s[36:37], 0, v[128:129]
	s_add_i32 m0, s38, 0x2000
	s_nop 0
	global_load_lds_dwordx4 v[138:139], off
	s_waitcnt vmcnt(6)
	s_barrier
	v_mfma_f32_16x16x32_bf16 v[56:59], v[200:203], v[156:159], v[56:59]
	v_mfma_f32_16x16x32_bf16 v[48:51], v[208:211], v[156:159], v[48:51]
	v_mfma_f32_16x16x32_bf16 v[40:43], v[200:203], v[164:167], v[40:43]
	v_mfma_f32_16x16x32_bf16 v[32:35], v[208:211], v[164:167], v[32:35]
	v_mfma_f32_16x16x32_bf16 v[24:27], v[200:203], v[184:187], v[24:27]
	v_mfma_f32_16x16x32_bf16 v[16:19], v[208:211], v[184:187], v[16:19]
	v_mfma_f32_16x16x32_bf16 v[8:11], v[200:203], v[192:195], v[8:11]
	v_mfma_f32_16x16x32_bf16 v[0:3], v[208:211], v[192:195], v[0:3]
	v_mfma_f32_16x16x32_bf16 v[56:59], v[204:207], v[160:163], v[56:59]
	v_mfma_f32_16x16x32_bf16 v[48:51], v[212:215], v[160:163], v[48:51]
	v_mfma_f32_16x16x32_bf16 v[40:43], v[204:207], v[180:183], v[40:43]
	v_mfma_f32_16x16x32_bf16 v[32:35], v[212:215], v[180:183], v[32:35]
	v_mfma_f32_16x16x32_bf16 v[24:27], v[204:207], v[188:191], v[24:27]
	v_mfma_f32_16x16x32_bf16 v[16:19], v[212:215], v[188:191], v[16:19]
	v_mfma_f32_16x16x32_bf16 v[8:11], v[204:207], v[196:199], v[8:11]
	v_mfma_f32_16x16x32_bf16 v[0:3], v[212:215], v[196:199], v[0:3]
	s_add_i32 s38, 0, 0x18000
	v_add_u32_e32 v152, s38, v142
	s_barrier
	ds_read_b128 v[138:141], v152
	ds_read_b128 v[144:147], v152 offset:1024
	ds_read_b128 v[148:151], v152 offset:2048
	ds_read_b128 v[152:155], v152 offset:3072
	s_add_u32 s36, s48, 0x40000
	s_addc_u32 s37, s49, 0
	s_mov_b32 m0, s50
	v_lshl_add_u64 v[200:201], s[36:37], 0, v[132:133]
	ds_read_b128 v[156:159], v143 offset:32768
	ds_read_b128 v[160:163], v143 offset:33792
	ds_read_b128 v[164:167], v143 offset:34816
	ds_read_b128 v[180:183], v143 offset:35840
	ds_read_b128 v[184:187], v143 offset:36864
	ds_read_b128 v[188:191], v143 offset:37888
	ds_read_b128 v[192:195], v143 offset:38912
	ds_read_b128 v[196:199], v143 offset:39936
	global_load_lds_dwordx4 v[200:201], off
	v_lshl_add_u64 v[200:201], s[36:37], 0, v[130:131]
	s_mov_b32 m0, s51
	s_nop 0
	global_load_lds_dwordx4 v[200:201], off
	s_waitcnt lgkmcnt(8)
	s_barrier
	s_waitcnt lgkmcnt(0)
	s_waitcnt lgkmcnt(0)
	v_mfma_f32_16x16x32_bf16 v[124:127], v[138:141], v[156:159], v[124:127]
	v_mfma_f32_16x16x32_bf16 v[116:119], v[148:151], v[156:159], v[116:119]
	v_mfma_f32_16x16x32_bf16 v[108:111], v[138:141], v[164:167], v[108:111]
	v_mfma_f32_16x16x32_bf16 v[100:103], v[148:151], v[164:167], v[100:103]
	v_mfma_f32_16x16x32_bf16 v[92:95], v[138:141], v[184:187], v[92:95]
	v_mfma_f32_16x16x32_bf16 v[84:87], v[148:151], v[184:187], v[84:87]
	v_mfma_f32_16x16x32_bf16 v[76:79], v[138:141], v[192:195], v[76:79]
	v_mfma_f32_16x16x32_bf16 v[68:71], v[148:151], v[192:195], v[68:71]
	v_mfma_f32_16x16x32_bf16 v[124:127], v[144:147], v[160:163], v[124:127]
	v_mfma_f32_16x16x32_bf16 v[116:119], v[152:155], v[160:163], v[116:119]
	v_mfma_f32_16x16x32_bf16 v[108:111], v[144:147], v[180:183], v[108:111]
	v_mfma_f32_16x16x32_bf16 v[100:103], v[152:155], v[180:183], v[100:103]
	v_mfma_f32_16x16x32_bf16 v[92:95], v[144:147], v[188:191], v[92:95]
	v_mfma_f32_16x16x32_bf16 v[84:87], v[152:155], v[188:191], v[84:87]
	v_mfma_f32_16x16x32_bf16 v[76:79], v[144:147], v[196:199], v[76:79]
	v_mfma_f32_16x16x32_bf16 v[68:71], v[152:155], v[196:199], v[68:71]
	s_barrier
	s_add_i32 s39, 0, 0x1c000
	s_add_i32 s36, s38, s29
	v_add_u32_e32 v212, s39, v142
	v_lshl_add_u64 v[172:173], v[172:173], 0, s[88:89]
	s_mov_b32 m0, s36
	ds_read_b128 v[200:203], v212
	ds_read_b128 v[204:207], v212 offset:1024
	ds_read_b128 v[208:211], v212 offset:2048
	ds_read_b128 v[212:215], v212 offset:3072
	global_load_lds_dwordx4 v[172:173], off
	v_lshl_add_u64 v[172:173], v[174:175], 0, s[88:89]
	s_add_i32 m0, s36, 0x2000
	s_nop 0
	global_load_lds_dwordx4 v[172:173], off
	s_barrier
	s_waitcnt lgkmcnt(0)
	s_waitcnt lgkmcnt(0)
	v_mfma_f32_16x16x32_bf16 v[120:123], v[200:203], v[156:159], v[120:123]
	v_mfma_f32_16x16x32_bf16 v[112:115], v[208:211], v[156:159], v[112:115]
	v_mfma_f32_16x16x32_bf16 v[104:107], v[200:203], v[164:167], v[104:107]
	v_mfma_f32_16x16x32_bf16 v[96:99], v[208:211], v[164:167], v[96:99]
	v_mfma_f32_16x16x32_bf16 v[88:91], v[200:203], v[184:187], v[88:91]
	v_mfma_f32_16x16x32_bf16 v[80:83], v[208:211], v[184:187], v[80:83]
	v_mfma_f32_16x16x32_bf16 v[72:75], v[200:203], v[192:195], v[72:75]
	v_mfma_f32_16x16x32_bf16 v[64:67], v[208:211], v[192:195], v[64:67]
	v_mfma_f32_16x16x32_bf16 v[120:123], v[204:207], v[160:163], v[120:123]
	v_mfma_f32_16x16x32_bf16 v[112:115], v[212:215], v[160:163], v[112:115]
	v_mfma_f32_16x16x32_bf16 v[104:107], v[204:207], v[180:183], v[104:107]
	v_mfma_f32_16x16x32_bf16 v[96:99], v[212:215], v[180:183], v[96:99]
	v_mfma_f32_16x16x32_bf16 v[88:91], v[204:207], v[188:191], v[88:91]
	v_mfma_f32_16x16x32_bf16 v[80:83], v[212:215], v[188:191], v[80:83]
	v_mfma_f32_16x16x32_bf16 v[72:75], v[204:207], v[196:199], v[72:75]
	v_mfma_f32_16x16x32_bf16 v[64:67], v[212:215], v[196:199], v[64:67]
	s_mov_b32 m0, s54
	v_lshl_add_u64 v[172:173], v[176:177], 0, s[88:89]
	s_barrier
	ds_read_b128 v[156:159], v143 offset:49152
	ds_read_b128 v[160:163], v143 offset:50176
	ds_read_b128 v[164:167], v143 offset:51200
	ds_read_b128 v[180:183], v143 offset:52224
	ds_read_b128 v[184:187], v143 offset:53248
	ds_read_b128 v[188:191], v143 offset:54272
	ds_read_b128 v[192:195], v143 offset:55296
	ds_read_b128 v[196:199], v143 offset:56320
	global_load_lds_dwordx4 v[172:173], off
	v_lshl_add_u64 v[172:173], v[178:179], 0, s[88:89]
	s_mov_b32 m0, s55
	s_nop 0
	global_load_lds_dwordx4 v[172:173], off
	s_barrier
	s_waitcnt lgkmcnt(0)
	s_waitcnt lgkmcnt(0)
	v_mfma_f32_16x16x32_bf16 v[60:63], v[138:141], v[156:159], v[60:63]
	v_mfma_f32_16x16x32_bf16 v[52:55], v[148:151], v[156:159], v[52:55]
	v_mfma_f32_16x16x32_bf16 v[44:47], v[138:141], v[164:167], v[44:47]
	v_mfma_f32_16x16x32_bf16 v[36:39], v[148:151], v[164:167], v[36:39]
	v_mfma_f32_16x16x32_bf16 v[28:31], v[138:141], v[184:187], v[28:31]
	v_mfma_f32_16x16x32_bf16 v[20:23], v[148:151], v[184:187], v[20:23]
	v_mfma_f32_16x16x32_bf16 v[12:15], v[138:141], v[192:195], v[12:15]
	v_mfma_f32_16x16x32_bf16 v[4:7], v[148:151], v[192:195], v[4:7]
	v_mfma_f32_16x16x32_bf16 v[60:63], v[144:147], v[160:163], v[60:63]
	v_mfma_f32_16x16x32_bf16 v[52:55], v[152:155], v[160:163], v[52:55]
	v_mfma_f32_16x16x32_bf16 v[44:47], v[144:147], v[180:183], v[44:47]
	v_mfma_f32_16x16x32_bf16 v[36:39], v[152:155], v[180:183], v[36:39]
	v_mfma_f32_16x16x32_bf16 v[28:31], v[144:147], v[188:191], v[28:31]
	v_mfma_f32_16x16x32_bf16 v[20:23], v[152:155], v[188:191], v[20:23]
	v_mfma_f32_16x16x32_bf16 v[12:15], v[144:147], v[196:199], v[12:15]
	v_mfma_f32_16x16x32_bf16 v[4:7], v[152:155], v[196:199], v[4:7]
	s_barrier
	s_add_u32 s36, s46, 0x40080
	s_addc_u32 s37, s47, 0
	s_add_i32 s38, s39, s29
	v_lshl_add_u64 v[138:139], s[36:37], 0, v[168:169]
	s_mov_b32 m0, s38
	s_nop 0
	global_load_lds_dwordx4 v[138:139], off
	v_lshl_add_u64 v[138:139], s[36:37], 0, v[128:129]
	s_add_i32 m0, s38, 0x2000
	s_nop 0
	global_load_lds_dwordx4 v[138:139], off
	s_waitcnt vmcnt(6)
	s_barrier
	v_mfma_f32_16x16x32_bf16 v[56:59], v[200:203], v[156:159], v[56:59]
	v_mfma_f32_16x16x32_bf16 v[48:51], v[208:211], v[156:159], v[48:51]
	v_mfma_f32_16x16x32_bf16 v[40:43], v[200:203], v[164:167], v[40:43]
	v_mfma_f32_16x16x32_bf16 v[32:35], v[208:211], v[164:167], v[32:35]
	v_mfma_f32_16x16x32_bf16 v[24:27], v[200:203], v[184:187], v[24:27]
	v_mfma_f32_16x16x32_bf16 v[16:19], v[208:211], v[184:187], v[16:19]
	v_mfma_f32_16x16x32_bf16 v[8:11], v[200:203], v[192:195], v[8:11]
	v_mfma_f32_16x16x32_bf16 v[0:3], v[208:211], v[192:195], v[0:3]
	v_mfma_f32_16x16x32_bf16 v[56:59], v[204:207], v[160:163], v[56:59]
	v_mfma_f32_16x16x32_bf16 v[48:51], v[212:215], v[160:163], v[48:51]
	v_mfma_f32_16x16x32_bf16 v[40:43], v[204:207], v[180:183], v[40:43]
	v_mfma_f32_16x16x32_bf16 v[32:35], v[212:215], v[180:183], v[32:35]
	v_mfma_f32_16x16x32_bf16 v[24:27], v[204:207], v[188:191], v[24:27]
	v_mfma_f32_16x16x32_bf16 v[16:19], v[212:215], v[188:191], v[16:19]
	v_mfma_f32_16x16x32_bf16 v[8:11], v[204:207], v[196:199], v[8:11]
	v_mfma_f32_16x16x32_bf16 v[0:3], v[212:215], v[196:199], v[0:3]
	s_add_i32 s61, s61, 2
	s_add_u32 s44, s44, 0x100
	s_addc_u32 s45, s45, 0
	s_add_u32 s59, s59, 0x100
	s_addc_u32 s60, s60, 0
	s_cmp_gt_u32 s61, 13
	s_barrier
	s_cbranch_scc0 .LBB0_191
	v_mul_f32_e32 v145, 0xbfb8aa3b, v124
	v_exp_f32_e32 v145, v145
	v_mov_b32_e32 v138, v171
	s_lshl_b32 s9, s58, 8
	v_add_f32_e32 v145, 1.0, v145
	v_rcp_f32_e32 v148, v145
	v_mul_f32_e32 v145, 0xbfb8aa3b, v125
	v_exp_f32_e32 v145, v145
	s_add_i32 s9, s9, s52
	v_and_or_b32 v144, v138, 15, s9
	s_lshl_b32 s9, s57, 7
	v_add_f32_e32 v145, 1.0, v145
	v_rcp_f32_e32 v149, v145
	v_lshrrev_b32_e32 v138, 1, v138
	v_and_or_b32 v138, v138, 24, s9
	v_or_b32_e32 v140, s53, v138
	v_pk_mul_f32 v[124:125], v[124:125], v[148:149]
	v_ashrrev_i32_e32 v141, 31, v140
	v_pk_mul_f32 v[120:121], v[124:125], v[120:121]
	v_mov_b64_e32 v[138:139], s[6:7]
	v_cvt_pk_bf16_f32 v120, v120, v121
	v_mul_f32_e32 v121, 0xbfb8aa3b, v126
	v_exp_f32_e32 v121, v121
	v_mad_i64_i32 v[146:147], s[34:35], v144, s18, v[138:139]
	v_lshlrev_b64 v[140:141], 1, v[140:141]
	v_add_f32_e32 v121, 1.0, v121
	v_rcp_f32_e32 v124, v121
	v_mul_f32_e32 v121, 0xbfb8aa3b, v127
	v_exp_f32_e32 v121, v121
	v_lshl_add_u64 v[146:147], v[146:147], 0, v[140:141]
	s_and_b64 vcc, exec, s[40:41]
	s_mov_b32 s57, s8
	v_add_f32_e32 v121, 1.0, v121
	v_rcp_f32_e32 v125, v121
	s_mov_b32 s58, s12
	s_mov_b64 s[46:47], s[42:43]
	s_mov_b64 s[44:45], s[14:15]
	v_pk_mul_f32 v[124:125], v[126:127], v[124:125]
	s_nop 0
	v_pk_mul_f32 v[122:123], v[124:125], v[122:123]
	s_nop 0
	v_cvt_pk_bf16_f32 v121, v122, v123
	v_mul_f32_e32 v122, 0xbfb8aa3b, v116
	v_mul_f32_e32 v123, 0xbfb8aa3b, v117
	v_exp_f32_e32 v122, v122
	v_exp_f32_e32 v123, v123
	v_add_f32_e32 v122, 1.0, v122
	v_add_f32_e32 v123, 1.0, v123
	v_rcp_f32_e32 v122, v122
	v_rcp_f32_e32 v123, v123
	s_nop 0
	v_pk_mul_f32 v[116:117], v[116:117], v[122:123]
	s_nop 0
	v_pk_mul_f32 v[112:113], v[116:117], v[112:113]
	s_nop 0
	v_cvt_pk_bf16_f32 v122, v112, v113
	v_mul_f32_e32 v112, 0xbfb8aa3b, v118
	v_mul_f32_e32 v113, 0xbfb8aa3b, v119
	v_exp_f32_e32 v112, v112
	v_exp_f32_e32 v113, v113
	v_add_f32_e32 v112, 1.0, v112
	v_add_f32_e32 v113, 1.0, v113
	v_rcp_f32_e32 v112, v112
	v_rcp_f32_e32 v113, v113
	s_nop 0
	v_pk_mul_f32 v[112:113], v[118:119], v[112:113]
	s_nop 0
	v_pk_mul_f32 v[112:113], v[112:113], v[114:115]
	v_mul_f32_e32 v114, 0xbfb8aa3b, v108
	v_mul_f32_e32 v115, 0xbfb8aa3b, v109
	v_exp_f32_e32 v114, v114
	v_exp_f32_e32 v115, v115
	v_cvt_pk_bf16_f32 v123, v112, v113
	v_or_b32_e32 v112, 16, v144
	v_add_f32_e32 v114, 1.0, v114
	v_add_f32_e32 v115, 1.0, v115
	v_rcp_f32_e32 v114, v114
	v_rcp_f32_e32 v115, v115
	v_mad_i64_i32 v[112:113], s[34:35], v112, s18, v[138:139]
	global_store_dwordx4 v[146:147], v[120:123], off
	v_pk_mul_f32 v[108:109], v[108:109], v[114:115]
	v_lshl_add_u64 v[112:113], v[112:113], 0, v[140:141]
	v_pk_mul_f32 v[104:105], v[108:109], v[104:105]
	s_nop 0
	v_cvt_pk_bf16_f32 v104, v104, v105
	v_mul_f32_e32 v105, 0xbfb8aa3b, v110
	v_exp_f32_e32 v105, v105
	s_nop 0
	v_add_f32_e32 v105, 1.0, v105
	v_rcp_f32_e32 v108, v105
	v_mul_f32_e32 v105, 0xbfb8aa3b, v111
	v_exp_f32_e32 v105, v105
	s_nop 0
	v_add_f32_e32 v105, 1.0, v105
	v_rcp_f32_e32 v109, v105
	s_nop 0
	v_pk_mul_f32 v[108:109], v[110:111], v[108:109]
	s_nop 0
	v_pk_mul_f32 v[106:107], v[108:109], v[106:107]
	s_nop 0
	v_cvt_pk_bf16_f32 v105, v106, v107
	v_mul_f32_e32 v106, 0xbfb8aa3b, v100
	v_mul_f32_e32 v107, 0xbfb8aa3b, v101
	v_exp_f32_e32 v106, v106
	v_exp_f32_e32 v107, v107
	v_add_f32_e32 v106, 1.0, v106
	v_add_f32_e32 v107, 1.0, v107
	v_rcp_f32_e32 v106, v106
	v_rcp_f32_e32 v107, v107
	s_nop 0
	v_pk_mul_f32 v[100:101], v[100:101], v[106:107]
	s_nop 0
	v_pk_mul_f32 v[96:97], v[100:101], v[96:97]
	s_nop 0
	v_cvt_pk_bf16_f32 v106, v96, v97
	v_mul_f32_e32 v96, 0xbfb8aa3b, v102
	v_mul_f32_e32 v97, 0xbfb8aa3b, v103
	v_exp_f32_e32 v96, v96
	v_exp_f32_e32 v97, v97
	v_add_f32_e32 v96, 1.0, v96
	v_add_f32_e32 v97, 1.0, v97
	v_rcp_f32_e32 v96, v96
	v_rcp_f32_e32 v97, v97
	s_nop 0
	v_pk_mul_f32 v[96:97], v[102:103], v[96:97]
	s_nop 0
	v_pk_mul_f32 v[96:97], v[96:97], v[98:99]
	v_mul_f32_e32 v98, 0xbfb8aa3b, v92
	v_mul_f32_e32 v99, 0xbfb8aa3b, v93
	v_exp_f32_e32 v98, v98
	v_exp_f32_e32 v99, v99
	v_cvt_pk_bf16_f32 v107, v96, v97
	v_or_b32_e32 v96, 32, v144
	v_add_f32_e32 v98, 1.0, v98
	v_add_f32_e32 v99, 1.0, v99
	v_rcp_f32_e32 v98, v98
	v_rcp_f32_e32 v99, v99
	v_mad_i64_i32 v[96:97], s[34:35], v96, s18, v[138:139]
	global_store_dwordx4 v[112:113], v[104:107], off
	v_pk_mul_f32 v[92:93], v[92:93], v[98:99]
	v_lshl_add_u64 v[96:97], v[96:97], 0, v[140:141]
	v_pk_mul_f32 v[88:89], v[92:93], v[88:89]
	s_nop 0
	v_cvt_pk_bf16_f32 v88, v88, v89
	v_mul_f32_e32 v89, 0xbfb8aa3b, v94
	v_exp_f32_e32 v89, v89
	s_nop 0
	v_add_f32_e32 v89, 1.0, v89
	v_rcp_f32_e32 v92, v89
	v_mul_f32_e32 v89, 0xbfb8aa3b, v95
	v_exp_f32_e32 v89, v89
	s_nop 0
	v_add_f32_e32 v89, 1.0, v89
	v_rcp_f32_e32 v93, v89
	s_nop 0
	v_pk_mul_f32 v[92:93], v[94:95], v[92:93]
	s_nop 0
	v_pk_mul_f32 v[90:91], v[92:93], v[90:91]
	s_nop 0
	v_cvt_pk_bf16_f32 v89, v90, v91
	v_mul_f32_e32 v90, 0xbfb8aa3b, v84
	v_mul_f32_e32 v91, 0xbfb8aa3b, v85
	v_exp_f32_e32 v90, v90
	v_exp_f32_e32 v91, v91
	v_add_f32_e32 v90, 1.0, v90
	v_add_f32_e32 v91, 1.0, v91
	v_rcp_f32_e32 v90, v90
	v_rcp_f32_e32 v91, v91
	s_nop 0
	v_pk_mul_f32 v[84:85], v[84:85], v[90:91]
	s_nop 0
	v_pk_mul_f32 v[80:81], v[84:85], v[80:81]
	s_nop 0
	v_cvt_pk_bf16_f32 v90, v80, v81
	v_mul_f32_e32 v80, 0xbfb8aa3b, v86
	v_mul_f32_e32 v81, 0xbfb8aa3b, v87
	v_exp_f32_e32 v80, v80
	v_exp_f32_e32 v81, v81
	v_add_f32_e32 v80, 1.0, v80
	v_add_f32_e32 v81, 1.0, v81
	v_rcp_f32_e32 v80, v80
	v_rcp_f32_e32 v81, v81
	s_nop 0
	v_pk_mul_f32 v[80:81], v[86:87], v[80:81]
	s_nop 0
	v_pk_mul_f32 v[80:81], v[80:81], v[82:83]
	v_mul_f32_e32 v82, 0xbfb8aa3b, v76
	v_mul_f32_e32 v83, 0xbfb8aa3b, v77
	v_exp_f32_e32 v82, v82
	v_exp_f32_e32 v83, v83
	v_cvt_pk_bf16_f32 v91, v80, v81
	v_or_b32_e32 v80, 48, v144
	v_add_f32_e32 v82, 1.0, v82
	v_add_f32_e32 v83, 1.0, v83
	v_rcp_f32_e32 v82, v82
	v_rcp_f32_e32 v83, v83
	v_mad_i64_i32 v[80:81], s[34:35], v80, s18, v[138:139]
	global_store_dwordx4 v[96:97], v[88:91], off
	v_pk_mul_f32 v[76:77], v[76:77], v[82:83]
	v_lshl_add_u64 v[80:81], v[80:81], 0, v[140:141]
	v_pk_mul_f32 v[72:73], v[76:77], v[72:73]
	s_nop 0
	v_cvt_pk_bf16_f32 v72, v72, v73
	v_mul_f32_e32 v73, 0xbfb8aa3b, v78
	v_exp_f32_e32 v73, v73
	s_nop 0
	v_add_f32_e32 v73, 1.0, v73
	v_rcp_f32_e32 v76, v73
	v_mul_f32_e32 v73, 0xbfb8aa3b, v79
	v_exp_f32_e32 v73, v73
	s_nop 0
	v_add_f32_e32 v73, 1.0, v73
	v_rcp_f32_e32 v77, v73
	s_nop 0
	v_pk_mul_f32 v[76:77], v[78:79], v[76:77]
	s_nop 0
	v_pk_mul_f32 v[74:75], v[76:77], v[74:75]
	s_nop 0
	v_cvt_pk_bf16_f32 v73, v74, v75
	v_mul_f32_e32 v74, 0xbfb8aa3b, v68
	v_mul_f32_e32 v75, 0xbfb8aa3b, v69
	v_exp_f32_e32 v74, v74
	v_exp_f32_e32 v75, v75
	v_add_f32_e32 v74, 1.0, v74
	v_add_f32_e32 v75, 1.0, v75
	v_rcp_f32_e32 v74, v74
	v_rcp_f32_e32 v75, v75
	s_nop 0
	v_pk_mul_f32 v[68:69], v[68:69], v[74:75]
	s_nop 0
	v_pk_mul_f32 v[64:65], v[68:69], v[64:65]
	s_nop 0
	v_cvt_pk_bf16_f32 v74, v64, v65
	v_mul_f32_e32 v64, 0xbfb8aa3b, v70
	v_mul_f32_e32 v65, 0xbfb8aa3b, v71
	v_exp_f32_e32 v64, v64
	v_exp_f32_e32 v65, v65
	v_add_f32_e32 v64, 1.0, v64
	v_add_f32_e32 v65, 1.0, v65
	v_rcp_f32_e32 v64, v64
	v_rcp_f32_e32 v65, v65
	s_nop 0
	v_pk_mul_f32 v[64:65], v[70:71], v[64:65]
	s_nop 0
	v_pk_mul_f32 v[64:65], v[64:65], v[66:67]
	v_mul_f32_e32 v66, 0xbfb8aa3b, v60
	v_mul_f32_e32 v67, 0xbfb8aa3b, v61
	v_exp_f32_e32 v66, v66
	v_exp_f32_e32 v67, v67
	v_cvt_pk_bf16_f32 v75, v64, v65
	v_add_u32_e32 v64, 0x80, v144
	v_add_f32_e32 v66, 1.0, v66
	v_add_f32_e32 v67, 1.0, v67
	v_rcp_f32_e32 v66, v66
	v_rcp_f32_e32 v67, v67
	v_mad_i64_i32 v[64:65], s[34:35], v64, s18, v[138:139]
	global_store_dwordx4 v[80:81], v[72:75], off
	v_pk_mul_f32 v[60:61], v[60:61], v[66:67]
	v_lshl_add_u64 v[64:65], v[64:65], 0, v[140:141]
	v_pk_mul_f32 v[56:57], v[60:61], v[56:57]
	s_nop 0
	v_cvt_pk_bf16_f32 v56, v56, v57
	v_mul_f32_e32 v57, 0xbfb8aa3b, v62
	v_exp_f32_e32 v57, v57
	s_nop 0
	v_add_f32_e32 v57, 1.0, v57
	v_rcp_f32_e32 v60, v57
	v_mul_f32_e32 v57, 0xbfb8aa3b, v63
	v_exp_f32_e32 v57, v57
	s_nop 0
	v_add_f32_e32 v57, 1.0, v57
	v_rcp_f32_e32 v61, v57
	s_nop 0
	v_pk_mul_f32 v[60:61], v[62:63], v[60:61]
	s_nop 0
	v_pk_mul_f32 v[58:59], v[60:61], v[58:59]
	s_nop 0
	v_cvt_pk_bf16_f32 v57, v58, v59
	v_mul_f32_e32 v58, 0xbfb8aa3b, v52
	v_mul_f32_e32 v59, 0xbfb8aa3b, v53
	v_exp_f32_e32 v58, v58
	v_exp_f32_e32 v59, v59
	v_add_f32_e32 v58, 1.0, v58
	v_add_f32_e32 v59, 1.0, v59
	v_rcp_f32_e32 v58, v58
	v_rcp_f32_e32 v59, v59
	s_nop 0
	v_pk_mul_f32 v[52:53], v[52:53], v[58:59]
	s_nop 0
	v_pk_mul_f32 v[48:49], v[52:53], v[48:49]
	s_nop 0
	v_cvt_pk_bf16_f32 v58, v48, v49
	v_mul_f32_e32 v48, 0xbfb8aa3b, v54
	v_mul_f32_e32 v49, 0xbfb8aa3b, v55
	v_exp_f32_e32 v48, v48
	v_exp_f32_e32 v49, v49
	v_add_f32_e32 v48, 1.0, v48
	v_add_f32_e32 v49, 1.0, v49
	v_rcp_f32_e32 v48, v48
	v_rcp_f32_e32 v49, v49
	s_nop 0
	v_pk_mul_f32 v[48:49], v[54:55], v[48:49]
	s_nop 0
	v_pk_mul_f32 v[48:49], v[48:49], v[50:51]
	v_mul_f32_e32 v50, 0xbfb8aa3b, v44
	v_mul_f32_e32 v51, 0xbfb8aa3b, v45
	v_exp_f32_e32 v50, v50
	v_exp_f32_e32 v51, v51
	v_cvt_pk_bf16_f32 v59, v48, v49
	v_add_u32_e32 v48, 0x90, v144
	v_add_f32_e32 v50, 1.0, v50
	v_add_f32_e32 v51, 1.0, v51
	v_rcp_f32_e32 v50, v50
	v_rcp_f32_e32 v51, v51
	v_mad_i64_i32 v[48:49], s[34:35], v48, s18, v[138:139]
	global_store_dwordx4 v[64:65], v[56:59], off
	v_pk_mul_f32 v[44:45], v[44:45], v[50:51]
	v_lshl_add_u64 v[48:49], v[48:49], 0, v[140:141]
	v_pk_mul_f32 v[40:41], v[44:45], v[40:41]
	s_nop 0
	v_cvt_pk_bf16_f32 v40, v40, v41
	v_mul_f32_e32 v41, 0xbfb8aa3b, v46
	v_exp_f32_e32 v41, v41
	s_nop 0
	v_add_f32_e32 v41, 1.0, v41
	v_rcp_f32_e32 v44, v41
	v_mul_f32_e32 v41, 0xbfb8aa3b, v47
	v_exp_f32_e32 v41, v41
	s_nop 0
	v_add_f32_e32 v41, 1.0, v41
	v_rcp_f32_e32 v45, v41
	s_nop 0
	v_pk_mul_f32 v[44:45], v[46:47], v[44:45]
	s_nop 0
	v_pk_mul_f32 v[42:43], v[44:45], v[42:43]
	s_nop 0
	v_cvt_pk_bf16_f32 v41, v42, v43
	v_mul_f32_e32 v42, 0xbfb8aa3b, v36
	v_mul_f32_e32 v43, 0xbfb8aa3b, v37
	v_exp_f32_e32 v42, v42
	v_exp_f32_e32 v43, v43
	v_add_f32_e32 v42, 1.0, v42
	v_add_f32_e32 v43, 1.0, v43
	v_rcp_f32_e32 v42, v42
	v_rcp_f32_e32 v43, v43
	s_nop 0
	v_pk_mul_f32 v[36:37], v[36:37], v[42:43]
	s_nop 0
	v_pk_mul_f32 v[32:33], v[36:37], v[32:33]
	s_nop 0
	v_cvt_pk_bf16_f32 v42, v32, v33
	v_mul_f32_e32 v32, 0xbfb8aa3b, v38
	v_mul_f32_e32 v33, 0xbfb8aa3b, v39
	v_exp_f32_e32 v32, v32
	v_exp_f32_e32 v33, v33
	v_add_f32_e32 v32, 1.0, v32
	v_add_f32_e32 v33, 1.0, v33
	v_rcp_f32_e32 v32, v32
	v_rcp_f32_e32 v33, v33
	s_nop 0
	v_pk_mul_f32 v[32:33], v[38:39], v[32:33]
	s_nop 0
	v_pk_mul_f32 v[32:33], v[32:33], v[34:35]
	v_mul_f32_e32 v34, 0xbfb8aa3b, v28
	v_mul_f32_e32 v35, 0xbfb8aa3b, v29
	v_exp_f32_e32 v34, v34
	v_exp_f32_e32 v35, v35
	v_cvt_pk_bf16_f32 v43, v32, v33
	v_add_u32_e32 v32, 0xa0, v144
	v_add_f32_e32 v34, 1.0, v34
	v_add_f32_e32 v35, 1.0, v35
	v_rcp_f32_e32 v34, v34
	v_rcp_f32_e32 v35, v35
	v_mad_i64_i32 v[32:33], s[34:35], v32, s18, v[138:139]
	global_store_dwordx4 v[48:49], v[40:43], off
	v_pk_mul_f32 v[28:29], v[28:29], v[34:35]
	v_lshl_add_u64 v[32:33], v[32:33], 0, v[140:141]
	v_pk_mul_f32 v[24:25], v[28:29], v[24:25]
	s_nop 0
	v_cvt_pk_bf16_f32 v24, v24, v25
	v_mul_f32_e32 v25, 0xbfb8aa3b, v30
	v_exp_f32_e32 v25, v25
	s_nop 0
	v_add_f32_e32 v25, 1.0, v25
	v_rcp_f32_e32 v28, v25
	v_mul_f32_e32 v25, 0xbfb8aa3b, v31
	v_exp_f32_e32 v25, v25
	s_nop 0
	v_add_f32_e32 v25, 1.0, v25
	v_rcp_f32_e32 v29, v25
	s_nop 0
	v_pk_mul_f32 v[28:29], v[30:31], v[28:29]
	s_nop 0
	v_pk_mul_f32 v[26:27], v[28:29], v[26:27]
	s_nop 0
	v_cvt_pk_bf16_f32 v25, v26, v27
	v_mul_f32_e32 v26, 0xbfb8aa3b, v20
	v_mul_f32_e32 v27, 0xbfb8aa3b, v21
	v_exp_f32_e32 v26, v26
	v_exp_f32_e32 v27, v27
	v_add_f32_e32 v26, 1.0, v26
	v_add_f32_e32 v27, 1.0, v27
	v_rcp_f32_e32 v26, v26
	v_rcp_f32_e32 v27, v27
	s_nop 0
	v_pk_mul_f32 v[20:21], v[20:21], v[26:27]
	s_nop 0
	v_pk_mul_f32 v[16:17], v[20:21], v[16:17]
	s_nop 0
	v_cvt_pk_bf16_f32 v26, v16, v17
	v_mul_f32_e32 v16, 0xbfb8aa3b, v22
	v_mul_f32_e32 v17, 0xbfb8aa3b, v23
	v_exp_f32_e32 v16, v16
	v_exp_f32_e32 v17, v17
	v_add_f32_e32 v16, 1.0, v16
	v_add_f32_e32 v17, 1.0, v17
	v_rcp_f32_e32 v16, v16
	v_rcp_f32_e32 v17, v17
	s_nop 0
	v_pk_mul_f32 v[16:17], v[22:23], v[16:17]
	s_nop 0
	v_pk_mul_f32 v[16:17], v[16:17], v[18:19]
	v_mul_f32_e32 v18, 0xbfb8aa3b, v12
	v_mul_f32_e32 v19, 0xbfb8aa3b, v13
	v_exp_f32_e32 v18, v18
	v_exp_f32_e32 v19, v19
	v_cvt_pk_bf16_f32 v27, v16, v17
	v_add_u32_e32 v16, 0xb0, v144
	v_add_f32_e32 v18, 1.0, v18
	v_add_f32_e32 v19, 1.0, v19
	v_rcp_f32_e32 v18, v18
	v_rcp_f32_e32 v19, v19
	v_mad_i64_i32 v[16:17], s[34:35], v16, s18, v[138:139]
	global_store_dwordx4 v[32:33], v[24:27], off
	v_pk_mul_f32 v[12:13], v[12:13], v[18:19]
	v_lshl_add_u64 v[16:17], v[16:17], 0, v[140:141]
	v_pk_mul_f32 v[8:9], v[12:13], v[8:9]
	s_nop 0
	v_cvt_pk_bf16_f32 v8, v8, v9
	v_mul_f32_e32 v9, 0xbfb8aa3b, v14
	v_exp_f32_e32 v9, v9
	s_nop 0
	v_add_f32_e32 v9, 1.0, v9
	v_rcp_f32_e32 v12, v9
	v_mul_f32_e32 v9, 0xbfb8aa3b, v15
	v_exp_f32_e32 v9, v9
	s_nop 0
	v_add_f32_e32 v9, 1.0, v9
	v_rcp_f32_e32 v13, v9
	s_nop 0
	v_pk_mul_f32 v[12:13], v[14:15], v[12:13]
	s_nop 0
	v_pk_mul_f32 v[10:11], v[12:13], v[10:11]
	s_nop 0
	v_cvt_pk_bf16_f32 v9, v10, v11
	v_mul_f32_e32 v10, 0xbfb8aa3b, v4
	v_mul_f32_e32 v11, 0xbfb8aa3b, v5
	v_exp_f32_e32 v10, v10
	v_exp_f32_e32 v11, v11
	v_add_f32_e32 v10, 1.0, v10
	v_add_f32_e32 v11, 1.0, v11
	v_rcp_f32_e32 v10, v10
	v_rcp_f32_e32 v11, v11
	s_nop 0
	v_pk_mul_f32 v[4:5], v[4:5], v[10:11]
	s_nop 0
	v_pk_mul_f32 v[0:1], v[4:5], v[0:1]
	s_nop 0
	v_cvt_pk_bf16_f32 v10, v0, v1
	v_mul_f32_e32 v0, 0xbfb8aa3b, v6
	v_mul_f32_e32 v1, 0xbfb8aa3b, v7
	v_exp_f32_e32 v0, v0
	v_exp_f32_e32 v1, v1
	v_add_f32_e32 v0, 1.0, v0
	v_add_f32_e32 v1, 1.0, v1
	v_rcp_f32_e32 v0, v0
	v_rcp_f32_e32 v1, v1
	s_nop 0
	v_pk_mul_f32 v[0:1], v[6:7], v[0:1]
	s_nop 0
	v_pk_mul_f32 v[0:1], v[0:1], v[2:3]
	s_nop 0
	v_cvt_pk_bf16_f32 v11, v0, v1
	global_store_dwordx4 v[16:17], v[8:11], off
	s_cbranch_vccz .LBB0_188
	s_waitcnt vmcnt(0)
	s_cmpk_gt_u32 s16, 0xff
	s_cbranch_scc1 .LBB0_195
	s_barrier

.LBB0_264:
	s_add_u32 s36, s50, 0xfffc0080
	s_addc_u32 s37, s51, -1
	s_add_i32 s38, 0, 0x10000
	v_add_u32_e32 v154, s38, v144
	ds_read_b128 v[140:143], v154
	ds_read_b128 v[146:149], v154 offset:1024
	ds_read_b128 v[150:153], v154 offset:2048
	ds_read_b128 v[154:157], v154 offset:3072
	s_cmp_eq_u32 s49, 12
	s_cselect_b32 s55, s15, s37
	s_cselect_b32 s54, s16, s36
	s_cselect_b32 s53, s13, s35
	s_cselect_b32 s52, s17, s34
	v_lshl_add_u64 v[166:167], s[50:51], 0, v[136:137]
	s_add_i32 m0, s31, 0xc000
	ds_read_b128 v[158:161], v145
	ds_read_b128 v[162:165], v145 offset:1024
	ds_read_b128 v[180:183], v145 offset:2048
	ds_read_b128 v[184:187], v145 offset:3072
	ds_read_b128 v[188:191], v145 offset:4096
	ds_read_b128 v[192:195], v145 offset:5120
	ds_read_b128 v[196:199], v145 offset:6144
	ds_read_b128 v[200:203], v145 offset:7168
	global_load_lds_dwordx4 v[166:167], off
	v_lshl_add_u64 v[166:167], s[50:51], 0, v[138:139]
	s_add_i32 m0, s31, 0xe000
	s_nop 0
	global_load_lds_dwordx4 v[166:167], off
	s_waitcnt lgkmcnt(8)
	s_barrier
	s_waitcnt lgkmcnt(0)
	s_waitcnt lgkmcnt(0)
	v_mfma_f32_16x16x32_bf16 v[124:127], v[140:143], v[158:161], v[124:127]
	v_mfma_f32_16x16x32_bf16 v[120:123], v[150:153], v[158:161], v[120:123]
	v_mfma_f32_16x16x32_bf16 v[116:119], v[140:143], v[180:183], v[116:119]
	v_mfma_f32_16x16x32_bf16 v[112:115], v[150:153], v[180:183], v[112:115]
	v_mfma_f32_16x16x32_bf16 v[108:111], v[140:143], v[188:191], v[108:111]
	v_mfma_f32_16x16x32_bf16 v[104:107], v[150:153], v[188:191], v[104:107]
	v_mfma_f32_16x16x32_bf16 v[100:103], v[140:143], v[196:199], v[100:103]
	v_mfma_f32_16x16x32_bf16 v[96:99], v[150:153], v[196:199], v[96:99]
	v_mfma_f32_16x16x32_bf16 v[124:127], v[146:149], v[162:165], v[124:127]
	v_mfma_f32_16x16x32_bf16 v[120:123], v[154:157], v[162:165], v[120:123]
	v_mfma_f32_16x16x32_bf16 v[116:119], v[146:149], v[184:187], v[116:119]
	v_mfma_f32_16x16x32_bf16 v[112:115], v[154:157], v[184:187], v[112:115]
	v_mfma_f32_16x16x32_bf16 v[108:111], v[146:149], v[192:195], v[108:111]
	v_mfma_f32_16x16x32_bf16 v[104:107], v[154:157], v[192:195], v[104:107]
	v_mfma_f32_16x16x32_bf16 v[100:103], v[146:149], v[200:203], v[100:103]
	v_mfma_f32_16x16x32_bf16 v[96:99], v[154:157], v[200:203], v[96:99]
	s_barrier
	s_add_i32 s39, 0, 0x14000
	v_add_u32_e32 v166, s39, v144
	s_add_i32 s36, s38, s30
	ds_read_b128 v[204:207], v166
	ds_read_b128 v[208:211], v166 offset:1024
	ds_read_b128 v[212:215], v166 offset:2048
	ds_read_b128 v[216:219], v166 offset:3072
	v_lshl_add_u64 v[166:167], s[52:53], 0, v[130:131]
	s_mov_b32 m0, s36
	v_lshl_add_u64 v[172:173], s[52:53], 0, v[134:135]
	global_load_lds_dwordx4 v[166:167], off
	s_add_i32 m0, s36, 0x2000
	s_nop 0
	global_load_lds_dwordx4 v[172:173], off
	s_barrier
	s_waitcnt lgkmcnt(0)
	s_waitcnt lgkmcnt(0)
	v_mfma_f32_16x16x32_bf16 v[68:71], v[204:207], v[158:161], v[68:71]
	v_mfma_f32_16x16x32_bf16 v[64:67], v[212:215], v[158:161], v[64:67]
	v_mfma_f32_16x16x32_bf16 v[52:55], v[204:207], v[180:183], v[52:55]
	v_mfma_f32_16x16x32_bf16 v[48:51], v[212:215], v[180:183], v[48:51]
	v_mfma_f32_16x16x32_bf16 v[44:47], v[204:207], v[188:191], v[44:47]
	v_mfma_f32_16x16x32_bf16 v[40:43], v[212:215], v[188:191], v[40:43]
	v_mfma_f32_16x16x32_bf16 v[36:39], v[204:207], v[196:199], v[36:39]
	v_mfma_f32_16x16x32_bf16 v[32:35], v[212:215], v[196:199], v[32:35]
	v_mfma_f32_16x16x32_bf16 v[68:71], v[208:211], v[162:165], v[68:71]
	v_mfma_f32_16x16x32_bf16 v[64:67], v[216:219], v[162:165], v[64:67]
	v_mfma_f32_16x16x32_bf16 v[52:55], v[208:211], v[184:187], v[52:55]
	v_mfma_f32_16x16x32_bf16 v[48:51], v[216:219], v[184:187], v[48:51]
	v_mfma_f32_16x16x32_bf16 v[44:47], v[208:211], v[192:195], v[44:47]
	v_mfma_f32_16x16x32_bf16 v[40:43], v[216:219], v[192:195], v[40:43]
	v_mfma_f32_16x16x32_bf16 v[36:39], v[208:211], v[200:203], v[36:39]
	v_mfma_f32_16x16x32_bf16 v[32:35], v[216:219], v[200:203], v[32:35]
	s_mov_b32 m0, s31
	v_lshl_add_u64 v[174:175], s[54:55], 0, v[128:129]
	s_barrier
	ds_read_b128 v[158:161], v145 offset:16384
	ds_read_b128 v[162:165], v145 offset:17408
	ds_read_b128 v[180:183], v145 offset:18432
	ds_read_b128 v[184:187], v145 offset:19456
	ds_read_b128 v[188:191], v145 offset:20480
	ds_read_b128 v[192:195], v145 offset:21504
	ds_read_b128 v[196:199], v145 offset:22528
	ds_read_b128 v[200:203], v145 offset:23552
	global_load_lds_dwordx4 v[174:175], off
	v_lshl_add_u64 v[176:177], s[54:55], 0, v[132:133]
	s_mov_b32 m0, s45
	s_nop 0
	global_load_lds_dwordx4 v[176:177], off
	s_barrier
	s_waitcnt lgkmcnt(0)
	s_waitcnt lgkmcnt(0)
	v_mfma_f32_16x16x32_bf16 v[92:95], v[140:143], v[158:161], v[92:95]
	v_mfma_f32_16x16x32_bf16 v[88:91], v[150:153], v[158:161], v[88:91]
	v_mfma_f32_16x16x32_bf16 v[84:87], v[140:143], v[180:183], v[84:87]
	v_mfma_f32_16x16x32_bf16 v[80:83], v[150:153], v[180:183], v[80:83]
	v_mfma_f32_16x16x32_bf16 v[76:79], v[140:143], v[188:191], v[76:79]
	v_mfma_f32_16x16x32_bf16 v[72:75], v[150:153], v[188:191], v[72:75]
	v_mfma_f32_16x16x32_bf16 v[60:63], v[140:143], v[196:199], v[60:63]
	v_mfma_f32_16x16x32_bf16 v[56:59], v[150:153], v[196:199], v[56:59]
	v_mfma_f32_16x16x32_bf16 v[92:95], v[146:149], v[162:165], v[92:95]
	v_mfma_f32_16x16x32_bf16 v[88:91], v[154:157], v[162:165], v[88:91]
	v_mfma_f32_16x16x32_bf16 v[84:87], v[146:149], v[184:187], v[84:87]
	v_mfma_f32_16x16x32_bf16 v[80:83], v[154:157], v[184:187], v[80:83]
	v_mfma_f32_16x16x32_bf16 v[76:79], v[146:149], v[192:195], v[76:79]
	v_mfma_f32_16x16x32_bf16 v[72:75], v[154:157], v[192:195], v[72:75]
	v_mfma_f32_16x16x32_bf16 v[60:63], v[146:149], v[200:203], v[60:63]
	v_mfma_f32_16x16x32_bf16 v[56:59], v[154:157], v[200:203], v[56:59]
	s_barrier
	s_add_u32 s36, s52, 0x40000
	s_addc_u32 s37, s53, 0
	s_add_i32 s38, s39, s30
	v_lshl_add_u64 v[140:141], s[36:37], 0, v[130:131]
	s_mov_b32 m0, s38
	s_nop 0
	global_load_lds_dwordx4 v[140:141], off
	v_lshl_add_u64 v[140:141], s[36:37], 0, v[134:135]
	s_add_i32 m0, s38, 0x2000
	s_nop 0
	global_load_lds_dwordx4 v[140:141], off
	s_waitcnt vmcnt(6)
	s_barrier
	v_mfma_f32_16x16x32_bf16 v[28:31], v[204:207], v[158:161], v[28:31]
	v_mfma_f32_16x16x32_bf16 v[24:27], v[212:215], v[158:161], v[24:27]
	v_mfma_f32_16x16x32_bf16 v[20:23], v[204:207], v[180:183], v[20:23]
	v_mfma_f32_16x16x32_bf16 v[16:19], v[212:215], v[180:183], v[16:19]
	v_mfma_f32_16x16x32_bf16 v[12:15], v[204:207], v[188:191], v[12:15]
	v_mfma_f32_16x16x32_bf16 v[8:11], v[212:215], v[188:191], v[8:11]
	v_mfma_f32_16x16x32_bf16 v[4:7], v[204:207], v[196:199], v[4:7]
	v_mfma_f32_16x16x32_bf16 v[0:3], v[212:215], v[196:199], v[0:3]
	v_mfma_f32_16x16x32_bf16 v[28:31], v[208:211], v[162:165], v[28:31]
	v_mfma_f32_16x16x32_bf16 v[24:27], v[216:219], v[162:165], v[24:27]
	v_mfma_f32_16x16x32_bf16 v[20:23], v[208:211], v[184:187], v[20:23]
	v_mfma_f32_16x16x32_bf16 v[16:19], v[216:219], v[184:187], v[16:19]
	v_mfma_f32_16x16x32_bf16 v[12:15], v[208:211], v[192:195], v[12:15]
	v_mfma_f32_16x16x32_bf16 v[8:11], v[216:219], v[192:195], v[8:11]
	v_mfma_f32_16x16x32_bf16 v[4:7], v[208:211], v[200:203], v[4:7]
	v_mfma_f32_16x16x32_bf16 v[0:3], v[216:219], v[200:203], v[0:3]
	s_add_i32 s38, 0, 0x18000
	v_add_u32_e32 v154, s38, v144
	s_barrier
	ds_read_b128 v[140:143], v154
	ds_read_b128 v[146:149], v154 offset:1024
	ds_read_b128 v[150:153], v154 offset:2048
	ds_read_b128 v[154:157], v154 offset:3072
	s_add_u32 s36, s54, 0x40000
	s_addc_u32 s37, s55, 0
	s_mov_b32 m0, s56
	v_lshl_add_u64 v[178:179], s[36:37], 0, v[128:129]
	ds_read_b128 v[158:161], v145 offset:32768
	ds_read_b128 v[162:165], v145 offset:33792
	ds_read_b128 v[180:183], v145 offset:34816
	ds_read_b128 v[184:187], v145 offset:35840
	ds_read_b128 v[188:191], v145 offset:36864
	ds_read_b128 v[192:195], v145 offset:37888
	ds_read_b128 v[196:199], v145 offset:38912
	ds_read_b128 v[200:203], v145 offset:39936
	global_load_lds_dwordx4 v[178:179], off
	v_lshl_add_u64 v[178:179], s[36:37], 0, v[132:133]
	s_mov_b32 m0, s57
	s_nop 0
	global_load_lds_dwordx4 v[178:179], off
	s_waitcnt lgkmcnt(8)
	s_barrier
	s_waitcnt lgkmcnt(0)
	s_waitcnt lgkmcnt(0)
	v_mfma_f32_16x16x32_bf16 v[124:127], v[140:143], v[158:161], v[124:127]
	v_mfma_f32_16x16x32_bf16 v[120:123], v[150:153], v[158:161], v[120:123]
	v_mfma_f32_16x16x32_bf16 v[116:119], v[140:143], v[180:183], v[116:119]
	v_mfma_f32_16x16x32_bf16 v[112:115], v[150:153], v[180:183], v[112:115]
	v_mfma_f32_16x16x32_bf16 v[108:111], v[140:143], v[188:191], v[108:111]
	v_mfma_f32_16x16x32_bf16 v[104:107], v[150:153], v[188:191], v[104:107]
	v_mfma_f32_16x16x32_bf16 v[100:103], v[140:143], v[196:199], v[100:103]
	v_mfma_f32_16x16x32_bf16 v[96:99], v[150:153], v[196:199], v[96:99]
	v_mfma_f32_16x16x32_bf16 v[124:127], v[146:149], v[162:165], v[124:127]
	v_mfma_f32_16x16x32_bf16 v[120:123], v[154:157], v[162:165], v[120:123]
	v_mfma_f32_16x16x32_bf16 v[116:119], v[146:149], v[184:187], v[116:119]
	v_mfma_f32_16x16x32_bf16 v[112:115], v[154:157], v[184:187], v[112:115]
	v_mfma_f32_16x16x32_bf16 v[108:111], v[146:149], v[192:195], v[108:111]
	v_mfma_f32_16x16x32_bf16 v[104:107], v[154:157], v[192:195], v[104:107]
	v_mfma_f32_16x16x32_bf16 v[100:103], v[146:149], v[200:203], v[100:103]
	v_mfma_f32_16x16x32_bf16 v[96:99], v[154:157], v[200:203], v[96:99]
	s_barrier
	s_add_i32 s39, 0, 0x1c000
	s_add_i32 s36, s38, s30
	v_add_u32_e32 v168, s39, v144
	v_lshl_add_u64 v[166:167], v[166:167], 0, s[88:89]
	s_mov_b32 m0, s36
	ds_read_b128 v[204:207], v168
	ds_read_b128 v[208:211], v168 offset:1024
	ds_read_b128 v[212:215], v168 offset:2048
	ds_read_b128 v[216:219], v168 offset:3072
	global_load_lds_dwordx4 v[166:167], off
	v_lshl_add_u64 v[166:167], v[172:173], 0, s[88:89]
	s_add_i32 m0, s36, 0x2000
	s_nop 0
	global_load_lds_dwordx4 v[166:167], off
	s_barrier
	s_waitcnt lgkmcnt(0)
	s_waitcnt lgkmcnt(0)
	v_mfma_f32_16x16x32_bf16 v[68:71], v[204:207], v[158:161], v[68:71]
	v_mfma_f32_16x16x32_bf16 v[64:67], v[212:215], v[158:161], v[64:67]
	v_mfma_f32_16x16x32_bf16 v[52:55], v[204:207], v[180:183], v[52:55]
	v_mfma_f32_16x16x32_bf16 v[48:51], v[212:215], v[180:183], v[48:51]
	v_mfma_f32_16x16x32_bf16 v[44:47], v[204:207], v[188:191], v[44:47]
	v_mfma_f32_16x16x32_bf16 v[40:43], v[212:215], v[188:191], v[40:43]
	v_mfma_f32_16x16x32_bf16 v[36:39], v[204:207], v[196:199], v[36:39]
	v_mfma_f32_16x16x32_bf16 v[32:35], v[212:215], v[196:199], v[32:35]
	v_mfma_f32_16x16x32_bf16 v[68:71], v[208:211], v[162:165], v[68:71]
	v_mfma_f32_16x16x32_bf16 v[64:67], v[216:219], v[162:165], v[64:67]
	v_mfma_f32_16x16x32_bf16 v[52:55], v[208:211], v[184:187], v[52:55]
	v_mfma_f32_16x16x32_bf16 v[48:51], v[216:219], v[184:187], v[48:51]
	v_mfma_f32_16x16x32_bf16 v[44:47], v[208:211], v[192:195], v[44:47]
	v_mfma_f32_16x16x32_bf16 v[40:43], v[216:219], v[192:195], v[40:43]
	v_mfma_f32_16x16x32_bf16 v[36:39], v[208:211], v[200:203], v[36:39]
	v_mfma_f32_16x16x32_bf16 v[32:35], v[216:219], v[200:203], v[32:35]
	s_mov_b32 m0, s60
	v_lshl_add_u64 v[166:167], v[174:175], 0, s[88:89]
	s_barrier
	ds_read_b128 v[158:161], v145 offset:49152
	ds_read_b128 v[162:165], v145 offset:50176
	ds_read_b128 v[180:183], v145 offset:51200
	ds_read_b128 v[184:187], v145 offset:52224
	ds_read_b128 v[188:191], v145 offset:53248
	ds_read_b128 v[192:195], v145 offset:54272
	ds_read_b128 v[196:199], v145 offset:55296
	ds_read_b128 v[200:203], v145 offset:56320
	global_load_lds_dwordx4 v[166:167], off
	v_lshl_add_u64 v[166:167], v[176:177], 0, s[88:89]
	s_mov_b32 m0, s61
	s_nop 0
	global_load_lds_dwordx4 v[166:167], off
	s_barrier
	s_waitcnt lgkmcnt(0)
	s_waitcnt lgkmcnt(0)
	v_mfma_f32_16x16x32_bf16 v[92:95], v[140:143], v[158:161], v[92:95]
	v_mfma_f32_16x16x32_bf16 v[88:91], v[150:153], v[158:161], v[88:91]
	v_mfma_f32_16x16x32_bf16 v[84:87], v[140:143], v[180:183], v[84:87]
	v_mfma_f32_16x16x32_bf16 v[80:83], v[150:153], v[180:183], v[80:83]
	v_mfma_f32_16x16x32_bf16 v[76:79], v[140:143], v[188:191], v[76:79]
	v_mfma_f32_16x16x32_bf16 v[72:75], v[150:153], v[188:191], v[72:75]
	v_mfma_f32_16x16x32_bf16 v[60:63], v[140:143], v[196:199], v[60:63]
	v_mfma_f32_16x16x32_bf16 v[56:59], v[150:153], v[196:199], v[56:59]
	v_mfma_f32_16x16x32_bf16 v[92:95], v[146:149], v[162:165], v[92:95]
	v_mfma_f32_16x16x32_bf16 v[88:91], v[154:157], v[162:165], v[88:91]
	v_mfma_f32_16x16x32_bf16 v[84:87], v[146:149], v[184:187], v[84:87]
	v_mfma_f32_16x16x32_bf16 v[80:83], v[154:157], v[184:187], v[80:83]
	v_mfma_f32_16x16x32_bf16 v[76:79], v[146:149], v[192:195], v[76:79]
	v_mfma_f32_16x16x32_bf16 v[72:75], v[154:157], v[192:195], v[72:75]
	v_mfma_f32_16x16x32_bf16 v[60:63], v[146:149], v[200:203], v[60:63]
	v_mfma_f32_16x16x32_bf16 v[56:59], v[154:157], v[200:203], v[56:59]
	s_barrier
	s_add_u32 s36, s52, 0x40080
	s_addc_u32 s37, s53, 0
	s_add_i32 s38, s39, s30
	v_lshl_add_u64 v[140:141], s[36:37], 0, v[130:131]
	s_mov_b32 m0, s38
	s_nop 0
	global_load_lds_dwordx4 v[140:141], off
	v_lshl_add_u64 v[140:141], s[36:37], 0, v[134:135]
	s_add_i32 m0, s38, 0x2000
	s_nop 0
	global_load_lds_dwordx4 v[140:141], off
	s_waitcnt vmcnt(6)
	s_barrier
	v_mfma_f32_16x16x32_bf16 v[28:31], v[204:207], v[158:161], v[28:31]
	v_mfma_f32_16x16x32_bf16 v[24:27], v[212:215], v[158:161], v[24:27]
	v_mfma_f32_16x16x32_bf16 v[20:23], v[204:207], v[180:183], v[20:23]
	v_mfma_f32_16x16x32_bf16 v[16:19], v[212:215], v[180:183], v[16:19]
	v_mfma_f32_16x16x32_bf16 v[12:15], v[204:207], v[188:191], v[12:15]
	v_mfma_f32_16x16x32_bf16 v[8:11], v[212:215], v[188:191], v[8:11]
	v_mfma_f32_16x16x32_bf16 v[4:7], v[204:207], v[196:199], v[4:7]
	v_mfma_f32_16x16x32_bf16 v[0:3], v[212:215], v[196:199], v[0:3]
	v_mfma_f32_16x16x32_bf16 v[28:31], v[208:211], v[162:165], v[28:31]
	v_mfma_f32_16x16x32_bf16 v[24:27], v[216:219], v[162:165], v[24:27]
	v_mfma_f32_16x16x32_bf16 v[20:23], v[208:211], v[184:187], v[20:23]
	v_mfma_f32_16x16x32_bf16 v[16:19], v[216:219], v[184:187], v[16:19]
	v_mfma_f32_16x16x32_bf16 v[12:15], v[208:211], v[192:195], v[12:15]
	v_mfma_f32_16x16x32_bf16 v[8:11], v[216:219], v[192:195], v[8:11]
	v_mfma_f32_16x16x32_bf16 v[4:7], v[208:211], v[200:203], v[4:7]
	v_mfma_f32_16x16x32_bf16 v[0:3], v[216:219], v[200:203], v[0:3]
	s_add_i32 s49, s49, 2
	s_add_u32 s50, s50, 0x100
	s_addc_u32 s51, s51, 0
	s_add_u32 s34, s34, 0x100
	s_addc_u32 s35, s35, 0
	s_cmp_gt_u32 s49, 13
	s_barrier
	s_cbranch_scc0 .LBB0_264
	v_mov_b32_e32 v141, v171
	s_lshl_b32 s13, s48, 8
	s_or_b32 s13, s13, s59
	v_lshrrev_b32_e32 v140, 1, v141
	s_cmpk_lg_i32 s13, 0x400
	v_and_or_b32 v140, v140, 24, s13
	s_mov_b64 s[48:49], -1
	s_cbranch_scc0 .LBB0_267
	v_add_u32_e32 v142, 0xfffff4d8, v140
	v_add_u32_e32 v143, 0xfffff518, v140
	v_cmp_gt_u32_e32 vcc, 16, v142
	s_movk_i32 s13, 0x720
	s_mov_b64 s[48:49], 0
	v_cndmask_b32_e32 v142, -1, v143, vcc
	v_cmp_ne_u32_e32 vcc, s13, v140
	s_nop 1
	v_cndmask_b32_e32 v168, 32, v142, vcc

.LBB0_631:
	s_ashr_i32 s43, s42, 31
	s_lshl_b64 s[34:35], s[42:43], 17
	v_mov_b64_e32 v[0:1], 0x84
	s_add_u32 s44, s6, s34
	v_cmp_lt_i64_e32 vcc, s[12:13], v[0:1]
	s_addc_u32 s45, s7, s35
	s_and_b64 s[34:35], vcc, exec
	s_cselect_b32 s55, s45, s49
	s_cselect_b32 s54, s44, s48
	s_ashr_i32 s15, s14, 31
	s_lshl_b64 s[34:35], s[14:15], 17
	s_add_u32 s46, s17, s34
	s_addc_u32 s47, s27, s35
	s_and_b64 s[34:35], vcc, exec
	s_cselect_b32 s53, s47, s51
	s_cselect_b32 s52, s46, s50
	s_add_i32 s31, 0, 0x10000
	v_add_u32_e32 v168, s31, v236
	ds_read_b128 v[0:3], v168
	ds_read_b128 v[4:7], v168 offset:1024
	ds_read_b128 v[8:11], v168 offset:2048
	ds_read_b128 v[12:15], v168 offset:3072
	v_mov_b32_e32 v170, 0x3f803f80
	v_mov_b64_e32 v[226:227], 0x200
	s_add_u32 s34, s48, 0x10080
	s_addc_u32 s35, s49, 0
	s_add_i32 s36, s29, 0xc000
	v_lshl_add_u64 v[48:49], s[34:35], 0, v[186:187]
	s_mov_b32 m0, s36
	s_add_i32 s15, s29, 0xe000
	ds_read_b128 v[16:19], v237
	ds_read_b128 v[20:23], v237 offset:1024
	ds_read_b128 v[24:27], v237 offset:2048
	ds_read_b128 v[28:31], v237 offset:3072
	ds_read_b128 v[32:35], v237 offset:4096
	ds_read_b128 v[36:39], v237 offset:5120
	ds_read_b128 v[40:43], v237 offset:6144
	ds_read_b128 v[44:47], v237 offset:7168
	global_load_lds_dwordx4 v[48:49], off
	v_lshl_add_u64 v[48:49], s[34:35], 0, v[182:183]
	s_mov_b32 m0, s15
	s_nop 0
	global_load_lds_dwordx4 v[48:49], off
	s_waitcnt lgkmcnt(8)
	s_barrier
	s_waitcnt lgkmcnt(0)
	s_waitcnt lgkmcnt(0)
	v_mfma_f32_16x16x32_bf16 v[48:51], v[0:3], v[16:19], 0
	v_mfma_f32_16x16x32_bf16 v[52:55], v[8:11], v[16:19], 0
	v_mfma_f32_16x16x32_bf16 v[56:59], v[0:3], v[24:27], 0
	v_mfma_f32_16x16x32_bf16 v[60:63], v[8:11], v[24:27], 0
	v_mfma_f32_16x16x32_bf16 v[64:67], v[0:3], v[32:35], 0
	v_mfma_f32_16x16x32_bf16 v[68:71], v[8:11], v[32:35], 0
	v_mfma_f32_16x16x32_bf16 v[72:75], v[0:3], v[40:43], 0
	v_mfma_f32_16x16x32_bf16 v[76:79], v[8:11], v[40:43], 0
	v_mfma_f32_16x16x32_bf16 v[48:51], v[4:7], v[20:23], v[48:51]
	v_mfma_f32_16x16x32_bf16 v[52:55], v[12:15], v[20:23], v[52:55]
	v_mfma_f32_16x16x32_bf16 v[56:59], v[4:7], v[28:31], v[56:59]
	v_mfma_f32_16x16x32_bf16 v[60:63], v[12:15], v[28:31], v[60:63]
	v_mfma_f32_16x16x32_bf16 v[64:67], v[4:7], v[36:39], v[64:67]
	v_mfma_f32_16x16x32_bf16 v[68:71], v[12:15], v[36:39], v[68:71]
	v_mfma_f32_16x16x32_bf16 v[72:75], v[4:7], v[44:47], v[72:75]
	v_mfma_f32_16x16x32_bf16 v[76:79], v[12:15], v[44:47], v[76:79]
	s_barrier
	s_add_i32 s37, 0, 0x14000
	v_lshl_add_u64 v[172:173], s[50:51], 0, v[184:185]
	s_add_i32 s35, s31, s28
	v_add_u32_e32 v212, s37, v236
	v_lshl_add_u64 v[96:97], v[172:173], 0, s[90:91]
	s_mov_b32 m0, s35
	v_lshl_add_u64 v[174:175], s[50:51], 0, v[180:181]
	s_add_i32 s31, s35, 0x2000
	ds_read_b128 v[80:83], v212
	ds_read_b128 v[84:87], v212 offset:1024
	ds_read_b128 v[88:91], v212 offset:2048
	ds_read_b128 v[92:95], v212 offset:3072
	global_load_lds_dwordx4 v[96:97], off
	v_lshl_add_u64 v[96:97], v[174:175], 0, s[90:91]
	s_mov_b32 m0, s31
	s_nop 0
	global_load_lds_dwordx4 v[96:97], off
	s_barrier
	s_waitcnt lgkmcnt(0)
	s_waitcnt lgkmcnt(0)
	v_mfma_f32_16x16x32_bf16 v[96:99], v[80:83], v[16:19], 0
	v_mfma_f32_16x16x32_bf16 v[16:19], v[88:91], v[16:19], 0
	v_mfma_f32_16x16x32_bf16 v[96:99], v[84:87], v[20:23], v[96:99]
	v_mfma_f32_16x16x32_bf16 v[16:19], v[92:95], v[20:23], v[16:19]
	v_mfma_f32_16x16x32_bf16 v[20:23], v[80:83], v[24:27], 0
	v_mfma_f32_16x16x32_bf16 v[24:27], v[88:91], v[24:27], 0
	v_mfma_f32_16x16x32_bf16 v[20:23], v[84:87], v[28:31], v[20:23]
	v_mfma_f32_16x16x32_bf16 v[24:27], v[92:95], v[28:31], v[24:27]
	v_mfma_f32_16x16x32_bf16 v[28:31], v[80:83], v[32:35], 0
	v_mfma_f32_16x16x32_bf16 v[32:35], v[88:91], v[32:35], 0
	v_mfma_f32_16x16x32_bf16 v[28:31], v[84:87], v[36:39], v[28:31]
	v_mfma_f32_16x16x32_bf16 v[32:35], v[92:95], v[36:39], v[32:35]
	v_mfma_f32_16x16x32_bf16 v[36:39], v[80:83], v[40:43], 0
	v_mfma_f32_16x16x32_bf16 v[40:43], v[88:91], v[40:43], 0
	v_mfma_f32_16x16x32_bf16 v[36:39], v[84:87], v[44:47], v[36:39]
	v_mfma_f32_16x16x32_bf16 v[40:43], v[92:95], v[44:47], v[40:43]
	v_lshl_add_u64 v[176:177], s[48:49], 0, v[186:187]
	s_mov_b32 m0, s29
	v_lshl_add_u64 v[128:129], v[176:177], 0, s[90:91]
	v_lshl_add_u64 v[178:179], s[48:49], 0, v[182:183]
	s_barrier
	ds_read_b128 v[44:47], v237 offset:16384
	ds_read_b128 v[100:103], v237 offset:17408
	ds_read_b128 v[104:107], v237 offset:18432
	ds_read_b128 v[108:111], v237 offset:19456
	ds_read_b128 v[112:115], v237 offset:20480
	ds_read_b128 v[116:119], v237 offset:21504
	ds_read_b128 v[120:123], v237 offset:22528
	ds_read_b128 v[124:127], v237 offset:23552
	global_load_lds_dwordx4 v[128:129], off
	v_lshl_add_u64 v[128:129], v[178:179], 0, s[90:91]
	s_mov_b32 m0, s56
	s_nop 0
	global_load_lds_dwordx4 v[128:129], off
	s_barrier
	s_waitcnt lgkmcnt(0)
	s_waitcnt lgkmcnt(0)
	v_mfma_f32_16x16x32_bf16 v[128:131], v[0:3], v[44:47], 0
	v_mfma_f32_16x16x32_bf16 v[136:139], v[0:3], v[104:107], 0
	v_mfma_f32_16x16x32_bf16 v[144:147], v[0:3], v[112:115], 0
	v_mfma_f32_16x16x32_bf16 v[0:3], v[0:3], v[120:123], 0
	v_mfma_f32_16x16x32_bf16 v[128:131], v[4:7], v[100:103], v[128:131]
	v_mfma_f32_16x16x32_bf16 v[132:135], v[8:11], v[44:47], 0
	v_mfma_f32_16x16x32_bf16 v[136:139], v[4:7], v[108:111], v[136:139]
	v_mfma_f32_16x16x32_bf16 v[140:143], v[8:11], v[104:107], 0
	v_mfma_f32_16x16x32_bf16 v[144:147], v[4:7], v[116:119], v[144:147]
	v_mfma_f32_16x16x32_bf16 v[148:151], v[8:11], v[112:115], 0
	v_mfma_f32_16x16x32_bf16 v[0:3], v[4:7], v[124:127], v[0:3]
	v_mfma_f32_16x16x32_bf16 v[4:7], v[8:11], v[120:123], 0
	v_mfma_f32_16x16x32_bf16 v[132:135], v[12:15], v[100:103], v[132:135]
	v_mfma_f32_16x16x32_bf16 v[140:143], v[12:15], v[108:111], v[140:143]
	v_mfma_f32_16x16x32_bf16 v[148:151], v[12:15], v[116:119], v[148:151]
	v_mfma_f32_16x16x32_bf16 v[4:7], v[12:15], v[124:127], v[4:7]
	s_barrier
	s_add_u32 s38, s50, 0x10100
	s_addc_u32 s39, s51, 0
	s_add_i32 s37, s37, s28
	v_lshl_add_u64 v[8:9], s[38:39], 0, v[184:185]
	s_mov_b32 m0, s37
	s_add_i32 s34, s37, 0x2000
	global_load_lds_dwordx4 v[8:9], off
	v_lshl_add_u64 v[8:9], s[38:39], 0, v[180:181]
	s_mov_b32 m0, s34
	s_nop 0
	global_load_lds_dwordx4 v[8:9], off
	s_waitcnt vmcnt(6)
	s_barrier
	v_mfma_f32_16x16x32_bf16 v[8:11], v[80:83], v[44:47], 0
	v_mfma_f32_16x16x32_bf16 v[12:15], v[88:91], v[44:47], 0
	v_mfma_f32_16x16x32_bf16 v[8:11], v[84:87], v[100:103], v[8:11]
	v_mfma_f32_16x16x32_bf16 v[12:15], v[92:95], v[100:103], v[12:15]
	v_mfma_f32_16x16x32_bf16 v[44:47], v[80:83], v[104:107], 0
	v_mfma_f32_16x16x32_bf16 v[100:103], v[88:91], v[104:107], 0
	v_mfma_f32_16x16x32_bf16 v[104:107], v[80:83], v[112:115], 0
	v_mfma_f32_16x16x32_bf16 v[80:83], v[80:83], v[120:123], 0
	v_mfma_f32_16x16x32_bf16 v[44:47], v[84:87], v[108:111], v[44:47]
	v_mfma_f32_16x16x32_bf16 v[100:103], v[92:95], v[108:111], v[100:103]
	v_mfma_f32_16x16x32_bf16 v[104:107], v[84:87], v[116:119], v[104:107]
	v_mfma_f32_16x16x32_bf16 v[108:111], v[88:91], v[112:115], 0
	v_mfma_f32_16x16x32_bf16 v[80:83], v[84:87], v[124:127], v[80:83]
	v_mfma_f32_16x16x32_bf16 v[84:87], v[88:91], v[120:123], 0
	v_mfma_f32_16x16x32_bf16 v[108:111], v[92:95], v[116:119], v[108:111]
	v_mfma_f32_16x16x32_bf16 v[84:87], v[92:95], v[124:127], v[84:87]
	s_add_i32 s64, 0, 0x18000
	v_add_u32_e32 v222, s64, v236
	s_barrier
	ds_read_b128 v[88:91], v222
	ds_read_b128 v[92:95], v222 offset:1024
	ds_read_b128 v[112:115], v222 offset:2048
	ds_read_b128 v[116:119], v222 offset:3072
	s_add_u32 s38, s48, 0x10100
	s_addc_u32 s39, s49, 0
	s_mov_b32 m0, s57
	v_lshl_add_u64 v[196:197], s[38:39], 0, v[186:187]
	ds_read_b128 v[120:123], v237 offset:32768
	ds_read_b128 v[124:127], v237 offset:33792
	ds_read_b128 v[152:155], v237 offset:34816
	ds_read_b128 v[156:159], v237 offset:35840
	ds_read_b128 v[160:163], v237 offset:36864
	ds_read_b128 v[164:167], v237 offset:37888
	ds_read_b128 v[188:191], v237 offset:38912
	ds_read_b128 v[192:195], v237 offset:39936
	global_load_lds_dwordx4 v[196:197], off
	v_lshl_add_u64 v[196:197], s[38:39], 0, v[182:183]
	s_mov_b32 m0, s58
	s_nop 0
	global_load_lds_dwordx4 v[196:197], off
	s_waitcnt lgkmcnt(8)
	s_barrier
	s_waitcnt lgkmcnt(0)
	s_waitcnt lgkmcnt(0)
	v_mfma_f32_16x16x32_bf16 v[48:51], v[88:91], v[120:123], v[48:51]
	v_mfma_f32_16x16x32_bf16 v[52:55], v[112:115], v[120:123], v[52:55]
	v_mfma_f32_16x16x32_bf16 v[56:59], v[88:91], v[152:155], v[56:59]
	v_mfma_f32_16x16x32_bf16 v[60:63], v[112:115], v[152:155], v[60:63]
	v_mfma_f32_16x16x32_bf16 v[64:67], v[88:91], v[160:163], v[64:67]
	v_mfma_f32_16x16x32_bf16 v[68:71], v[112:115], v[160:163], v[68:71]
	v_mfma_f32_16x16x32_bf16 v[72:75], v[88:91], v[188:191], v[72:75]
	v_mfma_f32_16x16x32_bf16 v[76:79], v[112:115], v[188:191], v[76:79]
	v_mfma_f32_16x16x32_bf16 v[48:51], v[92:95], v[124:127], v[48:51]
	v_mfma_f32_16x16x32_bf16 v[52:55], v[116:119], v[124:127], v[52:55]
	v_mfma_f32_16x16x32_bf16 v[56:59], v[92:95], v[156:159], v[56:59]
	v_mfma_f32_16x16x32_bf16 v[60:63], v[116:119], v[156:159], v[60:63]
	v_mfma_f32_16x16x32_bf16 v[64:67], v[92:95], v[164:167], v[64:67]
	v_mfma_f32_16x16x32_bf16 v[68:71], v[116:119], v[164:167], v[68:71]
	v_mfma_f32_16x16x32_bf16 v[72:75], v[92:95], v[192:195], v[72:75]
	v_mfma_f32_16x16x32_bf16 v[76:79], v[116:119], v[192:195], v[76:79]
	s_barrier
	s_add_i32 s65, 0, 0x1c000
	s_add_i32 s64, s64, s28
	v_add_u32_e32 v223, s65, v236
	v_lshl_add_u64 v[172:173], v[172:173], 0, s[94:95]
	s_mov_b32 m0, s64
	s_add_i32 s43, s64, 0x2000
	ds_read_b128 v[196:199], v223
	ds_read_b128 v[200:203], v223 offset:1024
	ds_read_b128 v[204:207], v223 offset:2048
	ds_read_b128 v[208:211], v223 offset:3072
	global_load_lds_dwordx4 v[172:173], off
	v_lshl_add_u64 v[172:173], v[174:175], 0, s[94:95]
	s_mov_b32 m0, s43
	s_nop 0
	global_load_lds_dwordx4 v[172:173], off
	s_barrier
	s_waitcnt lgkmcnt(0)
	s_waitcnt lgkmcnt(0)
	v_mfma_f32_16x16x32_bf16 v[96:99], v[196:199], v[120:123], v[96:99]
	v_mfma_f32_16x16x32_bf16 v[16:19], v[204:207], v[120:123], v[16:19]
	v_mfma_f32_16x16x32_bf16 v[20:23], v[196:199], v[152:155], v[20:23]
	v_mfma_f32_16x16x32_bf16 v[24:27], v[204:207], v[152:155], v[24:27]
	v_mfma_f32_16x16x32_bf16 v[28:31], v[196:199], v[160:163], v[28:31]
	v_mfma_f32_16x16x32_bf16 v[32:35], v[204:207], v[160:163], v[32:35]
	v_mfma_f32_16x16x32_bf16 v[36:39], v[196:199], v[188:191], v[36:39]
	v_mfma_f32_16x16x32_bf16 v[40:43], v[204:207], v[188:191], v[40:43]
	v_mfma_f32_16x16x32_bf16 v[96:99], v[200:203], v[124:127], v[96:99]
	v_mfma_f32_16x16x32_bf16 v[16:19], v[208:211], v[124:127], v[16:19]
	v_mfma_f32_16x16x32_bf16 v[20:23], v[200:203], v[156:159], v[20:23]
	v_mfma_f32_16x16x32_bf16 v[24:27], v[208:211], v[156:159], v[24:27]
	v_mfma_f32_16x16x32_bf16 v[28:31], v[200:203], v[164:167], v[28:31]
	v_mfma_f32_16x16x32_bf16 v[32:35], v[208:211], v[164:167], v[32:35]
	v_mfma_f32_16x16x32_bf16 v[36:39], v[200:203], v[192:195], v[36:39]
	v_mfma_f32_16x16x32_bf16 v[40:43], v[208:211], v[192:195], v[40:43]
	s_mov_b32 m0, s61
	v_lshl_add_u64 v[172:173], v[176:177], 0, s[94:95]
	s_barrier
	ds_read_b128 v[120:123], v237 offset:49152
	ds_read_b128 v[124:127], v237 offset:50176
	ds_read_b128 v[152:155], v237 offset:51200
	ds_read_b128 v[156:159], v237 offset:52224
	ds_read_b128 v[160:163], v237 offset:53248
	ds_read_b128 v[164:167], v237 offset:54272
	ds_read_b128 v[188:191], v237 offset:55296
	ds_read_b128 v[192:195], v237 offset:56320
	global_load_lds_dwordx4 v[172:173], off
	v_lshl_add_u64 v[172:173], v[178:179], 0, s[94:95]
	s_mov_b32 m0, s62
	s_nop 0
	global_load_lds_dwordx4 v[172:173], off
	s_barrier
	s_waitcnt lgkmcnt(0)
	s_waitcnt lgkmcnt(0)
	v_mfma_f32_16x16x32_bf16 v[128:131], v[88:91], v[120:123], v[128:131]
	v_mfma_f32_16x16x32_bf16 v[132:135], v[112:115], v[120:123], v[132:135]
	v_mfma_f32_16x16x32_bf16 v[136:139], v[88:91], v[152:155], v[136:139]
	v_mfma_f32_16x16x32_bf16 v[140:143], v[112:115], v[152:155], v[140:143]
	v_mfma_f32_16x16x32_bf16 v[144:147], v[88:91], v[160:163], v[144:147]
	v_mfma_f32_16x16x32_bf16 v[148:151], v[112:115], v[160:163], v[148:151]
	v_mfma_f32_16x16x32_bf16 v[0:3], v[88:91], v[188:191], v[0:3]
	v_mfma_f32_16x16x32_bf16 v[4:7], v[112:115], v[188:191], v[4:7]
	v_mfma_f32_16x16x32_bf16 v[128:131], v[92:95], v[124:127], v[128:131]
	v_mfma_f32_16x16x32_bf16 v[132:135], v[116:119], v[124:127], v[132:135]
	v_mfma_f32_16x16x32_bf16 v[136:139], v[92:95], v[156:159], v[136:139]
	v_mfma_f32_16x16x32_bf16 v[140:143], v[116:119], v[156:159], v[140:143]
	v_mfma_f32_16x16x32_bf16 v[144:147], v[92:95], v[164:167], v[144:147]
	v_mfma_f32_16x16x32_bf16 v[148:151], v[116:119], v[164:167], v[148:151]
	v_mfma_f32_16x16x32_bf16 v[0:3], v[92:95], v[192:195], v[0:3]
	v_mfma_f32_16x16x32_bf16 v[4:7], v[116:119], v[192:195], v[4:7]
	s_barrier
	s_add_u32 s38, s50, 0x10180
	s_addc_u32 s39, s51, 0
	s_add_i32 s51, s65, s28
	v_lshl_add_u64 v[88:89], s[38:39], 0, v[184:185]
	s_mov_b32 m0, s51
	s_add_i32 s50, s51, 0x2000
	global_load_lds_dwordx4 v[88:89], off
	v_lshl_add_u64 v[88:89], s[38:39], 0, v[180:181]
	s_mov_b32 m0, s50
	s_nop 0
	global_load_lds_dwordx4 v[88:89], off
	s_waitcnt vmcnt(6)
	s_barrier
	v_mfma_f32_16x16x32_bf16 v[8:11], v[196:199], v[120:123], v[8:11]
	v_mfma_f32_16x16x32_bf16 v[12:15], v[204:207], v[120:123], v[12:15]
	v_mfma_f32_16x16x32_bf16 v[44:47], v[196:199], v[152:155], v[44:47]
	v_mfma_f32_16x16x32_bf16 v[88:91], v[204:207], v[152:155], v[100:103]
	v_mfma_f32_16x16x32_bf16 v[92:95], v[196:199], v[160:163], v[104:107]
	v_mfma_f32_16x16x32_bf16 v[100:103], v[204:207], v[160:163], v[108:111]
	v_mfma_f32_16x16x32_bf16 v[80:83], v[196:199], v[188:191], v[80:83]
	v_mfma_f32_16x16x32_bf16 v[84:87], v[204:207], v[188:191], v[84:87]
	v_mfma_f32_16x16x32_bf16 v[8:11], v[200:203], v[124:127], v[8:11]
	v_mfma_f32_16x16x32_bf16 v[12:15], v[208:211], v[124:127], v[12:15]
	v_mfma_f32_16x16x32_bf16 v[44:47], v[200:203], v[156:159], v[44:47]
	v_mfma_f32_16x16x32_bf16 v[88:91], v[208:211], v[156:159], v[88:91]
	v_mfma_f32_16x16x32_bf16 v[92:95], v[200:203], v[164:167], v[92:95]
	v_mfma_f32_16x16x32_bf16 v[100:103], v[208:211], v[164:167], v[100:103]
	v_mfma_f32_16x16x32_bf16 v[80:83], v[200:203], v[192:195], v[80:83]
	v_mfma_f32_16x16x32_bf16 v[84:87], v[208:211], v[192:195], v[84:87]
	s_barrier
	ds_read_b128 v[104:107], v168
	ds_read_b128 v[108:111], v168 offset:1024
	ds_read_b128 v[112:115], v168 offset:2048
	ds_read_b128 v[116:119], v168 offset:3072
	s_add_u32 s38, s48, 0x10180
	s_addc_u32 s39, s49, 0
	s_mov_b32 m0, s36
	v_lshl_add_u64 v[172:173], s[38:39], 0, v[186:187]
	ds_read_b128 v[120:123], v237
	ds_read_b128 v[124:127], v237 offset:1024
	ds_read_b128 v[152:155], v237 offset:2048
	ds_read_b128 v[156:159], v237 offset:3072
	ds_read_b128 v[160:163], v237 offset:4096
	ds_read_b128 v[164:167], v237 offset:5120
	ds_read_b128 v[188:191], v237 offset:6144
	ds_read_b128 v[192:195], v237 offset:7168
	global_load_lds_dwordx4 v[172:173], off
	v_lshl_add_u64 v[172:173], s[38:39], 0, v[182:183]
	s_mov_b32 m0, s15
	s_nop 0
	global_load_lds_dwordx4 v[172:173], off
	s_waitcnt lgkmcnt(8)
	s_barrier
	s_waitcnt lgkmcnt(0)
	s_waitcnt lgkmcnt(0)
	v_mfma_f32_16x16x32_bf16 v[48:51], v[104:107], v[120:123], v[48:51]
	v_mfma_f32_16x16x32_bf16 v[52:55], v[112:115], v[120:123], v[52:55]
	v_mfma_f32_16x16x32_bf16 v[56:59], v[104:107], v[152:155], v[56:59]
	v_mfma_f32_16x16x32_bf16 v[60:63], v[112:115], v[152:155], v[60:63]
	v_mfma_f32_16x16x32_bf16 v[64:67], v[104:107], v[160:163], v[64:67]
	v_mfma_f32_16x16x32_bf16 v[68:71], v[112:115], v[160:163], v[68:71]
	v_mfma_f32_16x16x32_bf16 v[72:75], v[104:107], v[188:191], v[72:75]
	v_mfma_f32_16x16x32_bf16 v[76:79], v[112:115], v[188:191], v[76:79]
	v_mfma_f32_16x16x32_bf16 v[48:51], v[108:111], v[124:127], v[48:51]
	v_mfma_f32_16x16x32_bf16 v[52:55], v[116:119], v[124:127], v[52:55]
	v_mfma_f32_16x16x32_bf16 v[56:59], v[108:111], v[156:159], v[56:59]
	v_mfma_f32_16x16x32_bf16 v[60:63], v[116:119], v[156:159], v[60:63]
	v_mfma_f32_16x16x32_bf16 v[64:67], v[108:111], v[164:167], v[64:67]
	v_mfma_f32_16x16x32_bf16 v[68:71], v[116:119], v[164:167], v[68:71]
	v_mfma_f32_16x16x32_bf16 v[72:75], v[108:111], v[192:195], v[72:75]
	v_mfma_f32_16x16x32_bf16 v[76:79], v[116:119], v[192:195], v[76:79]
	s_barrier
	s_mov_b32 m0, s35
	v_lshl_add_u64 v[172:173], s[52:53], 0, v[184:185]
	ds_read_b128 v[196:199], v212
	ds_read_b128 v[200:203], v212 offset:1024
	ds_read_b128 v[204:207], v212 offset:2048
	ds_read_b128 v[208:211], v212 offset:3072
	global_load_lds_dwordx4 v[172:173], off
	v_lshl_add_u64 v[174:175], s[52:53], 0, v[180:181]
	s_mov_b32 m0, s31
	s_nop 0
	global_load_lds_dwordx4 v[174:175], off
	s_barrier
	s_waitcnt lgkmcnt(0)
	s_waitcnt lgkmcnt(0)
	v_mfma_f32_16x16x32_bf16 v[96:99], v[196:199], v[120:123], v[96:99]
	v_mfma_f32_16x16x32_bf16 v[16:19], v[204:207], v[120:123], v[16:19]
	v_mfma_f32_16x16x32_bf16 v[20:23], v[196:199], v[152:155], v[20:23]
	v_mfma_f32_16x16x32_bf16 v[24:27], v[204:207], v[152:155], v[24:27]
	v_mfma_f32_16x16x32_bf16 v[28:31], v[196:199], v[160:163], v[28:31]
	v_mfma_f32_16x16x32_bf16 v[32:35], v[204:207], v[160:163], v[32:35]
	v_mfma_f32_16x16x32_bf16 v[36:39], v[196:199], v[188:191], v[36:39]
	v_mfma_f32_16x16x32_bf16 v[40:43], v[204:207], v[188:191], v[40:43]
	v_mfma_f32_16x16x32_bf16 v[96:99], v[200:203], v[124:127], v[96:99]
	v_mfma_f32_16x16x32_bf16 v[16:19], v[208:211], v[124:127], v[16:19]
	v_mfma_f32_16x16x32_bf16 v[20:23], v[200:203], v[156:159], v[20:23]
	v_mfma_f32_16x16x32_bf16 v[24:27], v[208:211], v[156:159], v[24:27]
	v_mfma_f32_16x16x32_bf16 v[28:31], v[200:203], v[164:167], v[28:31]
	v_mfma_f32_16x16x32_bf16 v[32:35], v[208:211], v[164:167], v[32:35]
	v_mfma_f32_16x16x32_bf16 v[36:39], v[200:203], v[192:195], v[36:39]
	v_mfma_f32_16x16x32_bf16 v[152:155], v[208:211], v[192:195], v[40:43]
	s_mov_b32 m0, s29
	v_lshl_add_u64 v[220:221], s[54:55], 0, v[186:187]
	s_barrier
	ds_read_b128 v[40:43], v237 offset:16384
	ds_read_b128 v[120:123], v237 offset:17408
	ds_read_b128 v[124:127], v237 offset:18432
	ds_read_b128 v[156:159], v237 offset:19456
	ds_read_b128 v[160:163], v237 offset:20480
	ds_read_b128 v[164:167], v237 offset:21504
	ds_read_b128 v[188:191], v237 offset:22528
	ds_read_b128 v[192:195], v237 offset:23552
	global_load_lds_dwordx4 v[220:221], off
	v_lshl_add_u64 v[250:251], s[54:55], 0, v[182:183]
	s_mov_b32 m0, s56
	s_nop 0
	global_load_lds_dwordx4 v[250:251], off
	s_barrier
	s_waitcnt lgkmcnt(0)
	s_waitcnt lgkmcnt(0)
	v_mfma_f32_16x16x32_bf16 v[132:135], v[112:115], v[40:43], v[132:135]
	v_mfma_f32_16x16x32_bf16 v[212:215], v[116:119], v[120:123], v[132:135]
	v_mfma_f32_16x16x32_bf16 v[132:135], v[104:107], v[124:127], v[136:139]
	v_mfma_f32_16x16x32_bf16 v[216:219], v[108:111], v[156:159], v[132:135]
	v_mfma_f32_16x16x32_bf16 v[132:135], v[112:115], v[124:127], v[140:143]
	v_mfma_f32_16x16x32_bf16 v[140:143], v[116:119], v[156:159], v[132:135]
	v_mfma_f32_16x16x32_bf16 v[132:135], v[104:107], v[160:163], v[144:147]
	v_mfma_f32_16x16x32_bf16 v[128:131], v[104:107], v[40:43], v[128:131]
	v_mfma_f32_16x16x32_bf16 v[238:241], v[108:111], v[164:167], v[132:135]
	v_mfma_f32_16x16x32_bf16 v[132:135], v[112:115], v[160:163], v[148:151]
	v_mfma_f32_16x16x32_bf16 v[0:3], v[104:107], v[188:191], v[0:3]
	v_mfma_f32_16x16x32_bf16 v[4:7], v[112:115], v[188:191], v[4:7]
	v_mfma_f32_16x16x32_bf16 v[128:131], v[108:111], v[120:123], v[128:131]
	v_mfma_f32_16x16x32_bf16 v[242:245], v[116:119], v[164:167], v[132:135]
	v_mfma_f32_16x16x32_bf16 v[0:3], v[108:111], v[192:195], v[0:3]
	v_mfma_f32_16x16x32_bf16 v[4:7], v[116:119], v[192:195], v[4:7]
	s_barrier
	s_add_u32 s36, s52, 0x10000
	s_mov_b32 m0, s37
	s_addc_u32 s37, s53, 0
	v_lshl_add_u64 v[104:105], s[36:37], 0, v[184:185]
	global_load_lds_dwordx4 v[104:105], off
	v_lshl_add_u64 v[104:105], s[36:37], 0, v[180:181]
	s_mov_b32 m0, s34
	s_nop 0
	global_load_lds_dwordx4 v[104:105], off
	s_waitcnt vmcnt(6)
	s_barrier
	v_mfma_f32_16x16x32_bf16 v[8:11], v[196:199], v[40:43], v[8:11]
	v_mfma_f32_16x16x32_bf16 v[12:15], v[204:207], v[40:43], v[12:15]
	v_mfma_f32_16x16x32_bf16 v[40:43], v[196:199], v[124:127], v[44:47]
	v_mfma_f32_16x16x32_bf16 v[104:107], v[200:203], v[156:159], v[40:43]
	v_mfma_f32_16x16x32_bf16 v[40:43], v[204:207], v[124:127], v[88:91]
	v_mfma_f32_16x16x32_bf16 v[116:119], v[208:211], v[156:159], v[40:43]
	v_mfma_f32_16x16x32_bf16 v[40:43], v[196:199], v[160:163], v[92:95]
	v_mfma_f32_16x16x32_bf16 v[92:95], v[200:203], v[164:167], v[40:43]
	v_mfma_f32_16x16x32_bf16 v[40:43], v[204:207], v[160:163], v[100:103]
	v_mfma_f32_16x16x32_bf16 v[156:159], v[208:211], v[164:167], v[40:43]
	v_mfma_f32_16x16x32_bf16 v[40:43], v[196:199], v[188:191], v[80:83]
	v_mfma_f32_16x16x32_bf16 v[80:83], v[200:203], v[192:195], v[40:43]
	v_mfma_f32_16x16x32_bf16 v[40:43], v[204:207], v[188:191], v[84:87]
	v_mfma_f32_16x16x32_bf16 v[8:11], v[200:203], v[120:123], v[8:11]
	v_mfma_f32_16x16x32_bf16 v[12:15], v[208:211], v[120:123], v[12:15]
	v_mfma_f32_16x16x32_bf16 v[188:191], v[208:211], v[192:195], v[40:43]
	s_barrier
	ds_read_b128 v[192:195], v222
	ds_read_b128 v[196:199], v222 offset:1024
	ds_read_b128 v[200:203], v222 offset:2048
	ds_read_b128 v[204:207], v222 offset:3072
	s_add_u32 s34, s54, 0x10000
	s_addc_u32 s35, s55, 0
	s_mov_b32 m0, s57
	v_lshl_add_u64 v[120:121], s[34:35], 0, v[186:187]
	ds_read_b128 v[40:43], v237 offset:32768
	ds_read_b128 v[44:47], v237 offset:33792
	ds_read_b128 v[84:87], v237 offset:34816
	ds_read_b128 v[88:91], v237 offset:35840
	ds_read_b128 v[100:103], v237 offset:36864
	ds_read_b128 v[108:111], v237 offset:37888
	ds_read_b128 v[112:115], v237 offset:38912
	ds_read_b128 v[208:211], v237 offset:39936
	global_load_lds_dwordx4 v[120:121], off
	v_lshl_add_u64 v[120:121], s[34:35], 0, v[182:183]
	s_mov_b32 m0, s58
	s_nop 0
	global_load_lds_dwordx4 v[120:121], off
	s_waitcnt lgkmcnt(8)
	s_barrier
	s_waitcnt lgkmcnt(0)
	s_waitcnt lgkmcnt(0)
	v_mfma_f32_16x16x32_bf16 v[48:51], v[192:195], v[40:43], v[48:51]
	v_mfma_f32_16x16x32_bf16 v[164:167], v[196:199], v[44:47], v[48:51]
	v_mfma_f32_16x16x32_bf16 v[48:51], v[200:203], v[40:43], v[52:55]
	v_mfma_f32_16x16x32_bf16 v[160:163], v[204:207], v[44:47], v[48:51]
	v_mfma_f32_16x16x32_bf16 v[48:51], v[192:195], v[84:87], v[56:59]
	v_mfma_f32_16x16x32_bf16 v[148:151], v[196:199], v[88:91], v[48:51]
	v_mfma_f32_16x16x32_bf16 v[48:51], v[200:203], v[84:87], v[60:63]
	v_mfma_f32_16x16x32_bf16 v[144:147], v[204:207], v[88:91], v[48:51]
	v_mfma_f32_16x16x32_bf16 v[48:51], v[192:195], v[100:103], v[64:67]
	v_mfma_f32_16x16x32_bf16 v[136:139], v[196:199], v[108:111], v[48:51]
	v_mfma_f32_16x16x32_bf16 v[48:51], v[200:203], v[100:103], v[68:71]
	v_mfma_f32_16x16x32_bf16 v[132:135], v[204:207], v[108:111], v[48:51]
	v_mfma_f32_16x16x32_bf16 v[48:51], v[192:195], v[112:115], v[72:75]
	v_mfma_f32_16x16x32_bf16 v[124:127], v[196:199], v[208:211], v[48:51]
	v_mfma_f32_16x16x32_bf16 v[48:51], v[200:203], v[112:115], v[76:79]
	v_mfma_f32_16x16x32_bf16 v[120:123], v[204:207], v[208:211], v[48:51]
	s_barrier
	s_mov_b32 m0, s64
	s_nop 3
	v_lshl_add_u64 v[48:49], v[172:173], 0, s[88:89]
	ds_read_b128 v[72:75], v223
	ds_read_b128 v[76:79], v223 offset:1024
	ds_read_b128 v[246:249], v223 offset:2048
	ds_read_b128 v[222:225], v223 offset:3072
	global_load_lds_dwordx4 v[48:49], off
	v_lshl_add_u64 v[48:49], v[174:175], 0, s[88:89]
	s_mov_b32 m0, s43
	s_nop 0
	global_load_lds_dwordx4 v[48:49], off
	s_barrier
	s_waitcnt lgkmcnt(0)
	s_waitcnt lgkmcnt(0)
	v_mfma_f32_16x16x32_bf16 v[16:19], v[246:249], v[40:43], v[16:19]
	v_mfma_f32_16x16x32_bf16 v[56:59], v[222:225], v[44:47], v[16:19]
	v_mfma_f32_16x16x32_bf16 v[16:19], v[72:75], v[84:87], v[20:23]
	v_mfma_f32_16x16x32_bf16 v[48:51], v[72:75], v[40:43], v[96:99]
	v_mfma_f32_16x16x32_bf16 v[52:55], v[76:79], v[88:91], v[16:19]
	v_mfma_f32_16x16x32_bf16 v[16:19], v[246:249], v[84:87], v[24:27]
	v_mfma_f32_16x16x32_bf16 v[60:63], v[76:79], v[44:47], v[48:51]
	v_mfma_f32_16x16x32_bf16 v[48:51], v[222:225], v[88:91], v[16:19]
	v_mfma_f32_16x16x32_bf16 v[16:19], v[72:75], v[100:103], v[28:31]
	v_mfma_f32_16x16x32_bf16 v[44:47], v[76:79], v[108:111], v[16:19]
	v_mfma_f32_16x16x32_bf16 v[16:19], v[246:249], v[100:103], v[32:35]
	v_mfma_f32_16x16x32_bf16 v[40:43], v[222:225], v[108:111], v[16:19]
	v_mfma_f32_16x16x32_bf16 v[16:19], v[72:75], v[112:115], v[36:39]
	v_mfma_f32_16x16x32_bf16 v[36:39], v[76:79], v[208:211], v[16:19]
	v_mfma_f32_16x16x32_bf16 v[16:19], v[246:249], v[112:115], v[152:155]
	v_mfma_f32_16x16x32_bf16 v[32:35], v[222:225], v[208:211], v[16:19]
	s_mov_b32 m0, s61
	v_lshl_add_u64 v[24:25], v[220:221], 0, s[88:89]
	s_barrier
	s_nop 2
	ds_read_b128 v[16:19], v237 offset:49152
	ds_read_b128 v[20:23], v237 offset:50176
	ds_read_b128 v[152:155], v237 offset:51200
	ds_read_b128 v[208:211], v237 offset:52224
	ds_read_b128 v[232:235], v237 offset:53248
	ds_read_b128 v[228:231], v237 offset:54272
	ds_read_b128 v[172:175], v237 offset:55296
	ds_read_b128 v[176:179], v237 offset:56320
	global_load_lds_dwordx4 v[24:25], off
	v_lshl_add_u64 v[24:25], v[250:251], 0, s[88:89]
	s_mov_b32 m0, s62
	s_nop 0
	global_load_lds_dwordx4 v[24:25], off
	s_barrier
	s_waitcnt lgkmcnt(0)
	s_waitcnt lgkmcnt(0)
	v_mfma_f32_16x16x32_bf16 v[24:27], v[192:195], v[16:19], v[128:131]
	v_mfma_f32_16x16x32_bf16 v[112:115], v[196:199], v[20:23], v[24:27]
	v_mfma_f32_16x16x32_bf16 v[24:27], v[200:203], v[16:19], v[212:215]
	v_mfma_f32_16x16x32_bf16 v[108:111], v[204:207], v[20:23], v[24:27]
	v_mfma_f32_16x16x32_bf16 v[24:27], v[192:195], v[152:155], v[216:219]
	v_mfma_f32_16x16x32_bf16 v[100:103], v[196:199], v[208:211], v[24:27]
	v_mfma_f32_16x16x32_bf16 v[24:27], v[200:203], v[152:155], v[140:143]
	v_mfma_f32_16x16x32_bf16 v[96:99], v[204:207], v[208:211], v[24:27]
	v_mfma_f32_16x16x32_bf16 v[24:27], v[192:195], v[232:235], v[238:241]
	v_mfma_f32_16x16x32_bf16 v[0:3], v[192:195], v[172:175], v[0:3]
	v_mfma_f32_16x16x32_bf16 v[88:91], v[196:199], v[228:231], v[24:27]
	v_mfma_f32_16x16x32_bf16 v[24:27], v[200:203], v[232:235], v[242:245]
	v_mfma_f32_16x16x32_bf16 v[68:71], v[196:199], v[176:179], v[0:3]
	v_mfma_f32_16x16x32_bf16 v[0:3], v[200:203], v[172:175], v[4:7]
	v_mfma_f32_16x16x32_bf16 v[84:87], v[204:207], v[228:231], v[24:27]
	v_mfma_f32_16x16x32_bf16 v[64:67], v[204:207], v[176:179], v[0:3]
	s_barrier
	s_add_u32 s34, s52, 0x10080
	s_addc_u32 s35, s53, 0
	s_mov_b32 m0, s51
	s_nop 0
	v_lshl_add_u64 v[0:1], s[34:35], 0, v[184:185]
	global_load_lds_dwordx4 v[0:1], off
	v_lshl_add_u64 v[0:1], s[34:35], 0, v[180:181]
	s_mov_b32 m0, s50
	s_nop 0
	global_load_lds_dwordx4 v[0:1], off
	s_waitcnt vmcnt(6)
	s_barrier
	v_mfma_f32_16x16x32_bf16 v[0:3], v[72:75], v[16:19], v[8:11]
	v_mfma_f32_16x16x32_bf16 v[28:31], v[76:79], v[20:23], v[0:3]
	v_mfma_f32_16x16x32_bf16 v[0:3], v[246:249], v[16:19], v[12:15]
	v_mfma_f32_16x16x32_bf16 v[24:27], v[222:225], v[20:23], v[0:3]
	v_mfma_f32_16x16x32_bf16 v[0:3], v[72:75], v[152:155], v[104:107]
	v_mfma_f32_16x16x32_bf16 v[20:23], v[76:79], v[208:211], v[0:3]
	v_mfma_f32_16x16x32_bf16 v[0:3], v[246:249], v[152:155], v[116:119]
	v_mfma_f32_16x16x32_bf16 v[16:19], v[222:225], v[208:211], v[0:3]
	v_mfma_f32_16x16x32_bf16 v[0:3], v[72:75], v[232:235], v[92:95]
	v_mfma_f32_16x16x32_bf16 v[12:15], v[76:79], v[228:231], v[0:3]
	v_mfma_f32_16x16x32_bf16 v[0:3], v[246:249], v[232:235], v[156:159]
	v_mfma_f32_16x16x32_bf16 v[8:11], v[222:225], v[228:231], v[0:3]
	v_mfma_f32_16x16x32_bf16 v[0:3], v[72:75], v[172:175], v[80:83]
	v_mfma_f32_16x16x32_bf16 v[4:7], v[76:79], v[176:179], v[0:3]
	v_mfma_f32_16x16x32_bf16 v[0:3], v[246:249], v[172:175], v[188:191]
	v_mfma_f32_16x16x32_bf16 v[0:3], v[222:225], v[176:179], v[0:3]
	v_mov_b32_e32 v72, v171
	s_lshl_b32 s15, s30, 8
	s_barrier
	s_add_i32 s15, s15, s59
	v_and_or_b32 v218, v72, 15, s15
	v_lshrrev_b32_e32 v72, 1, v72
	v_and_or_b32 v80, v72, 24, s60
	v_lshlrev_b32_e32 v238, 2, v80
	global_load_dwordx4 v[72:75], v238, s[8:9] offset:16
	global_load_dwordx4 v[76:79], v238, s[8:9]
	v_lshlrev_b32_e32 v168, 1, v80
	v_ashrrev_i32_e32 v219, 31, v218
	v_lshl_add_u64 v[80:81], s[6:7], 0, v[168:169]
	v_lshlrev_b64 v[188:189], 9, v[218:219]
	v_lshl_add_u64 v[82:83], v[80:81], 0, v[188:189]
	global_load_dwordx4 v[156:159], v[82:83], off
	v_or_b32_e32 v216, 16, v218
	v_ashrrev_i32_e32 v217, 31, v216
	v_lshlrev_b64 v[190:191], 9, v[216:217]
	v_lshl_add_u64 v[82:83], v[80:81], 0, v[190:191]
	global_load_dwordx4 v[152:155], v[82:83], off
	v_or_b32_e32 v214, 32, v218
	v_ashrrev_i32_e32 v215, 31, v214
	v_lshlrev_b64 v[192:193], 9, v[214:215]
	v_lshl_add_u64 v[82:83], v[80:81], 0, v[192:193]
	global_load_dwordx4 v[140:143], v[82:83], off
	v_or_b32_e32 v212, 48, v218
	v_add_u32_e32 v210, 0x80, v218
	v_ashrrev_i32_e32 v213, 31, v212
	v_ashrrev_i32_e32 v211, 31, v210
	v_lshlrev_b64 v[196:197], 9, v[212:213]
	v_add_u32_e32 v208, 0x90, v218
	v_lshl_add_u64 v[82:83], v[80:81], 0, v[196:197]
	v_lshlrev_b64 v[194:195], 9, v[210:211]
	v_ashrrev_i32_e32 v209, 31, v208
	v_add_u32_e32 v206, 0xa0, v218
	v_add_u32_e32 v204, 0xb0, v218
	global_load_dwordx4 v[128:131], v[82:83], off
	v_lshl_add_u64 v[82:83], v[80:81], 0, v[194:195]
	v_lshlrev_b64 v[198:199], 9, v[208:209]
	v_ashrrev_i32_e32 v207, 31, v206
	v_ashrrev_i32_e32 v205, 31, v204
	global_load_dwordx4 v[116:119], v[82:83], off
	v_lshl_add_u64 v[82:83], v[80:81], 0, v[198:199]
	v_lshlrev_b64 v[200:201], 9, v[206:207]
	v_lshlrev_b64 v[202:203], 9, v[204:205]
	global_load_dwordx4 v[104:107], v[82:83], off
	v_lshl_add_u64 v[82:83], v[80:81], 0, v[200:201]
	v_lshl_add_u64 v[80:81], v[80:81], 0, v[202:203]
	global_load_dwordx4 v[92:95], v[82:83], off
	s_add_i32 s63, s63, s96
	global_load_dwordx4 v[80:83], v[80:81], off
	s_andn2_b64 vcc, exec, s[40:41]
	s_mov_b32 s30, s42
	s_mov_b64 s[50:51], s[46:47]
	s_mov_b64 s[48:49], s[44:45]
	s_mov_b32 s39, 0x83ff
	s_movk_i32 s38, 0x1000
	v_mov_b64_e32 v[240:241], 0x1ff
	s_waitcnt vmcnt(0)
	v_pk_add_f32 v[160:161], v[160:161], v[72:73]
	v_pk_add_f32 v[164:165], v[164:165], v[76:77]
	v_pk_add_f32 v[166:167], v[166:167], v[78:79]
	v_mul_f32_e32 v164, 0xbfb8aa3b, v164
	v_mul_f32_e32 v165, 0xbfb8aa3b, v165
	v_exp_f32_e32 v164, v164
	v_exp_f32_e32 v165, v165
	v_lshlrev_b32_e32 v172, 16, v156
	v_and_b32_e32 v173, 0xffff0000, v156
	v_add_f32_e32 v164, 1.0, v164
	v_add_f32_e32 v165, 1.0, v165
	v_rcp_f32_e32 v164, v164
	v_rcp_f32_e32 v165, v165
	v_mul_f32_e32 v160, 0xbfb8aa3b, v160
	v_mul_f32_e32 v161, 0xbfb8aa3b, v161
	v_exp_f32_e32 v160, v160
	v_pk_mul_f32 v[164:165], v[164:165], v[172:173]
	v_exp_f32_e32 v161, v161
	v_cvt_pk_bf16_f32 v156, v164, v165
	v_mul_f32_e32 v164, 0xbfb8aa3b, v166
	v_mul_f32_e32 v165, 0xbfb8aa3b, v167
	v_exp_f32_e32 v164, v164
	v_exp_f32_e32 v165, v165
	v_add_f32_e32 v160, 1.0, v160
	v_add_f32_e32 v161, 1.0, v161
	v_add_f32_e32 v164, 1.0, v164
	v_add_f32_e32 v165, 1.0, v165
	v_rcp_f32_e32 v164, v164
	v_rcp_f32_e32 v165, v165
	v_rcp_f32_e32 v160, v160
	v_rcp_f32_e32 v161, v161
	v_lshlrev_b32_e32 v166, 16, v157
	v_and_b32_e32 v167, 0xffff0000, v157
	v_pk_mul_f32 v[164:165], v[164:165], v[166:167]
	v_pk_add_f32 v[162:163], v[162:163], v[74:75]
	v_cvt_pk_bf16_f32 v157, v164, v165
	v_lshlrev_b32_e32 v164, 16, v158
	v_and_b32_e32 v165, 0xffff0000, v158
	v_pk_mul_f32 v[160:161], v[160:161], v[164:165]
	v_pk_add_f32 v[148:149], v[148:149], v[76:77]
	v_cvt_pk_bf16_f32 v158, v160, v161
	v_mul_f32_e32 v160, 0xbfb8aa3b, v162
	v_mul_f32_e32 v161, 0xbfb8aa3b, v163
	v_exp_f32_e32 v160, v160
	v_exp_f32_e32 v161, v161
	v_lshlrev_b32_e32 v162, 16, v159
	v_and_b32_e32 v163, 0xffff0000, v159
	v_add_f32_e32 v160, 1.0, v160
	v_add_f32_e32 v161, 1.0, v161
	v_rcp_f32_e32 v160, v160
	v_rcp_f32_e32 v161, v161
	v_pk_add_f32 v[150:151], v[150:151], v[78:79]
	v_pk_add_f32 v[144:145], v[144:145], v[72:73]
	v_pk_add_f32 v[136:137], v[136:137], v[76:77]
	v_pk_mul_f32 v[160:161], v[160:161], v[162:163]
	v_mul_f32_e32 v144, 0xbfb8aa3b, v144
	v_cvt_pk_bf16_f32 v159, v160, v161
	v_lshlrev_b64 v[160:161], 11, v[218:219]
	v_lshl_add_u64 v[160:161], s[10:11], 0, v[160:161]
	v_lshl_add_u64 v[160:161], v[160:161], 0, v[168:169]
	global_store_dwordx4 v[160:161], v[156:159], off offset:1536
	v_mul_f32_e32 v145, 0xbfb8aa3b, v145
	v_exp_f32_e32 v144, v144
	v_pk_add_f32 v[156:157], v[146:147], v[74:75]
	v_mul_f32_e32 v146, 0xbfb8aa3b, v148
	v_mul_f32_e32 v147, 0xbfb8aa3b, v149
	v_exp_f32_e32 v146, v146
	v_exp_f32_e32 v147, v147
	v_lshlrev_b32_e32 v148, 16, v152
	v_and_b32_e32 v149, 0xffff0000, v152
	v_add_f32_e32 v146, 1.0, v146
	v_add_f32_e32 v147, 1.0, v147
	v_rcp_f32_e32 v146, v146
	v_rcp_f32_e32 v147, v147
	v_exp_f32_e32 v145, v145
	v_add_f32_e32 v144, 1.0, v144
	v_rcp_f32_e32 v144, v144
	v_pk_mul_f32 v[146:147], v[146:147], v[148:149]
	v_add_f32_e32 v145, 1.0, v145
	v_cvt_pk_bf16_f32 v146, v146, v147
	v_mul_f32_e32 v147, 0xbfb8aa3b, v150
	v_exp_f32_e32 v147, v147
	v_rcp_f32_e32 v145, v145
	v_lshlrev_b32_e32 v150, 16, v153
	v_pk_add_f32 v[138:139], v[138:139], v[78:79]
	v_add_f32_e32 v147, 1.0, v147
	v_rcp_f32_e32 v148, v147
	v_mul_f32_e32 v147, 0xbfb8aa3b, v151
	v_exp_f32_e32 v147, v147
	v_and_b32_e32 v151, 0xffff0000, v153
	v_pk_add_f32 v[132:133], v[132:133], v[72:73]
	v_pk_add_f32 v[124:125], v[124:125], v[76:77]
	v_add_f32_e32 v147, 1.0, v147
	v_rcp_f32_e32 v149, v147
	v_mul_f32_e32 v132, 0xbfb8aa3b, v132
	v_mul_f32_e32 v133, 0xbfb8aa3b, v133
	v_exp_f32_e32 v132, v132
	v_pk_mul_f32 v[148:149], v[148:149], v[150:151]
	v_lshlrev_b32_e32 v150, 16, v155
	v_cvt_pk_bf16_f32 v147, v148, v149
	v_lshlrev_b32_e32 v148, 16, v154
	v_and_b32_e32 v149, 0xffff0000, v154
	v_pk_mul_f32 v[144:145], v[144:145], v[148:149]
	v_and_b32_e32 v151, 0xffff0000, v155
	v_cvt_pk_bf16_f32 v148, v144, v145
	v_mul_f32_e32 v144, 0xbfb8aa3b, v156
	v_mul_f32_e32 v145, 0xbfb8aa3b, v157
	v_exp_f32_e32 v144, v144
	v_exp_f32_e32 v145, v145
	v_exp_f32_e32 v133, v133
	v_add_f32_e32 v132, 1.0, v132
	v_add_f32_e32 v144, 1.0, v144
	v_add_f32_e32 v145, 1.0, v145
	v_rcp_f32_e32 v144, v144
	v_rcp_f32_e32 v145, v145
	v_add_f32_e32 v133, 1.0, v133
	v_rcp_f32_e32 v132, v132
	v_rcp_f32_e32 v133, v133
	v_pk_mul_f32 v[144:145], v[144:145], v[150:151]
	v_pk_add_f32 v[126:127], v[126:127], v[78:79]
	v_cvt_pk_bf16_f32 v149, v144, v145
	v_lshlrev_b64 v[144:145], 11, v[216:217]
	v_lshl_add_u64 v[144:145], s[10:11], 0, v[144:145]
	v_lshl_add_u64 v[144:145], v[144:145], 0, v[168:169]
	global_store_dwordx4 v[144:145], v[146:149], off offset:1536
	v_pk_add_f32 v[120:121], v[120:121], v[72:73]
	v_pk_add_f32 v[112:113], v[112:113], v[76:77]
	v_pk_add_f32 v[146:147], v[134:135], v[74:75]
	v_mul_f32_e32 v134, 0xbfb8aa3b, v136
	v_mul_f32_e32 v135, 0xbfb8aa3b, v137
	v_exp_f32_e32 v134, v134
	v_exp_f32_e32 v135, v135
	v_lshlrev_b32_e32 v136, 16, v140
	v_and_b32_e32 v137, 0xffff0000, v140
	v_add_f32_e32 v134, 1.0, v134
	v_add_f32_e32 v135, 1.0, v135
	v_rcp_f32_e32 v134, v134
	v_rcp_f32_e32 v135, v135
	v_mul_f32_e32 v120, 0xbfb8aa3b, v120
	v_mul_f32_e32 v121, 0xbfb8aa3b, v121
	v_exp_f32_e32 v120, v120
	v_pk_mul_f32 v[134:135], v[134:135], v[136:137]
	v_exp_f32_e32 v121, v121
	v_cvt_pk_bf16_f32 v134, v134, v135
	v_mul_f32_e32 v135, 0xbfb8aa3b, v138
	v_exp_f32_e32 v135, v135
	v_lshlrev_b32_e32 v138, 16, v141
	v_add_f32_e32 v120, 1.0, v120
	v_add_f32_e32 v121, 1.0, v121
	v_add_f32_e32 v135, 1.0, v135
	v_rcp_f32_e32 v136, v135
	v_mul_f32_e32 v135, 0xbfb8aa3b, v139
	v_exp_f32_e32 v135, v135
	v_and_b32_e32 v139, 0xffff0000, v141
	v_rcp_f32_e32 v120, v120
	v_rcp_f32_e32 v121, v121
	v_add_f32_e32 v135, 1.0, v135
	v_rcp_f32_e32 v137, v135
	v_pk_add_f32 v[114:115], v[114:115], v[78:79]
	v_pk_add_f32 v[108:109], v[108:109], v[72:73]
	v_pk_add_f32 v[100:101], v[100:101], v[76:77]
	v_pk_mul_f32 v[136:137], v[136:137], v[138:139]
	v_lshlrev_b32_e32 v138, 16, v143
	v_cvt_pk_bf16_f32 v135, v136, v137
	v_lshlrev_b32_e32 v136, 16, v142
	v_and_b32_e32 v137, 0xffff0000, v142
	v_pk_mul_f32 v[132:133], v[132:133], v[136:137]
	v_and_b32_e32 v139, 0xffff0000, v143
	v_cvt_pk_bf16_f32 v136, v132, v133
	v_mul_f32_e32 v132, 0xbfb8aa3b, v146
	v_mul_f32_e32 v133, 0xbfb8aa3b, v147
	v_exp_f32_e32 v132, v132
	v_exp_f32_e32 v133, v133
	v_mul_f32_e32 v108, 0xbfb8aa3b, v108
	v_mul_f32_e32 v109, 0xbfb8aa3b, v109
	v_add_f32_e32 v132, 1.0, v132
	v_add_f32_e32 v133, 1.0, v133
	v_rcp_f32_e32 v132, v132
	v_rcp_f32_e32 v133, v133
	v_exp_f32_e32 v108, v108
	v_exp_f32_e32 v109, v109
	v_pk_add_f32 v[102:103], v[102:103], v[78:79]
	v_pk_mul_f32 v[132:133], v[132:133], v[138:139]
	v_add_f32_e32 v108, 1.0, v108
	v_cvt_pk_bf16_f32 v137, v132, v133
	v_lshlrev_b64 v[132:133], 11, v[214:215]
	v_lshl_add_u64 v[132:133], s[10:11], 0, v[132:133]
	v_lshl_add_u64 v[132:133], v[132:133], 0, v[168:169]
	global_store_dwordx4 v[132:133], v[134:137], off offset:1536
	v_add_f32_e32 v109, 1.0, v109
	v_rcp_f32_e32 v108, v108
	v_pk_add_f32 v[134:135], v[122:123], v[74:75]
	v_mul_f32_e32 v122, 0xbfb8aa3b, v124
	v_mul_f32_e32 v123, 0xbfb8aa3b, v125
	v_exp_f32_e32 v122, v122
	v_exp_f32_e32 v123, v123
	v_lshlrev_b32_e32 v124, 16, v128
	v_and_b32_e32 v125, 0xffff0000, v128
	v_add_f32_e32 v122, 1.0, v122
	v_add_f32_e32 v123, 1.0, v123
	v_rcp_f32_e32 v122, v122
	v_rcp_f32_e32 v123, v123
	v_rcp_f32_e32 v109, v109
	v_pk_add_f32 v[88:89], v[88:89], v[76:77]
	v_pk_add_f32 v[68:69], v[68:69], v[76:77]
	v_pk_mul_f32 v[122:123], v[122:123], v[124:125]
	v_pk_add_f32 v[90:91], v[90:91], v[78:79]
	v_cvt_pk_bf16_f32 v122, v122, v123
	v_mul_f32_e32 v123, 0xbfb8aa3b, v126
	v_exp_f32_e32 v123, v123
	v_lshlrev_b32_e32 v126, 16, v129
	v_pk_add_f32 v[70:71], v[70:71], v[78:79]
	v_add_f32_e32 v123, 1.0, v123
	v_rcp_f32_e32 v124, v123
	v_mul_f32_e32 v123, 0xbfb8aa3b, v127
	v_exp_f32_e32 v123, v123
	v_and_b32_e32 v127, 0xffff0000, v129
	v_add_f32_e32 v123, 1.0, v123
	v_rcp_f32_e32 v125, v123
	s_nop 0
	v_pk_mul_f32 v[124:125], v[124:125], v[126:127]
	s_nop 0
	v_cvt_pk_bf16_f32 v123, v124, v125
	v_lshlrev_b32_e32 v124, 16, v130
	v_and_b32_e32 v125, 0xffff0000, v130
	v_pk_mul_f32 v[120:121], v[120:121], v[124:125]
	v_lshlrev_b32_e32 v126, 16, v131
	v_cvt_pk_bf16_f32 v124, v120, v121
	v_mul_f32_e32 v120, 0xbfb8aa3b, v134
	v_mul_f32_e32 v121, 0xbfb8aa3b, v135
	v_exp_f32_e32 v120, v120
	v_exp_f32_e32 v121, v121
	v_and_b32_e32 v127, 0xffff0000, v131
	v_add_f32_e32 v120, 1.0, v120
	v_add_f32_e32 v121, 1.0, v121
	v_rcp_f32_e32 v120, v120
	v_rcp_f32_e32 v121, v121
	s_nop 0
	v_pk_mul_f32 v[120:121], v[120:121], v[126:127]
	s_nop 0
	v_cvt_pk_bf16_f32 v125, v120, v121
	v_lshlrev_b64 v[120:121], 11, v[212:213]
	v_lshl_add_u64 v[120:121], s[10:11], 0, v[120:121]
	v_lshl_add_u64 v[120:121], v[120:121], 0, v[168:169]
	global_store_dwordx4 v[120:121], v[122:125], off offset:1536
	s_nop 1
	v_pk_add_f32 v[122:123], v[110:111], v[74:75]
	v_mul_f32_e32 v110, 0xbfb8aa3b, v112
	v_mul_f32_e32 v111, 0xbfb8aa3b, v113
	v_exp_f32_e32 v110, v110
	v_exp_f32_e32 v111, v111
	v_lshlrev_b32_e32 v112, 16, v116
	v_and_b32_e32 v113, 0xffff0000, v116
	v_add_f32_e32 v110, 1.0, v110
	v_add_f32_e32 v111, 1.0, v111
	v_rcp_f32_e32 v110, v110
	v_rcp_f32_e32 v111, v111
	s_nop 0
	v_pk_mul_f32 v[110:111], v[110:111], v[112:113]
	s_nop 0
	v_cvt_pk_bf16_f32 v110, v110, v111
	v_mul_f32_e32 v111, 0xbfb8aa3b, v114
	v_exp_f32_e32 v111, v111
	v_lshlrev_b32_e32 v114, 16, v117
	v_add_f32_e32 v111, 1.0, v111
	v_rcp_f32_e32 v112, v111
	v_mul_f32_e32 v111, 0xbfb8aa3b, v115
	v_exp_f32_e32 v111, v111
	v_and_b32_e32 v115, 0xffff0000, v117
	v_add_f32_e32 v111, 1.0, v111
	v_rcp_f32_e32 v113, v111
	s_nop 0
	v_pk_mul_f32 v[112:113], v[112:113], v[114:115]
	s_nop 0
	v_cvt_pk_bf16_f32 v111, v112, v113
	v_lshlrev_b32_e32 v112, 16, v118
	v_and_b32_e32 v113, 0xffff0000, v118
	v_pk_mul_f32 v[108:109], v[108:109], v[112:113]
	v_lshlrev_b32_e32 v114, 16, v119
	v_cvt_pk_bf16_f32 v112, v108, v109
	v_mul_f32_e32 v108, 0xbfb8aa3b, v122
	v_mul_f32_e32 v109, 0xbfb8aa3b, v123
	v_exp_f32_e32 v108, v108
	v_exp_f32_e32 v109, v109
	v_and_b32_e32 v115, 0xffff0000, v119
	v_add_f32_e32 v108, 1.0, v108
	v_add_f32_e32 v109, 1.0, v109
	v_rcp_f32_e32 v108, v108
	v_rcp_f32_e32 v109, v109
	s_nop 0
	v_pk_mul_f32 v[108:109], v[108:109], v[114:115]
	s_nop 0
	v_cvt_pk_bf16_f32 v113, v108, v109
	v_lshlrev_b64 v[108:109], 11, v[210:211]
	v_lshl_add_u64 v[108:109], s[10:11], 0, v[108:109]
	v_lshl_add_u64 v[108:109], v[108:109], 0, v[168:169]
	global_store_dwordx4 v[108:109], v[110:113], off offset:1536
	s_nop 1
	v_pk_add_f32 v[110:111], v[98:99], v[74:75]
	v_pk_add_f32 v[98:99], v[96:97], v[72:73]
	v_mul_f32_e32 v96, 0xbfb8aa3b, v100
	v_mul_f32_e32 v97, 0xbfb8aa3b, v101
	v_exp_f32_e32 v96, v96
	v_exp_f32_e32 v97, v97
	v_lshlrev_b32_e32 v100, 16, v104
	v_and_b32_e32 v101, 0xffff0000, v104
	v_add_f32_e32 v96, 1.0, v96
	v_add_f32_e32 v97, 1.0, v97
	v_rcp_f32_e32 v96, v96
	v_rcp_f32_e32 v97, v97
	v_mul_f32_e32 v98, 0xbfb8aa3b, v98
	v_mul_f32_e32 v99, 0xbfb8aa3b, v99
	v_exp_f32_e32 v98, v98
	v_pk_mul_f32 v[96:97], v[96:97], v[100:101]
	v_exp_f32_e32 v99, v99
	v_cvt_pk_bf16_f32 v96, v96, v97
	v_mul_f32_e32 v97, 0xbfb8aa3b, v102
	v_exp_f32_e32 v97, v97
	v_add_f32_e32 v98, 1.0, v98
	v_add_f32_e32 v99, 1.0, v99
	v_rcp_f32_e32 v98, v98
	v_add_f32_e32 v97, 1.0, v97
	v_rcp_f32_e32 v100, v97
	v_mul_f32_e32 v97, 0xbfb8aa3b, v103
	v_exp_f32_e32 v97, v97
	v_rcp_f32_e32 v99, v99
	v_lshlrev_b32_e32 v102, 16, v105
	v_and_b32_e32 v103, 0xffff0000, v105
	v_add_f32_e32 v97, 1.0, v97
	v_rcp_f32_e32 v101, v97
	s_nop 0
	v_pk_mul_f32 v[100:101], v[100:101], v[102:103]
	s_nop 0
	v_cvt_pk_bf16_f32 v97, v100, v101
	v_lshlrev_b32_e32 v100, 16, v106
	v_and_b32_e32 v101, 0xffff0000, v106
	v_pk_mul_f32 v[98:99], v[98:99], v[100:101]
	v_lshlrev_b32_e32 v102, 16, v107
	v_cvt_pk_bf16_f32 v98, v98, v99
	v_mul_f32_e32 v99, 0xbfb8aa3b, v110
	v_exp_f32_e32 v99, v99
	v_and_b32_e32 v103, 0xffff0000, v107
	v_add_f32_e32 v99, 1.0, v99
	v_rcp_f32_e32 v100, v99
	v_mul_f32_e32 v99, 0xbfb8aa3b, v111
	v_exp_f32_e32 v99, v99
	s_nop 0
	v_add_f32_e32 v99, 1.0, v99
	v_rcp_f32_e32 v101, v99
	s_nop 0
	v_pk_mul_f32 v[100:101], v[100:101], v[102:103]
	s_nop 0
	v_cvt_pk_bf16_f32 v99, v100, v101
	v_lshlrev_b64 v[100:101], 11, v[208:209]
	v_lshl_add_u64 v[100:101], s[10:11], 0, v[100:101]
	v_lshl_add_u64 v[100:101], v[100:101], 0, v[168:169]
	global_store_dwordx4 v[100:101], v[96:99], off offset:1536
	s_nop 1
	v_pk_add_f32 v[96:97], v[86:87], v[74:75]
	v_pk_add_f32 v[86:87], v[84:85], v[72:73]
	v_mul_f32_e32 v84, 0xbfb8aa3b, v88
	v_mul_f32_e32 v85, 0xbfb8aa3b, v89
	v_pk_add_f32 v[74:75], v[66:67], v[74:75]
	v_pk_add_f32 v[66:67], v[64:65], v[72:73]
	v_mul_f32_e32 v64, 0xbfb8aa3b, v68
	v_mul_f32_e32 v65, 0xbfb8aa3b, v69
	v_exp_f32_e32 v84, v84
	v_exp_f32_e32 v85, v85
	v_exp_f32_e32 v64, v64
	v_exp_f32_e32 v65, v65
	v_add_f32_e32 v84, 1.0, v84
	v_add_f32_e32 v85, 1.0, v85
	v_add_f32_e32 v64, 1.0, v64
	v_add_f32_e32 v65, 1.0, v65
	v_rcp_f32_e32 v84, v84
	v_rcp_f32_e32 v85, v85
	v_rcp_f32_e32 v64, v64
	v_rcp_f32_e32 v65, v65
	v_lshlrev_b32_e32 v88, 16, v92
	v_and_b32_e32 v89, 0xffff0000, v92
	v_lshlrev_b32_e32 v68, 16, v80
	v_and_b32_e32 v69, 0xffff0000, v80
	v_pk_mul_f32 v[84:85], v[84:85], v[88:89]
	v_pk_mul_f32 v[64:65], v[64:65], v[68:69]
	v_cvt_pk_bf16_f32 v84, v84, v85
	v_mul_f32_e32 v85, 0xbfb8aa3b, v90
	v_cvt_pk_bf16_f32 v64, v64, v65
	v_mul_f32_e32 v65, 0xbfb8aa3b, v70
	v_exp_f32_e32 v85, v85
	v_exp_f32_e32 v65, v65
	v_mul_f32_e32 v86, 0xbfb8aa3b, v86
	v_mul_f32_e32 v87, 0xbfb8aa3b, v87
	v_add_f32_e32 v85, 1.0, v85
	v_add_f32_e32 v65, 1.0, v65
	v_rcp_f32_e32 v88, v85
	v_mul_f32_e32 v85, 0xbfb8aa3b, v91
	v_rcp_f32_e32 v68, v65
	v_mul_f32_e32 v65, 0xbfb8aa3b, v71
	v_exp_f32_e32 v85, v85
	v_exp_f32_e32 v65, v65
	v_mul_f32_e32 v66, 0xbfb8aa3b, v66
	v_mul_f32_e32 v67, 0xbfb8aa3b, v67
	v_exp_f32_e32 v86, v86
	v_exp_f32_e32 v87, v87
	v_exp_f32_e32 v66, v66
	v_exp_f32_e32 v67, v67
	v_add_f32_e32 v85, 1.0, v85
	v_add_f32_e32 v65, 1.0, v65
	v_rcp_f32_e32 v89, v85
	v_rcp_f32_e32 v69, v65
	v_add_f32_e32 v86, 1.0, v86
	v_add_f32_e32 v87, 1.0, v87
	v_add_f32_e32 v66, 1.0, v66
	v_add_f32_e32 v67, 1.0, v67
	v_rcp_f32_e32 v86, v86
	v_rcp_f32_e32 v87, v87
	v_rcp_f32_e32 v66, v66
	v_rcp_f32_e32 v67, v67
	v_lshlrev_b32_e32 v90, 16, v93
	v_and_b32_e32 v91, 0xffff0000, v93
	v_lshlrev_b32_e32 v70, 16, v81
	v_and_b32_e32 v71, 0xffff0000, v81
	v_pk_mul_f32 v[88:89], v[88:89], v[90:91]
	v_pk_mul_f32 v[68:69], v[68:69], v[70:71]
	v_cvt_pk_bf16_f32 v85, v88, v89
	v_lshlrev_b32_e32 v88, 16, v94
	v_and_b32_e32 v89, 0xffff0000, v94
	v_cvt_pk_bf16_f32 v65, v68, v69
	v_lshlrev_b32_e32 v68, 16, v82
	v_and_b32_e32 v69, 0xffff0000, v82
	v_pk_mul_f32 v[86:87], v[86:87], v[88:89]
	v_pk_mul_f32 v[66:67], v[66:67], v[68:69]
	v_cvt_pk_bf16_f32 v86, v86, v87
	v_mul_f32_e32 v87, 0xbfb8aa3b, v96
	v_cvt_pk_bf16_f32 v66, v66, v67
	v_mul_f32_e32 v67, 0xbfb8aa3b, v74
	v_exp_f32_e32 v87, v87
	v_exp_f32_e32 v67, v67
	v_lshlrev_b32_e32 v90, 16, v95
	v_and_b32_e32 v91, 0xffff0000, v95
	v_add_f32_e32 v87, 1.0, v87
	v_add_f32_e32 v67, 1.0, v67
	v_rcp_f32_e32 v88, v87
	v_mul_f32_e32 v87, 0xbfb8aa3b, v97
	v_rcp_f32_e32 v68, v67
	v_mul_f32_e32 v67, 0xbfb8aa3b, v75
	v_exp_f32_e32 v87, v87
	v_exp_f32_e32 v67, v67
	v_lshlrev_b32_e32 v70, 16, v83
	v_and_b32_e32 v71, 0xffff0000, v83
	v_add_f32_e32 v87, 1.0, v87
	v_add_f32_e32 v67, 1.0, v67
	v_rcp_f32_e32 v89, v87
	v_rcp_f32_e32 v69, v67
	v_pk_mul_f32 v[88:89], v[88:89], v[90:91]
	v_pk_mul_f32 v[68:69], v[68:69], v[70:71]
	v_cvt_pk_bf16_f32 v87, v88, v89
	v_lshlrev_b64 v[88:89], 11, v[206:207]
	v_cvt_pk_bf16_f32 v67, v68, v69
	v_lshlrev_b64 v[68:69], 11, v[204:205]
	v_lshl_add_u64 v[88:89], s[10:11], 0, v[88:89]
	v_lshl_add_u64 v[68:69], s[10:11], 0, v[68:69]
	v_lshl_add_u64 v[102:103], v[88:89], 0, v[168:169]
	v_lshl_add_u64 v[104:105], v[68:69], 0, v[168:169]
	global_store_dwordx4 v[102:103], v[84:87], off offset:1536
	global_store_dwordx4 v[104:105], v[64:67], off offset:1536
	global_load_dwordx4 v[68:71], v238, s[8:9] offset:528
	global_load_dwordx4 v[72:75], v238, s[8:9] offset:512
	v_lshl_add_u64 v[64:65], s[6:7], 0, v[188:189]
	v_or_b32_e32 v168, 0x100, v168
	v_lshl_add_u64 v[64:65], v[64:65], 0, v[168:169]
	global_load_dwordx4 v[110:113], v[64:65], off
	v_lshl_add_u64 v[64:65], s[6:7], 0, v[190:191]
	v_lshl_add_u64 v[64:65], v[64:65], 0, v[168:169]
	global_load_dwordx4 v[96:99], v[64:65], off
	v_lshl_add_u64 v[64:65], s[6:7], 0, v[192:193]
	v_lshl_add_u64 v[64:65], v[64:65], 0, v[168:169]
	global_load_dwordx4 v[92:95], v[64:65], off
	v_lshl_add_u64 v[64:65], s[6:7], 0, v[196:197]
	v_lshl_add_u64 v[64:65], v[64:65], 0, v[168:169]
	global_load_dwordx4 v[88:91], v[64:65], off
	v_lshl_add_u64 v[64:65], s[6:7], 0, v[194:195]
	v_lshl_add_u64 v[64:65], v[64:65], 0, v[168:169]
	global_load_dwordx4 v[84:87], v[64:65], off
	v_lshl_add_u64 v[64:65], s[6:7], 0, v[198:199]
	v_lshl_add_u64 v[64:65], v[64:65], 0, v[168:169]
	global_load_dwordx4 v[80:83], v[64:65], off
	v_lshl_add_u64 v[64:65], s[6:7], 0, v[200:201]
	v_lshl_add_u64 v[64:65], v[64:65], 0, v[168:169]
	global_load_dwordx4 v[76:79], v[64:65], off
	v_lshl_add_u64 v[64:65], s[6:7], 0, v[202:203]
	v_lshl_add_u64 v[64:65], v[64:65], 0, v[168:169]
	global_load_dwordx4 v[64:67], v[64:65], off
	v_mov_b64_e32 v[238:239], v[226:227]
	v_mov_b32_e32 v227, v170
	v_mov_b32_e32 v170, 0x358637bd
	s_waitcnt vmcnt(0)
	v_pk_add_f32 v[106:107], v[58:59], v[70:71]
	v_pk_add_f32 v[60:61], v[60:61], v[72:73]
	v_pk_add_f32 v[58:59], v[56:57], v[68:69]
	v_mul_f32_e32 v56, 0xbfb8aa3b, v60
	v_mul_f32_e32 v57, 0xbfb8aa3b, v61
	v_exp_f32_e32 v56, v56
	v_exp_f32_e32 v57, v57
	v_lshlrev_b32_e32 v60, 16, v110
	v_and_b32_e32 v61, 0xffff0000, v110
	v_add_f32_e32 v56, 1.0, v56
	v_add_f32_e32 v57, 1.0, v57
	v_rcp_f32_e32 v56, v56
	v_rcp_f32_e32 v57, v57
	v_pk_add_f32 v[62:63], v[62:63], v[74:75]
	v_mul_f32_e32 v58, 0xbfb8aa3b, v58
	v_mul_f32_e32 v59, 0xbfb8aa3b, v59
	v_pk_mul_f32 v[56:57], v[56:57], v[60:61]
	v_exp_f32_e32 v58, v58
	v_cvt_pk_bf16_f32 v56, v56, v57
	v_mul_f32_e32 v57, 0xbfb8aa3b, v62
	v_exp_f32_e32 v57, v57
	v_exp_f32_e32 v59, v59
	v_add_f32_e32 v58, 1.0, v58
	v_rcp_f32_e32 v58, v58
	v_add_f32_e32 v57, 1.0, v57
	v_rcp_f32_e32 v60, v57
	v_mul_f32_e32 v57, 0xbfb8aa3b, v63
	v_exp_f32_e32 v57, v57
	v_add_f32_e32 v59, 1.0, v59
	v_rcp_f32_e32 v59, v59
	v_lshlrev_b32_e32 v62, 16, v111
	v_add_f32_e32 v57, 1.0, v57
	v_rcp_f32_e32 v61, v57
	v_and_b32_e32 v63, 0xffff0000, v111
	v_pk_add_f32 v[52:53], v[52:53], v[72:73]
	v_pk_add_f32 v[54:55], v[54:55], v[74:75]
	v_pk_mul_f32 v[60:61], v[60:61], v[62:63]
	v_lshlrev_b32_e32 v62, 16, v113
	v_cvt_pk_bf16_f32 v57, v60, v61
	v_lshlrev_b32_e32 v60, 16, v112
	v_and_b32_e32 v61, 0xffff0000, v112
	v_pk_mul_f32 v[58:59], v[58:59], v[60:61]
	v_and_b32_e32 v63, 0xffff0000, v113
	v_cvt_pk_bf16_f32 v58, v58, v59
	v_mul_f32_e32 v59, 0xbfb8aa3b, v106
	v_exp_f32_e32 v59, v59
	v_pk_add_f32 v[44:45], v[44:45], v[72:73]
	v_pk_add_f32 v[46:47], v[46:47], v[74:75]
	v_pk_add_f32 v[36:37], v[36:37], v[72:73]
	v_add_f32_e32 v59, 1.0, v59
	v_rcp_f32_e32 v60, v59
	v_mul_f32_e32 v59, 0xbfb8aa3b, v107
	v_exp_f32_e32 v59, v59
	v_pk_add_f32 v[38:39], v[38:39], v[74:75]
	v_pk_add_f32 v[28:29], v[28:29], v[72:73]
	v_pk_add_f32 v[30:31], v[30:31], v[74:75]
	v_add_f32_e32 v59, 1.0, v59
	v_rcp_f32_e32 v61, v59
	v_pk_add_f32 v[20:21], v[20:21], v[72:73]
	v_pk_add_f32 v[22:23], v[22:23], v[74:75]
	v_pk_add_f32 v[12:13], v[12:13], v[72:73]
	v_pk_mul_f32 v[60:61], v[60:61], v[62:63]
	v_pk_add_f32 v[14:15], v[14:15], v[74:75]
	v_cvt_pk_bf16_f32 v59, v60, v61
	global_store_dwordx4 v[160:161], v[56:59], off offset:1792
	v_pk_add_f32 v[4:5], v[4:5], v[72:73]
	v_pk_add_f32 v[6:7], v[6:7], v[74:75]
	v_pk_add_f32 v[56:57], v[50:51], v[70:71]
	v_pk_add_f32 v[50:51], v[48:49], v[68:69]
	v_mul_f32_e32 v48, 0xbfb8aa3b, v52
	v_mul_f32_e32 v49, 0xbfb8aa3b, v53
	v_exp_f32_e32 v48, v48
	v_exp_f32_e32 v49, v49
	v_lshlrev_b32_e32 v52, 16, v96
	v_and_b32_e32 v53, 0xffff0000, v96
	v_add_f32_e32 v48, 1.0, v48
	v_add_f32_e32 v49, 1.0, v49
	v_rcp_f32_e32 v48, v48
	v_rcp_f32_e32 v49, v49
	v_mul_f32_e32 v50, 0xbfb8aa3b, v50
	v_mul_f32_e32 v51, 0xbfb8aa3b, v51
	v_exp_f32_e32 v50, v50
	v_pk_mul_f32 v[48:49], v[48:49], v[52:53]
	v_exp_f32_e32 v51, v51
	v_cvt_pk_bf16_f32 v48, v48, v49
	v_mul_f32_e32 v49, 0xbfb8aa3b, v54
	v_exp_f32_e32 v49, v49
	v_add_f32_e32 v50, 1.0, v50
	v_add_f32_e32 v51, 1.0, v51
	v_rcp_f32_e32 v50, v50
	v_add_f32_e32 v49, 1.0, v49
	v_rcp_f32_e32 v52, v49
	v_mul_f32_e32 v49, 0xbfb8aa3b, v55
	v_exp_f32_e32 v49, v49
	v_rcp_f32_e32 v51, v51
	v_lshlrev_b32_e32 v54, 16, v97
	v_and_b32_e32 v55, 0xffff0000, v97
	v_add_f32_e32 v49, 1.0, v49
	v_rcp_f32_e32 v53, v49
	s_nop 0
	v_pk_mul_f32 v[52:53], v[52:53], v[54:55]
	s_nop 0
	v_cvt_pk_bf16_f32 v49, v52, v53
	v_lshlrev_b32_e32 v52, 16, v98
	v_and_b32_e32 v53, 0xffff0000, v98
	v_pk_mul_f32 v[50:51], v[50:51], v[52:53]
	v_lshlrev_b32_e32 v54, 16, v99
	v_cvt_pk_bf16_f32 v50, v50, v51
	v_mul_f32_e32 v51, 0xbfb8aa3b, v56
	v_exp_f32_e32 v51, v51
	v_and_b32_e32 v55, 0xffff0000, v99
	v_add_f32_e32 v51, 1.0, v51
	v_rcp_f32_e32 v52, v51
	v_mul_f32_e32 v51, 0xbfb8aa3b, v57
	v_exp_f32_e32 v51, v51
	s_nop 0
	v_add_f32_e32 v51, 1.0, v51
	v_rcp_f32_e32 v53, v51
	s_nop 0
	v_pk_mul_f32 v[52:53], v[52:53], v[54:55]
	s_nop 0
	v_cvt_pk_bf16_f32 v51, v52, v53
	global_store_dwordx4 v[144:145], v[48:51], off offset:1792
	s_nop 1
	v_pk_add_f32 v[48:49], v[42:43], v[70:71]
	v_pk_add_f32 v[42:43], v[40:41], v[68:69]
	v_mul_f32_e32 v40, 0xbfb8aa3b, v44
	v_mul_f32_e32 v41, 0xbfb8aa3b, v45
	v_exp_f32_e32 v40, v40
	v_exp_f32_e32 v41, v41
	v_lshlrev_b32_e32 v44, 16, v92
	v_and_b32_e32 v45, 0xffff0000, v92
	v_add_f32_e32 v40, 1.0, v40
	v_add_f32_e32 v41, 1.0, v41
	v_rcp_f32_e32 v40, v40
	v_rcp_f32_e32 v41, v41
	v_mul_f32_e32 v42, 0xbfb8aa3b, v42
	v_mul_f32_e32 v43, 0xbfb8aa3b, v43
	v_exp_f32_e32 v42, v42
	v_pk_mul_f32 v[40:41], v[40:41], v[44:45]
	v_exp_f32_e32 v43, v43
	v_cvt_pk_bf16_f32 v40, v40, v41
	v_mul_f32_e32 v41, 0xbfb8aa3b, v46
	v_exp_f32_e32 v41, v41
	v_add_f32_e32 v42, 1.0, v42
	v_add_f32_e32 v43, 1.0, v43
	v_rcp_f32_e32 v42, v42
	v_add_f32_e32 v41, 1.0, v41
	v_rcp_f32_e32 v44, v41
	v_mul_f32_e32 v41, 0xbfb8aa3b, v47
	v_exp_f32_e32 v41, v41
	v_rcp_f32_e32 v43, v43
	v_lshlrev_b32_e32 v46, 16, v93
	v_and_b32_e32 v47, 0xffff0000, v93
	v_add_f32_e32 v41, 1.0, v41
	v_rcp_f32_e32 v45, v41
	s_nop 0
	v_pk_mul_f32 v[44:45], v[44:45], v[46:47]
	s_nop 0
	v_cvt_pk_bf16_f32 v41, v44, v45
	v_lshlrev_b32_e32 v44, 16, v94
	v_and_b32_e32 v45, 0xffff0000, v94
	v_pk_mul_f32 v[42:43], v[42:43], v[44:45]
	v_lshlrev_b32_e32 v46, 16, v95
	v_cvt_pk_bf16_f32 v42, v42, v43
	v_mul_f32_e32 v43, 0xbfb8aa3b, v48
	v_exp_f32_e32 v43, v43
	v_and_b32_e32 v47, 0xffff0000, v95
	v_add_f32_e32 v43, 1.0, v43
	v_rcp_f32_e32 v44, v43
	v_mul_f32_e32 v43, 0xbfb8aa3b, v49
	v_exp_f32_e32 v43, v43
	s_nop 0
	v_add_f32_e32 v43, 1.0, v43
	v_rcp_f32_e32 v45, v43
	s_nop 0
	v_pk_mul_f32 v[44:45], v[44:45], v[46:47]
	s_nop 0
	v_cvt_pk_bf16_f32 v43, v44, v45
	global_store_dwordx4 v[132:133], v[40:43], off offset:1792
	s_nop 1
	v_pk_add_f32 v[40:41], v[34:35], v[70:71]
	v_pk_add_f32 v[34:35], v[32:33], v[68:69]
	v_mul_f32_e32 v32, 0xbfb8aa3b, v36
	v_mul_f32_e32 v33, 0xbfb8aa3b, v37
	v_exp_f32_e32 v32, v32
	v_exp_f32_e32 v33, v33
	v_lshlrev_b32_e32 v36, 16, v88
	v_and_b32_e32 v37, 0xffff0000, v88
	v_add_f32_e32 v32, 1.0, v32
	v_add_f32_e32 v33, 1.0, v33
	v_rcp_f32_e32 v32, v32
	v_rcp_f32_e32 v33, v33
	v_mul_f32_e32 v34, 0xbfb8aa3b, v34
	v_mul_f32_e32 v35, 0xbfb8aa3b, v35
	v_exp_f32_e32 v34, v34
	v_pk_mul_f32 v[32:33], v[32:33], v[36:37]
	v_exp_f32_e32 v35, v35
	v_cvt_pk_bf16_f32 v32, v32, v33
	v_mul_f32_e32 v33, 0xbfb8aa3b, v38
	v_exp_f32_e32 v33, v33
	v_add_f32_e32 v34, 1.0, v34
	v_add_f32_e32 v35, 1.0, v35
	v_rcp_f32_e32 v34, v34
	v_add_f32_e32 v33, 1.0, v33
	v_rcp_f32_e32 v36, v33
	v_mul_f32_e32 v33, 0xbfb8aa3b, v39
	v_exp_f32_e32 v33, v33
	v_rcp_f32_e32 v35, v35
	v_lshlrev_b32_e32 v38, 16, v89
	v_and_b32_e32 v39, 0xffff0000, v89
	v_add_f32_e32 v33, 1.0, v33
	v_rcp_f32_e32 v37, v33
	s_nop 0
	v_pk_mul_f32 v[36:37], v[36:37], v[38:39]
	s_nop 0
	v_cvt_pk_bf16_f32 v33, v36, v37
	v_lshlrev_b32_e32 v36, 16, v90
	v_and_b32_e32 v37, 0xffff0000, v90
	v_pk_mul_f32 v[34:35], v[34:35], v[36:37]
	v_lshlrev_b32_e32 v38, 16, v91
	v_cvt_pk_bf16_f32 v34, v34, v35
	v_mul_f32_e32 v35, 0xbfb8aa3b, v40
	v_exp_f32_e32 v35, v35
	v_and_b32_e32 v39, 0xffff0000, v91
	v_add_f32_e32 v35, 1.0, v35
	v_rcp_f32_e32 v36, v35
	v_mul_f32_e32 v35, 0xbfb8aa3b, v41
	v_exp_f32_e32 v35, v35
	s_nop 0
	v_add_f32_e32 v35, 1.0, v35
	v_rcp_f32_e32 v37, v35
	s_nop 0
	v_pk_mul_f32 v[36:37], v[36:37], v[38:39]
	s_nop 0
	v_cvt_pk_bf16_f32 v35, v36, v37
	global_store_dwordx4 v[120:121], v[32:35], off offset:1792
	s_nop 1
	v_pk_add_f32 v[32:33], v[26:27], v[70:71]
	v_pk_add_f32 v[26:27], v[24:25], v[68:69]
	v_mul_f32_e32 v24, 0xbfb8aa3b, v28
	v_mul_f32_e32 v25, 0xbfb8aa3b, v29
	v_exp_f32_e32 v24, v24
	v_exp_f32_e32 v25, v25
	v_lshlrev_b32_e32 v28, 16, v84
	v_and_b32_e32 v29, 0xffff0000, v84
	v_add_f32_e32 v24, 1.0, v24
	v_add_f32_e32 v25, 1.0, v25
	v_rcp_f32_e32 v24, v24
	v_rcp_f32_e32 v25, v25
	v_mul_f32_e32 v26, 0xbfb8aa3b, v26
	v_mul_f32_e32 v27, 0xbfb8aa3b, v27
	v_exp_f32_e32 v26, v26
	v_pk_mul_f32 v[24:25], v[24:25], v[28:29]
	v_exp_f32_e32 v27, v27
	v_cvt_pk_bf16_f32 v24, v24, v25
	v_mul_f32_e32 v25, 0xbfb8aa3b, v30
	v_exp_f32_e32 v25, v25
	v_add_f32_e32 v26, 1.0, v26
	v_add_f32_e32 v27, 1.0, v27
	v_rcp_f32_e32 v26, v26
	v_add_f32_e32 v25, 1.0, v25
	v_rcp_f32_e32 v28, v25
	v_mul_f32_e32 v25, 0xbfb8aa3b, v31
	v_exp_f32_e32 v25, v25
	v_rcp_f32_e32 v27, v27
	v_lshlrev_b32_e32 v30, 16, v85
	v_and_b32_e32 v31, 0xffff0000, v85
	v_add_f32_e32 v25, 1.0, v25
	v_rcp_f32_e32 v29, v25
	s_nop 0
	v_pk_mul_f32 v[28:29], v[28:29], v[30:31]
	s_nop 0
	v_cvt_pk_bf16_f32 v25, v28, v29
	v_lshlrev_b32_e32 v28, 16, v86
	v_and_b32_e32 v29, 0xffff0000, v86
	v_pk_mul_f32 v[26:27], v[26:27], v[28:29]
	v_lshlrev_b32_e32 v30, 16, v87
	v_cvt_pk_bf16_f32 v26, v26, v27
	v_mul_f32_e32 v27, 0xbfb8aa3b, v32
	v_exp_f32_e32 v27, v27
	v_and_b32_e32 v31, 0xffff0000, v87
	v_add_f32_e32 v27, 1.0, v27
	v_rcp_f32_e32 v28, v27
	v_mul_f32_e32 v27, 0xbfb8aa3b, v33
	v_exp_f32_e32 v27, v27
	s_nop 0
	v_add_f32_e32 v27, 1.0, v27
	v_rcp_f32_e32 v29, v27
	s_nop 0
	v_pk_mul_f32 v[28:29], v[28:29], v[30:31]
	s_nop 0
	v_cvt_pk_bf16_f32 v27, v28, v29
	global_store_dwordx4 v[108:109], v[24:27], off offset:1792
	s_nop 1
	v_pk_add_f32 v[24:25], v[18:19], v[70:71]
	v_pk_add_f32 v[18:19], v[16:17], v[68:69]
	v_mul_f32_e32 v16, 0xbfb8aa3b, v20
	v_mul_f32_e32 v17, 0xbfb8aa3b, v21
	v_exp_f32_e32 v16, v16
	v_exp_f32_e32 v17, v17
	v_lshlrev_b32_e32 v20, 16, v80
	v_and_b32_e32 v21, 0xffff0000, v80
	v_add_f32_e32 v16, 1.0, v16
	v_add_f32_e32 v17, 1.0, v17
	v_rcp_f32_e32 v16, v16
	v_rcp_f32_e32 v17, v17
	v_mul_f32_e32 v18, 0xbfb8aa3b, v18
	v_mul_f32_e32 v19, 0xbfb8aa3b, v19
	v_exp_f32_e32 v18, v18
	v_pk_mul_f32 v[16:17], v[16:17], v[20:21]
	v_exp_f32_e32 v19, v19
	v_cvt_pk_bf16_f32 v16, v16, v17
	v_mul_f32_e32 v17, 0xbfb8aa3b, v22
	v_exp_f32_e32 v17, v17
	v_add_f32_e32 v18, 1.0, v18
	v_add_f32_e32 v19, 1.0, v19
	v_rcp_f32_e32 v18, v18
	v_add_f32_e32 v17, 1.0, v17
	v_rcp_f32_e32 v20, v17
	v_mul_f32_e32 v17, 0xbfb8aa3b, v23
	v_exp_f32_e32 v17, v17
	v_rcp_f32_e32 v19, v19
	v_lshlrev_b32_e32 v22, 16, v81
	v_and_b32_e32 v23, 0xffff0000, v81
	v_add_f32_e32 v17, 1.0, v17
	v_rcp_f32_e32 v21, v17
	s_nop 0
	v_pk_mul_f32 v[20:21], v[20:21], v[22:23]
	s_nop 0
	v_cvt_pk_bf16_f32 v17, v20, v21
	v_lshlrev_b32_e32 v20, 16, v82
	v_and_b32_e32 v21, 0xffff0000, v82
	v_pk_mul_f32 v[18:19], v[18:19], v[20:21]
	v_lshlrev_b32_e32 v22, 16, v83
	v_cvt_pk_bf16_f32 v18, v18, v19
	v_mul_f32_e32 v19, 0xbfb8aa3b, v24
	v_exp_f32_e32 v19, v19
	v_and_b32_e32 v23, 0xffff0000, v83
	v_add_f32_e32 v19, 1.0, v19
	v_rcp_f32_e32 v20, v19
	v_mul_f32_e32 v19, 0xbfb8aa3b, v25
	v_exp_f32_e32 v19, v19
	s_nop 0
	v_add_f32_e32 v19, 1.0, v19
	v_rcp_f32_e32 v21, v19
	s_nop 0
	v_pk_mul_f32 v[20:21], v[20:21], v[22:23]
	s_nop 0
	v_cvt_pk_bf16_f32 v19, v20, v21
	global_store_dwordx4 v[100:101], v[16:19], off offset:1792
	s_nop 1
	v_pk_add_f32 v[16:17], v[10:11], v[70:71]
	v_pk_add_f32 v[10:11], v[8:9], v[68:69]
	v_mul_f32_e32 v8, 0xbfb8aa3b, v12
	v_mul_f32_e32 v9, 0xbfb8aa3b, v13
	v_exp_f32_e32 v8, v8
	v_exp_f32_e32 v9, v9
	v_lshlrev_b32_e32 v12, 16, v76
	v_and_b32_e32 v13, 0xffff0000, v76
	v_add_f32_e32 v8, 1.0, v8
	v_add_f32_e32 v9, 1.0, v9
	v_rcp_f32_e32 v8, v8
	v_rcp_f32_e32 v9, v9
	v_mul_f32_e32 v10, 0xbfb8aa3b, v10
	v_mul_f32_e32 v11, 0xbfb8aa3b, v11
	v_exp_f32_e32 v10, v10
	v_pk_mul_f32 v[8:9], v[8:9], v[12:13]
	v_exp_f32_e32 v11, v11
	v_cvt_pk_bf16_f32 v8, v8, v9
	v_mul_f32_e32 v9, 0xbfb8aa3b, v14
	v_exp_f32_e32 v9, v9
	v_add_f32_e32 v10, 1.0, v10
	v_add_f32_e32 v11, 1.0, v11
	v_rcp_f32_e32 v10, v10
	v_add_f32_e32 v9, 1.0, v9
	v_rcp_f32_e32 v12, v9
	v_mul_f32_e32 v9, 0xbfb8aa3b, v15
	v_exp_f32_e32 v9, v9
	v_rcp_f32_e32 v11, v11
	v_lshlrev_b32_e32 v14, 16, v77
	v_and_b32_e32 v15, 0xffff0000, v77
	v_add_f32_e32 v9, 1.0, v9
	v_rcp_f32_e32 v13, v9
	s_nop 0
	v_pk_mul_f32 v[12:13], v[12:13], v[14:15]
	s_nop 0
	v_cvt_pk_bf16_f32 v9, v12, v13
	v_lshlrev_b32_e32 v12, 16, v78
	v_and_b32_e32 v13, 0xffff0000, v78
	v_pk_mul_f32 v[10:11], v[10:11], v[12:13]
	v_lshlrev_b32_e32 v14, 16, v79
	v_cvt_pk_bf16_f32 v10, v10, v11
	v_mul_f32_e32 v11, 0xbfb8aa3b, v16
	v_exp_f32_e32 v11, v11
	v_and_b32_e32 v15, 0xffff0000, v79
	v_add_f32_e32 v11, 1.0, v11
	v_rcp_f32_e32 v12, v11
	v_mul_f32_e32 v11, 0xbfb8aa3b, v17
	v_exp_f32_e32 v11, v11
	s_nop 0
	v_add_f32_e32 v11, 1.0, v11
	v_rcp_f32_e32 v13, v11
	s_nop 0
	v_pk_mul_f32 v[12:13], v[12:13], v[14:15]
	s_nop 0
	v_cvt_pk_bf16_f32 v11, v12, v13
	global_store_dwordx4 v[102:103], v[8:11], off offset:1792
	s_nop 1
	v_pk_add_f32 v[8:9], v[2:3], v[70:71]
	v_pk_add_f32 v[2:3], v[0:1], v[68:69]
	v_mul_f32_e32 v0, 0xbfb8aa3b, v4
	v_mul_f32_e32 v1, 0xbfb8aa3b, v5
	v_exp_f32_e32 v0, v0
	v_exp_f32_e32 v1, v1
	v_lshlrev_b32_e32 v4, 16, v64
	v_and_b32_e32 v5, 0xffff0000, v64
	v_add_f32_e32 v0, 1.0, v0
	v_add_f32_e32 v1, 1.0, v1
	v_rcp_f32_e32 v0, v0
	v_rcp_f32_e32 v1, v1
	v_mul_f32_e32 v2, 0xbfb8aa3b, v2
	v_mul_f32_e32 v3, 0xbfb8aa3b, v3
	v_exp_f32_e32 v2, v2
	v_pk_mul_f32 v[0:1], v[0:1], v[4:5]
	v_exp_f32_e32 v3, v3
	v_cvt_pk_bf16_f32 v0, v0, v1
	v_mul_f32_e32 v1, 0xbfb8aa3b, v6
	v_exp_f32_e32 v1, v1
	v_add_f32_e32 v2, 1.0, v2
	v_add_f32_e32 v3, 1.0, v3
	v_rcp_f32_e32 v2, v2
	v_add_f32_e32 v1, 1.0, v1
	v_rcp_f32_e32 v4, v1
	v_mul_f32_e32 v1, 0xbfb8aa3b, v7
	v_exp_f32_e32 v1, v1
	v_rcp_f32_e32 v3, v3
	v_lshlrev_b32_e32 v6, 16, v65
	v_and_b32_e32 v7, 0xffff0000, v65
	v_add_f32_e32 v1, 1.0, v1
	v_rcp_f32_e32 v5, v1
	s_nop 0
	v_pk_mul_f32 v[4:5], v[4:5], v[6:7]
	s_nop 0
	v_cvt_pk_bf16_f32 v1, v4, v5
	v_lshlrev_b32_e32 v4, 16, v66
	v_and_b32_e32 v5, 0xffff0000, v66
	v_pk_mul_f32 v[2:3], v[2:3], v[4:5]
	v_lshlrev_b32_e32 v6, 16, v67
	v_cvt_pk_bf16_f32 v2, v2, v3
	v_mul_f32_e32 v3, 0xbfb8aa3b, v8
	v_exp_f32_e32 v3, v3
	v_and_b32_e32 v7, 0xffff0000, v67
	v_add_f32_e32 v3, 1.0, v3
	v_rcp_f32_e32 v4, v3
	v_mul_f32_e32 v3, 0xbfb8aa3b, v9
	v_exp_f32_e32 v3, v3
	s_nop 0
	v_add_f32_e32 v3, 1.0, v3
	v_rcp_f32_e32 v5, v3
	s_nop 0
	v_pk_mul_f32 v[4:5], v[4:5], v[6:7]
	s_nop 0
	v_cvt_pk_bf16_f32 v3, v4, v5
	global_store_dwordx4 v[104:105], v[0:3], off offset:1792
	s_cbranch_vccz .LBB0_637

.LBB0_709:
	s_add_i32 s70, s49, 2
	s_add_u32 s36, s50, 0x80
	s_addc_u32 s37, s51, 0
	s_add_i32 s38, 0, 0x10000
	v_add_u32_e32 v146, s38, v152
	ds_read_b128 v[134:137], v146
	ds_read_b128 v[138:141], v146 offset:1024
	ds_read_b128 v[142:145], v146 offset:2048
	ds_read_b128 v[146:149], v146 offset:3072
	s_cmp_eq_u32 s66, s49
	s_cselect_b32 s53, s43, s37
	s_cselect_b32 s52, s42, s36
	s_cselect_b32 s55, s45, s35
	s_cselect_b32 s54, s44, s34
	v_lshl_add_u64 v[150:151], s[50:51], 0, v[130:131]
	s_add_i32 m0, s29, 0xc000
	ds_read_b128 v[154:157], v153
	ds_read_b128 v[158:161], v153 offset:1024
	ds_read_b128 v[162:165], v153 offset:2048
	ds_read_b128 v[172:175], v153 offset:3072
	ds_read_b128 v[176:179], v153 offset:4096
	ds_read_b128 v[180:183], v153 offset:5120
	ds_read_b128 v[184:187], v153 offset:6144
	ds_read_b128 v[188:191], v153 offset:7168
	global_load_lds_dwordx4 v[150:151], off
	v_lshl_add_u64 v[150:151], s[50:51], 0, v[132:133]
	s_add_i32 m0, s29, 0xe000
	s_nop 0
	global_load_lds_dwordx4 v[150:151], off
	s_waitcnt lgkmcnt(8)
	s_barrier
	s_waitcnt lgkmcnt(0)
	s_waitcnt lgkmcnt(0)
	v_mfma_f32_16x16x32_bf16 v[124:127], v[134:137], v[154:157], v[124:127]
	v_mfma_f32_16x16x32_bf16 v[104:107], v[142:145], v[154:157], v[104:107]
	v_mfma_f32_16x16x32_bf16 v[120:123], v[134:137], v[162:165], v[120:123]
	v_mfma_f32_16x16x32_bf16 v[92:95], v[142:145], v[162:165], v[92:95]
	v_mfma_f32_16x16x32_bf16 v[116:119], v[134:137], v[176:179], v[116:119]
	v_mfma_f32_16x16x32_bf16 v[84:87], v[142:145], v[176:179], v[84:87]
	v_mfma_f32_16x16x32_bf16 v[112:115], v[134:137], v[184:187], v[112:115]
	v_mfma_f32_16x16x32_bf16 v[80:83], v[142:145], v[184:187], v[80:83]
	v_mfma_f32_16x16x32_bf16 v[124:127], v[138:141], v[158:161], v[124:127]
	v_mfma_f32_16x16x32_bf16 v[104:107], v[146:149], v[158:161], v[104:107]
	v_mfma_f32_16x16x32_bf16 v[120:123], v[138:141], v[172:175], v[120:123]
	v_mfma_f32_16x16x32_bf16 v[92:95], v[146:149], v[172:175], v[92:95]
	v_mfma_f32_16x16x32_bf16 v[116:119], v[138:141], v[180:183], v[116:119]
	v_mfma_f32_16x16x32_bf16 v[84:87], v[146:149], v[180:183], v[84:87]
	v_mfma_f32_16x16x32_bf16 v[112:115], v[138:141], v[188:191], v[112:115]
	v_mfma_f32_16x16x32_bf16 v[80:83], v[146:149], v[188:191], v[80:83]
	s_barrier
	s_add_i32 s39, 0, 0x14000
	v_add_u32_e32 v150, s39, v152
	s_add_i32 s36, s38, s28
	ds_read_b128 v[192:195], v150
	ds_read_b128 v[196:199], v150 offset:1024
	ds_read_b128 v[200:203], v150 offset:2048
	ds_read_b128 v[204:207], v150 offset:3072
	v_lshl_add_u64 v[150:151], s[54:55], 0, v[168:169]
	s_mov_b32 m0, s36
	v_lshl_add_u64 v[166:167], s[54:55], 0, v[128:129]
	global_load_lds_dwordx4 v[150:151], off
	s_add_i32 m0, s36, 0x2000
	s_nop 0
	global_load_lds_dwordx4 v[166:167], off
	s_barrier
	s_waitcnt lgkmcnt(0)
	s_waitcnt lgkmcnt(0)
	v_mfma_f32_16x16x32_bf16 v[60:63], v[192:195], v[154:157], v[60:63]
	v_mfma_f32_16x16x32_bf16 v[48:51], v[200:203], v[154:157], v[48:51]
	v_mfma_f32_16x16x32_bf16 v[56:59], v[192:195], v[162:165], v[56:59]
	v_mfma_f32_16x16x32_bf16 v[40:43], v[200:203], v[162:165], v[40:43]
	v_mfma_f32_16x16x32_bf16 v[52:55], v[192:195], v[176:179], v[52:55]
	v_mfma_f32_16x16x32_bf16 v[36:39], v[200:203], v[176:179], v[36:39]
	v_mfma_f32_16x16x32_bf16 v[44:47], v[192:195], v[184:187], v[44:47]
	v_mfma_f32_16x16x32_bf16 v[28:31], v[200:203], v[184:187], v[28:31]
	v_mfma_f32_16x16x32_bf16 v[60:63], v[196:199], v[158:161], v[60:63]
	v_mfma_f32_16x16x32_bf16 v[48:51], v[204:207], v[158:161], v[48:51]
	v_mfma_f32_16x16x32_bf16 v[56:59], v[196:199], v[172:175], v[56:59]
	v_mfma_f32_16x16x32_bf16 v[40:43], v[204:207], v[172:175], v[40:43]
	v_mfma_f32_16x16x32_bf16 v[52:55], v[196:199], v[180:183], v[52:55]
	v_mfma_f32_16x16x32_bf16 v[36:39], v[204:207], v[180:183], v[36:39]
	v_mfma_f32_16x16x32_bf16 v[44:47], v[196:199], v[188:191], v[44:47]
	v_mfma_f32_16x16x32_bf16 v[28:31], v[204:207], v[188:191], v[28:31]
	s_mov_b32 m0, s29
	v_lshl_add_u64 v[208:209], s[52:53], 0, v[168:169]
	s_barrier
	ds_read_b128 v[154:157], v153 offset:16384
	ds_read_b128 v[158:161], v153 offset:17408
	ds_read_b128 v[162:165], v153 offset:18432
	ds_read_b128 v[172:175], v153 offset:19456
	ds_read_b128 v[176:179], v153 offset:20480
	ds_read_b128 v[180:183], v153 offset:21504
	ds_read_b128 v[184:187], v153 offset:22528
	ds_read_b128 v[188:191], v153 offset:23552
	global_load_lds_dwordx4 v[208:209], off
	v_lshl_add_u64 v[210:211], s[52:53], 0, v[128:129]
	s_mov_b32 m0, s30
	s_nop 0
	global_load_lds_dwordx4 v[210:211], off
	s_barrier
	s_waitcnt lgkmcnt(0)
	s_waitcnt lgkmcnt(0)
	v_mfma_f32_16x16x32_bf16 v[108:111], v[134:137], v[154:157], v[108:111]
	v_mfma_f32_16x16x32_bf16 v[76:79], v[142:145], v[154:157], v[76:79]
	v_mfma_f32_16x16x32_bf16 v[100:103], v[134:137], v[162:165], v[100:103]
	v_mfma_f32_16x16x32_bf16 v[72:75], v[142:145], v[162:165], v[72:75]
	v_mfma_f32_16x16x32_bf16 v[96:99], v[134:137], v[176:179], v[96:99]
	v_mfma_f32_16x16x32_bf16 v[68:71], v[142:145], v[176:179], v[68:71]
	v_mfma_f32_16x16x32_bf16 v[88:91], v[134:137], v[184:187], v[88:91]
	v_mfma_f32_16x16x32_bf16 v[64:67], v[142:145], v[184:187], v[64:67]
	v_mfma_f32_16x16x32_bf16 v[108:111], v[138:141], v[158:161], v[108:111]
	v_mfma_f32_16x16x32_bf16 v[76:79], v[146:149], v[158:161], v[76:79]
	v_mfma_f32_16x16x32_bf16 v[100:103], v[138:141], v[172:175], v[100:103]
	v_mfma_f32_16x16x32_bf16 v[72:75], v[146:149], v[172:175], v[72:75]
	v_mfma_f32_16x16x32_bf16 v[96:99], v[138:141], v[180:183], v[96:99]
	v_mfma_f32_16x16x32_bf16 v[68:71], v[146:149], v[180:183], v[68:71]
	v_mfma_f32_16x16x32_bf16 v[88:91], v[138:141], v[188:191], v[88:91]
	v_mfma_f32_16x16x32_bf16 v[64:67], v[146:149], v[188:191], v[64:67]
	s_barrier
	s_add_u32 s36, s54, s10
	s_addc_u32 s37, s55, 0
	s_add_i32 s38, s39, s28
	v_lshl_add_u64 v[212:213], s[36:37], 0, v[168:169]
	s_mov_b32 m0, s38
	v_lshl_add_u64 v[214:215], s[36:37], 0, v[128:129]
	global_load_lds_dwordx4 v[212:213], off
	s_add_i32 m0, s38, 0x2000
	s_nop 0
	global_load_lds_dwordx4 v[214:215], off
	s_waitcnt vmcnt(6)
	s_barrier
	v_mfma_f32_16x16x32_bf16 v[32:35], v[192:195], v[154:157], v[32:35]
	v_mfma_f32_16x16x32_bf16 v[12:15], v[200:203], v[154:157], v[12:15]
	v_mfma_f32_16x16x32_bf16 v[24:27], v[192:195], v[162:165], v[24:27]
	v_mfma_f32_16x16x32_bf16 v[8:11], v[200:203], v[162:165], v[8:11]
	v_mfma_f32_16x16x32_bf16 v[20:23], v[192:195], v[176:179], v[20:23]
	v_mfma_f32_16x16x32_bf16 v[4:7], v[200:203], v[176:179], v[4:7]
	v_mfma_f32_16x16x32_bf16 v[16:19], v[192:195], v[184:187], v[16:19]
	v_mfma_f32_16x16x32_bf16 v[0:3], v[200:203], v[184:187], v[0:3]
	v_mfma_f32_16x16x32_bf16 v[32:35], v[196:199], v[158:161], v[32:35]
	v_mfma_f32_16x16x32_bf16 v[12:15], v[204:207], v[158:161], v[12:15]
	v_mfma_f32_16x16x32_bf16 v[24:27], v[196:199], v[172:175], v[24:27]
	v_mfma_f32_16x16x32_bf16 v[8:11], v[204:207], v[172:175], v[8:11]
	v_mfma_f32_16x16x32_bf16 v[20:23], v[196:199], v[180:183], v[20:23]
	v_mfma_f32_16x16x32_bf16 v[4:7], v[204:207], v[180:183], v[4:7]
	v_mfma_f32_16x16x32_bf16 v[16:19], v[196:199], v[188:191], v[16:19]
	v_mfma_f32_16x16x32_bf16 v[0:3], v[204:207], v[188:191], v[0:3]
	s_add_i32 s38, 0, 0x18000
	v_add_u32_e32 v146, s38, v152
	s_barrier
	ds_read_b128 v[134:137], v146
	ds_read_b128 v[138:141], v146 offset:1024
	ds_read_b128 v[142:145], v146 offset:2048
	ds_read_b128 v[146:149], v146 offset:3072
	s_add_u32 s36, s52, s10
	s_addc_u32 s37, s53, 0
	s_mov_b32 m0, s31
	v_lshl_add_u64 v[192:193], s[36:37], 0, v[168:169]
	ds_read_b128 v[154:157], v153 offset:32768
	ds_read_b128 v[158:161], v153 offset:33792
	ds_read_b128 v[162:165], v153 offset:34816
	ds_read_b128 v[172:175], v153 offset:35840
	ds_read_b128 v[176:179], v153 offset:36864
	ds_read_b128 v[180:183], v153 offset:37888
	ds_read_b128 v[184:187], v153 offset:38912
	ds_read_b128 v[188:191], v153 offset:39936
	global_load_lds_dwordx4 v[192:193], off
	v_lshl_add_u64 v[192:193], s[36:37], 0, v[128:129]
	s_mov_b32 m0, s56
	s_nop 0
	global_load_lds_dwordx4 v[192:193], off
	s_waitcnt lgkmcnt(8)
	s_barrier
	s_waitcnt lgkmcnt(0)
	s_waitcnt lgkmcnt(0)
	v_mfma_f32_16x16x32_bf16 v[124:127], v[134:137], v[154:157], v[124:127]
	v_mfma_f32_16x16x32_bf16 v[104:107], v[142:145], v[154:157], v[104:107]
	v_mfma_f32_16x16x32_bf16 v[120:123], v[134:137], v[162:165], v[120:123]
	v_mfma_f32_16x16x32_bf16 v[92:95], v[142:145], v[162:165], v[92:95]
	v_mfma_f32_16x16x32_bf16 v[116:119], v[134:137], v[176:179], v[116:119]
	v_mfma_f32_16x16x32_bf16 v[84:87], v[142:145], v[176:179], v[84:87]
	v_mfma_f32_16x16x32_bf16 v[112:115], v[134:137], v[184:187], v[112:115]
	v_mfma_f32_16x16x32_bf16 v[80:83], v[142:145], v[184:187], v[80:83]
	v_mfma_f32_16x16x32_bf16 v[124:127], v[138:141], v[158:161], v[124:127]
	v_mfma_f32_16x16x32_bf16 v[104:107], v[146:149], v[158:161], v[104:107]
	v_mfma_f32_16x16x32_bf16 v[120:123], v[138:141], v[172:175], v[120:123]
	v_mfma_f32_16x16x32_bf16 v[92:95], v[146:149], v[172:175], v[92:95]
	v_mfma_f32_16x16x32_bf16 v[116:119], v[138:141], v[180:183], v[116:119]
	v_mfma_f32_16x16x32_bf16 v[84:87], v[146:149], v[180:183], v[84:87]
	v_mfma_f32_16x16x32_bf16 v[112:115], v[138:141], v[188:191], v[112:115]
	v_mfma_f32_16x16x32_bf16 v[80:83], v[146:149], v[188:191], v[80:83]
	s_barrier
	s_add_i32 s36, 0, 0x1c000
	s_add_i32 s37, s38, s28
	v_add_u32_e32 v204, s36, v152
	v_lshl_add_u64 v[150:151], v[150:151], 0, s[88:89]
	s_mov_b32 m0, s37
	ds_read_b128 v[192:195], v204
	ds_read_b128 v[196:199], v204 offset:1024
	ds_read_b128 v[200:203], v204 offset:2048
	ds_read_b128 v[204:207], v204 offset:3072
	global_load_lds_dwordx4 v[150:151], off
	v_lshl_add_u64 v[150:151], v[166:167], 0, s[88:89]
	s_add_i32 m0, s37, 0x2000
	s_nop 0
	global_load_lds_dwordx4 v[150:151], off
	s_barrier
	s_waitcnt lgkmcnt(0)
	s_waitcnt lgkmcnt(0)
	v_mfma_f32_16x16x32_bf16 v[60:63], v[192:195], v[154:157], v[60:63]
	v_mfma_f32_16x16x32_bf16 v[48:51], v[200:203], v[154:157], v[48:51]
	v_mfma_f32_16x16x32_bf16 v[56:59], v[192:195], v[162:165], v[56:59]
	v_mfma_f32_16x16x32_bf16 v[40:43], v[200:203], v[162:165], v[40:43]
	v_mfma_f32_16x16x32_bf16 v[52:55], v[192:195], v[176:179], v[52:55]
	v_mfma_f32_16x16x32_bf16 v[36:39], v[200:203], v[176:179], v[36:39]
	v_mfma_f32_16x16x32_bf16 v[44:47], v[192:195], v[184:187], v[44:47]
	v_mfma_f32_16x16x32_bf16 v[28:31], v[200:203], v[184:187], v[28:31]
	v_mfma_f32_16x16x32_bf16 v[60:63], v[196:199], v[158:161], v[60:63]
	v_mfma_f32_16x16x32_bf16 v[48:51], v[204:207], v[158:161], v[48:51]
	v_mfma_f32_16x16x32_bf16 v[56:59], v[196:199], v[172:175], v[56:59]
	v_mfma_f32_16x16x32_bf16 v[40:43], v[204:207], v[172:175], v[40:43]
	v_mfma_f32_16x16x32_bf16 v[52:55], v[196:199], v[180:183], v[52:55]
	v_mfma_f32_16x16x32_bf16 v[36:39], v[204:207], v[180:183], v[36:39]
	v_mfma_f32_16x16x32_bf16 v[44:47], v[196:199], v[188:191], v[44:47]
	v_mfma_f32_16x16x32_bf16 v[28:31], v[204:207], v[188:191], v[28:31]
	s_mov_b32 m0, s61
	v_lshl_add_u64 v[150:151], v[208:209], 0, s[88:89]
	s_barrier
	ds_read_b128 v[154:157], v153 offset:49152
	ds_read_b128 v[158:161], v153 offset:50176
	ds_read_b128 v[162:165], v153 offset:51200
	ds_read_b128 v[172:175], v153 offset:52224
	ds_read_b128 v[176:179], v153 offset:53248
	ds_read_b128 v[180:183], v153 offset:54272
	ds_read_b128 v[184:187], v153 offset:55296
	ds_read_b128 v[188:191], v153 offset:56320
	global_load_lds_dwordx4 v[150:151], off
	v_lshl_add_u64 v[150:151], v[210:211], 0, s[88:89]
	s_mov_b32 m0, s62
	s_nop 0
	global_load_lds_dwordx4 v[150:151], off
	s_barrier
	s_waitcnt lgkmcnt(0)
	s_waitcnt lgkmcnt(0)
	v_mfma_f32_16x16x32_bf16 v[108:111], v[134:137], v[154:157], v[108:111]
	v_mfma_f32_16x16x32_bf16 v[76:79], v[142:145], v[154:157], v[76:79]
	v_mfma_f32_16x16x32_bf16 v[100:103], v[134:137], v[162:165], v[100:103]
	v_mfma_f32_16x16x32_bf16 v[72:75], v[142:145], v[162:165], v[72:75]
	v_mfma_f32_16x16x32_bf16 v[96:99], v[134:137], v[176:179], v[96:99]
	v_mfma_f32_16x16x32_bf16 v[68:71], v[142:145], v[176:179], v[68:71]
	v_mfma_f32_16x16x32_bf16 v[88:91], v[134:137], v[184:187], v[88:91]
	v_mfma_f32_16x16x32_bf16 v[64:67], v[142:145], v[184:187], v[64:67]
	v_mfma_f32_16x16x32_bf16 v[108:111], v[138:141], v[158:161], v[108:111]
	v_mfma_f32_16x16x32_bf16 v[76:79], v[146:149], v[158:161], v[76:79]
	v_mfma_f32_16x16x32_bf16 v[100:103], v[138:141], v[172:175], v[100:103]
	v_mfma_f32_16x16x32_bf16 v[72:75], v[146:149], v[172:175], v[72:75]
	v_mfma_f32_16x16x32_bf16 v[96:99], v[138:141], v[180:183], v[96:99]
	v_mfma_f32_16x16x32_bf16 v[68:71], v[146:149], v[180:183], v[68:71]
	v_mfma_f32_16x16x32_bf16 v[88:91], v[138:141], v[188:191], v[88:91]
	v_mfma_f32_16x16x32_bf16 v[64:67], v[146:149], v[188:191], v[64:67]
	s_barrier
	s_add_i32 s36, s36, s28
	v_lshl_add_u64 v[134:135], v[212:213], 0, s[88:89]
	s_mov_b32 m0, s36
	s_nop 0
	global_load_lds_dwordx4 v[134:135], off
	v_lshl_add_u64 v[134:135], v[214:215], 0, s[88:89]
	s_add_i32 m0, s36, 0x2000
	s_nop 0
	global_load_lds_dwordx4 v[134:135], off
	s_waitcnt vmcnt(6)
	s_barrier
	v_mfma_f32_16x16x32_bf16 v[32:35], v[192:195], v[154:157], v[32:35]
	v_mfma_f32_16x16x32_bf16 v[12:15], v[200:203], v[154:157], v[12:15]
	v_mfma_f32_16x16x32_bf16 v[24:27], v[192:195], v[162:165], v[24:27]
	v_mfma_f32_16x16x32_bf16 v[8:11], v[200:203], v[162:165], v[8:11]
	v_mfma_f32_16x16x32_bf16 v[20:23], v[192:195], v[176:179], v[20:23]
	v_mfma_f32_16x16x32_bf16 v[4:7], v[200:203], v[176:179], v[4:7]
	v_mfma_f32_16x16x32_bf16 v[16:19], v[192:195], v[184:187], v[16:19]
	v_mfma_f32_16x16x32_bf16 v[0:3], v[200:203], v[184:187], v[0:3]
	v_mfma_f32_16x16x32_bf16 v[32:35], v[196:199], v[158:161], v[32:35]
	v_mfma_f32_16x16x32_bf16 v[12:15], v[204:207], v[158:161], v[12:15]
	v_mfma_f32_16x16x32_bf16 v[24:27], v[196:199], v[172:175], v[24:27]
	v_mfma_f32_16x16x32_bf16 v[8:11], v[204:207], v[172:175], v[8:11]
	v_mfma_f32_16x16x32_bf16 v[20:23], v[196:199], v[180:183], v[20:23]
	v_mfma_f32_16x16x32_bf16 v[4:7], v[204:207], v[180:183], v[4:7]
	v_mfma_f32_16x16x32_bf16 v[16:19], v[196:199], v[188:191], v[16:19]
	v_mfma_f32_16x16x32_bf16 v[0:3], v[204:207], v[188:191], v[0:3]
	s_add_u32 s50, s50, 0x100
	s_addc_u32 s51, s51, 0
	s_add_u32 s34, s34, 0x100
	s_addc_u32 s35, s35, 0
	s_cmp_ge_u32 s70, s63
	s_mov_b32 s49, s70
	s_barrier
	s_cbranch_scc0 .LBB0_709
	v_mov_b32_e32 v134, v171
	s_cmpk_gt_i32 s48, 0x7f
	s_mov_b64 s[52:53], -1
	s_cbranch_scc0 .LBB0_712
	s_add_i32 s84, s48, 0xffffff80
	s_lshl_b64 s[34:35], s[84:85], 20
	s_add_u32 s50, s57, s34
	s_addc_u32 s51, s58, s35
	s_mov_b64 s[52:53], 0

.LBB0_721:
	s_add_i32 s37, 0, 0x10000
	v_add_u32_e32 v216, s37, v6
	ds_read_b128 v[8:11], v216
	ds_read_b128 v[12:15], v216 offset:1024
	ds_read_b128 v[16:19], v216 offset:2048
	ds_read_b128 v[20:23], v216 offset:3072
	s_add_u32 s38, s50, s10
	s_addc_u32 s39, s51, 0
	v_lshl_add_u64 v[2:3], s[38:39], 0, v[168:169]
	s_add_i32 s36, s31, 0xc000
	v_lshl_add_u64 v[4:5], v[2:3], 0, s[88:89]
	s_mov_b32 m0, s36
	ds_read_b128 v[24:27], v7
	ds_read_b128 v[28:31], v7 offset:1024
	ds_read_b128 v[32:35], v7 offset:2048
	ds_read_b128 v[36:39], v7 offset:3072
	ds_read_b128 v[40:43], v7 offset:4096
	ds_read_b128 v[44:47], v7 offset:5120
	ds_read_b128 v[48:51], v7 offset:6144
	ds_read_b128 v[52:55], v7 offset:7168
	global_load_lds_dwordx4 v[4:5], off
	v_lshl_add_u64 v[4:5], s[38:39], 0, v[0:1]
	s_add_i32 s7, s31, 0xe000
	v_lshl_add_u64 v[56:57], v[4:5], 0, s[88:89]
	s_mov_b32 m0, s7
	s_nop 0
	global_load_lds_dwordx4 v[56:57], off
	s_waitcnt lgkmcnt(8)
	s_barrier
	s_waitcnt lgkmcnt(0)
	s_waitcnt lgkmcnt(0)
	v_mfma_f32_16x16x32_bf16 v[56:59], v[8:11], v[24:27], 0
	v_mfma_f32_16x16x32_bf16 v[60:63], v[16:19], v[24:27], 0
	v_mfma_f32_16x16x32_bf16 v[64:67], v[8:11], v[32:35], 0
	v_mfma_f32_16x16x32_bf16 v[68:71], v[16:19], v[32:35], 0
	v_mfma_f32_16x16x32_bf16 v[72:75], v[8:11], v[40:43], 0
	v_mfma_f32_16x16x32_bf16 v[76:79], v[16:19], v[40:43], 0
	v_mfma_f32_16x16x32_bf16 v[80:83], v[8:11], v[48:51], 0
	v_mfma_f32_16x16x32_bf16 v[84:87], v[16:19], v[48:51], 0
	v_mfma_f32_16x16x32_bf16 v[56:59], v[12:15], v[28:31], v[56:59]
	v_mfma_f32_16x16x32_bf16 v[60:63], v[20:23], v[28:31], v[60:63]
	v_mfma_f32_16x16x32_bf16 v[64:67], v[12:15], v[36:39], v[64:67]
	v_mfma_f32_16x16x32_bf16 v[68:71], v[20:23], v[36:39], v[68:71]
	v_mfma_f32_16x16x32_bf16 v[72:75], v[12:15], v[44:47], v[72:75]
	v_mfma_f32_16x16x32_bf16 v[76:79], v[20:23], v[44:47], v[76:79]
	v_mfma_f32_16x16x32_bf16 v[80:83], v[12:15], v[52:55], v[80:83]
	v_mfma_f32_16x16x32_bf16 v[84:87], v[20:23], v[52:55], v[84:87]
	s_barrier
	s_add_i32 s47, 0, 0x14000
	v_lshl_add_u64 v[204:205], s[48:49], 0, v[168:169]
	s_add_i32 s37, s37, s30
	v_add_u32_e32 v217, s47, v6
	v_lshl_add_u64 v[104:105], v[204:205], 0, s[90:91]
	s_mov_b32 m0, s37
	v_lshl_add_u64 v[206:207], s[48:49], 0, v[0:1]
	s_add_i32 s13, s37, 0x2000
	ds_read_b128 v[88:91], v217
	ds_read_b128 v[92:95], v217 offset:1024
	ds_read_b128 v[96:99], v217 offset:2048
	ds_read_b128 v[100:103], v217 offset:3072
	global_load_lds_dwordx4 v[104:105], off
	v_lshl_add_u64 v[104:105], v[206:207], 0, s[90:91]
	s_mov_b32 m0, s13
	s_nop 0
	global_load_lds_dwordx4 v[104:105], off
	s_barrier
	s_waitcnt lgkmcnt(0)
	s_waitcnt lgkmcnt(0)
	v_mfma_f32_16x16x32_bf16 v[104:107], v[88:91], v[24:27], 0
	v_mfma_f32_16x16x32_bf16 v[24:27], v[96:99], v[24:27], 0
	v_mfma_f32_16x16x32_bf16 v[104:107], v[92:95], v[28:31], v[104:107]
	v_mfma_f32_16x16x32_bf16 v[24:27], v[100:103], v[28:31], v[24:27]
	v_mfma_f32_16x16x32_bf16 v[28:31], v[88:91], v[32:35], 0
	v_mfma_f32_16x16x32_bf16 v[32:35], v[96:99], v[32:35], 0
	v_mfma_f32_16x16x32_bf16 v[28:31], v[92:95], v[36:39], v[28:31]
	v_mfma_f32_16x16x32_bf16 v[32:35], v[100:103], v[36:39], v[32:35]
	v_mfma_f32_16x16x32_bf16 v[36:39], v[88:91], v[40:43], 0
	v_mfma_f32_16x16x32_bf16 v[40:43], v[96:99], v[40:43], 0
	v_mfma_f32_16x16x32_bf16 v[36:39], v[92:95], v[44:47], v[36:39]
	v_mfma_f32_16x16x32_bf16 v[40:43], v[100:103], v[44:47], v[40:43]
	v_mfma_f32_16x16x32_bf16 v[44:47], v[88:91], v[48:51], 0
	v_mfma_f32_16x16x32_bf16 v[48:51], v[96:99], v[48:51], 0
	v_mfma_f32_16x16x32_bf16 v[44:47], v[92:95], v[52:55], v[44:47]
	v_mfma_f32_16x16x32_bf16 v[48:51], v[100:103], v[52:55], v[48:51]
	v_lshl_add_u64 v[208:209], s[50:51], 0, v[168:169]
	s_mov_b32 m0, s31
	v_lshl_add_u64 v[136:137], v[208:209], 0, s[90:91]
	v_lshl_add_u64 v[210:211], s[50:51], 0, v[0:1]
	s_barrier
	ds_read_b128 v[52:55], v7 offset:16384
	ds_read_b128 v[108:111], v7 offset:17408
	ds_read_b128 v[112:115], v7 offset:18432
	ds_read_b128 v[116:119], v7 offset:19456
	ds_read_b128 v[120:123], v7 offset:20480
	ds_read_b128 v[124:127], v7 offset:21504
	ds_read_b128 v[128:131], v7 offset:22528
	ds_read_b128 v[132:135], v7 offset:23552
	global_load_lds_dwordx4 v[136:137], off
	v_lshl_add_u64 v[136:137], v[210:211], 0, s[90:91]
	s_mov_b32 m0, s34
	s_nop 0
	global_load_lds_dwordx4 v[136:137], off
	s_barrier
	s_waitcnt lgkmcnt(0)
	s_waitcnt lgkmcnt(0)
	v_mfma_f32_16x16x32_bf16 v[136:139], v[8:11], v[52:55], 0
	v_mfma_f32_16x16x32_bf16 v[144:147], v[8:11], v[112:115], 0
	v_mfma_f32_16x16x32_bf16 v[152:155], v[8:11], v[120:123], 0
	v_mfma_f32_16x16x32_bf16 v[8:11], v[8:11], v[128:131], 0
	v_mfma_f32_16x16x32_bf16 v[136:139], v[12:15], v[108:111], v[136:139]
	v_mfma_f32_16x16x32_bf16 v[140:143], v[16:19], v[52:55], 0
	v_mfma_f32_16x16x32_bf16 v[144:147], v[12:15], v[116:119], v[144:147]
	v_mfma_f32_16x16x32_bf16 v[148:151], v[16:19], v[112:115], 0
	v_mfma_f32_16x16x32_bf16 v[152:155], v[12:15], v[124:127], v[152:155]
	v_mfma_f32_16x16x32_bf16 v[156:159], v[16:19], v[120:123], 0
	v_mfma_f32_16x16x32_bf16 v[8:11], v[12:15], v[132:135], v[8:11]
	v_mfma_f32_16x16x32_bf16 v[12:15], v[16:19], v[128:131], 0
	v_mfma_f32_16x16x32_bf16 v[140:143], v[20:23], v[108:111], v[140:143]
	v_mfma_f32_16x16x32_bf16 v[148:151], v[20:23], v[116:119], v[148:151]
	v_mfma_f32_16x16x32_bf16 v[156:159], v[20:23], v[124:127], v[156:159]
	v_mfma_f32_16x16x32_bf16 v[12:15], v[20:23], v[132:135], v[12:15]
	s_barrier
	s_add_u32 s38, s48, s10
	s_addc_u32 s39, s49, 0
	v_lshl_add_u64 v[212:213], s[38:39], 0, v[168:169]
	s_add_i32 s51, s47, s30
	v_lshl_add_u64 v[16:17], v[212:213], 0, s[90:91]
	s_mov_b32 m0, s51
	v_lshl_add_u64 v[214:215], s[38:39], 0, v[0:1]
	s_add_i32 s47, s51, 0x2000
	global_load_lds_dwordx4 v[16:17], off
	v_lshl_add_u64 v[16:17], v[214:215], 0, s[90:91]
	s_mov_b32 m0, s47
	s_nop 0
	global_load_lds_dwordx4 v[16:17], off
	s_waitcnt vmcnt(6)
	s_barrier
	v_mfma_f32_16x16x32_bf16 v[16:19], v[88:91], v[52:55], 0
	v_mfma_f32_16x16x32_bf16 v[20:23], v[96:99], v[52:55], 0
	v_mfma_f32_16x16x32_bf16 v[16:19], v[92:95], v[108:111], v[16:19]
	v_mfma_f32_16x16x32_bf16 v[20:23], v[100:103], v[108:111], v[20:23]
	v_mfma_f32_16x16x32_bf16 v[52:55], v[88:91], v[112:115], 0
	v_mfma_f32_16x16x32_bf16 v[108:111], v[96:99], v[112:115], 0
	v_mfma_f32_16x16x32_bf16 v[112:115], v[88:91], v[120:123], 0
	v_mfma_f32_16x16x32_bf16 v[88:91], v[88:91], v[128:131], 0
	v_mfma_f32_16x16x32_bf16 v[52:55], v[92:95], v[116:119], v[52:55]
	v_mfma_f32_16x16x32_bf16 v[108:111], v[100:103], v[116:119], v[108:111]
	v_mfma_f32_16x16x32_bf16 v[112:115], v[92:95], v[124:127], v[112:115]
	v_mfma_f32_16x16x32_bf16 v[116:119], v[96:99], v[120:123], 0
	v_mfma_f32_16x16x32_bf16 v[88:91], v[92:95], v[132:135], v[88:91]
	v_mfma_f32_16x16x32_bf16 v[92:95], v[96:99], v[128:131], 0
	v_mfma_f32_16x16x32_bf16 v[116:119], v[100:103], v[124:127], v[116:119]
	v_mfma_f32_16x16x32_bf16 v[92:95], v[100:103], v[132:135], v[92:95]
	s_add_i32 s63, 0, 0x18000
	v_add_u32_e32 v218, s63, v6
	s_barrier
	ds_read_b128 v[96:99], v218
	ds_read_b128 v[100:103], v218 offset:1024
	ds_read_b128 v[120:123], v218 offset:2048
	ds_read_b128 v[124:127], v218 offset:3072
	s_mov_b32 m0, s35
	v_lshl_add_u64 v[188:189], v[2:3], 0, s[90:91]
	ds_read_b128 v[128:131], v7 offset:32768
	ds_read_b128 v[132:135], v7 offset:33792
	ds_read_b128 v[160:163], v7 offset:34816
	ds_read_b128 v[164:167], v7 offset:35840
	ds_read_b128 v[172:175], v7 offset:36864
	ds_read_b128 v[176:179], v7 offset:37888
	ds_read_b128 v[180:183], v7 offset:38912
	ds_read_b128 v[184:187], v7 offset:39936
	global_load_lds_dwordx4 v[188:189], off
	v_lshl_add_u64 v[188:189], v[4:5], 0, s[90:91]
	s_mov_b32 m0, s52
	s_nop 0
	global_load_lds_dwordx4 v[188:189], off
	s_waitcnt lgkmcnt(8)
	s_barrier
	s_waitcnt lgkmcnt(0)
	s_waitcnt lgkmcnt(0)
	v_mfma_f32_16x16x32_bf16 v[56:59], v[96:99], v[128:131], v[56:59]
	v_mfma_f32_16x16x32_bf16 v[60:63], v[120:123], v[128:131], v[60:63]
	v_mfma_f32_16x16x32_bf16 v[64:67], v[96:99], v[160:163], v[64:67]
	v_mfma_f32_16x16x32_bf16 v[68:71], v[120:123], v[160:163], v[68:71]
	v_mfma_f32_16x16x32_bf16 v[72:75], v[96:99], v[172:175], v[72:75]
	v_mfma_f32_16x16x32_bf16 v[76:79], v[120:123], v[172:175], v[76:79]
	v_mfma_f32_16x16x32_bf16 v[80:83], v[96:99], v[180:183], v[80:83]
	v_mfma_f32_16x16x32_bf16 v[84:87], v[120:123], v[180:183], v[84:87]
	v_mfma_f32_16x16x32_bf16 v[56:59], v[100:103], v[132:135], v[56:59]
	v_mfma_f32_16x16x32_bf16 v[60:63], v[124:127], v[132:135], v[60:63]
	v_mfma_f32_16x16x32_bf16 v[64:67], v[100:103], v[164:167], v[64:67]
	v_mfma_f32_16x16x32_bf16 v[68:71], v[124:127], v[164:167], v[68:71]
	v_mfma_f32_16x16x32_bf16 v[72:75], v[100:103], v[176:179], v[72:75]
	v_mfma_f32_16x16x32_bf16 v[76:79], v[124:127], v[176:179], v[76:79]
	v_mfma_f32_16x16x32_bf16 v[80:83], v[100:103], v[184:187], v[80:83]
	v_mfma_f32_16x16x32_bf16 v[84:87], v[124:127], v[184:187], v[84:87]
	s_barrier
	s_add_i32 s50, 0, 0x1c000
	s_add_i32 s63, s63, s30
	v_add_u32_e32 v219, s50, v6
	v_lshl_add_u64 v[204:205], v[204:205], 0, s[94:95]
	s_mov_b32 m0, s63
	s_add_i32 s48, s63, 0x2000
	ds_read_b128 v[188:191], v219
	ds_read_b128 v[192:195], v219 offset:1024
	ds_read_b128 v[196:199], v219 offset:2048
	ds_read_b128 v[200:203], v219 offset:3072
	global_load_lds_dwordx4 v[204:205], off
	v_lshl_add_u64 v[204:205], v[206:207], 0, s[94:95]
	s_mov_b32 m0, s48
	s_nop 0
	global_load_lds_dwordx4 v[204:205], off
	s_barrier
	s_waitcnt lgkmcnt(0)
	s_waitcnt lgkmcnt(0)
	v_mfma_f32_16x16x32_bf16 v[104:107], v[188:191], v[128:131], v[104:107]
	v_mfma_f32_16x16x32_bf16 v[24:27], v[196:199], v[128:131], v[24:27]
	v_mfma_f32_16x16x32_bf16 v[28:31], v[188:191], v[160:163], v[28:31]
	v_mfma_f32_16x16x32_bf16 v[32:35], v[196:199], v[160:163], v[32:35]
	v_mfma_f32_16x16x32_bf16 v[36:39], v[188:191], v[172:175], v[36:39]
	v_mfma_f32_16x16x32_bf16 v[40:43], v[196:199], v[172:175], v[40:43]
	v_mfma_f32_16x16x32_bf16 v[44:47], v[188:191], v[180:183], v[44:47]
	v_mfma_f32_16x16x32_bf16 v[48:51], v[196:199], v[180:183], v[48:51]
	v_mfma_f32_16x16x32_bf16 v[104:107], v[192:195], v[132:135], v[104:107]
	v_mfma_f32_16x16x32_bf16 v[24:27], v[200:203], v[132:135], v[24:27]
	v_mfma_f32_16x16x32_bf16 v[28:31], v[192:195], v[164:167], v[28:31]
	v_mfma_f32_16x16x32_bf16 v[32:35], v[200:203], v[164:167], v[32:35]
	v_mfma_f32_16x16x32_bf16 v[36:39], v[192:195], v[176:179], v[36:39]
	v_mfma_f32_16x16x32_bf16 v[40:43], v[200:203], v[176:179], v[40:43]
	v_mfma_f32_16x16x32_bf16 v[44:47], v[192:195], v[184:187], v[44:47]
	v_mfma_f32_16x16x32_bf16 v[48:51], v[200:203], v[184:187], v[48:51]
	s_mov_b32 m0, s58
	v_lshl_add_u64 v[204:205], v[208:209], 0, s[94:95]
	s_barrier
	ds_read_b128 v[128:131], v7 offset:49152
	ds_read_b128 v[132:135], v7 offset:50176
	ds_read_b128 v[160:163], v7 offset:51200
	ds_read_b128 v[164:167], v7 offset:52224
	ds_read_b128 v[172:175], v7 offset:53248
	ds_read_b128 v[176:179], v7 offset:54272
	ds_read_b128 v[180:183], v7 offset:55296
	ds_read_b128 v[184:187], v7 offset:56320
	global_load_lds_dwordx4 v[204:205], off
	v_lshl_add_u64 v[204:205], v[210:211], 0, s[94:95]
	s_mov_b32 m0, s59
	s_nop 0
	global_load_lds_dwordx4 v[204:205], off
	s_barrier
	s_waitcnt lgkmcnt(0)
	s_waitcnt lgkmcnt(0)
	v_mfma_f32_16x16x32_bf16 v[136:139], v[96:99], v[128:131], v[136:139]
	v_mfma_f32_16x16x32_bf16 v[140:143], v[120:123], v[128:131], v[140:143]
	v_mfma_f32_16x16x32_bf16 v[144:147], v[96:99], v[160:163], v[144:147]
	v_mfma_f32_16x16x32_bf16 v[148:151], v[120:123], v[160:163], v[148:151]
	v_mfma_f32_16x16x32_bf16 v[152:155], v[96:99], v[172:175], v[152:155]
	v_mfma_f32_16x16x32_bf16 v[156:159], v[120:123], v[172:175], v[156:159]
	v_mfma_f32_16x16x32_bf16 v[8:11], v[96:99], v[180:183], v[8:11]
	v_mfma_f32_16x16x32_bf16 v[12:15], v[120:123], v[180:183], v[12:15]
	v_mfma_f32_16x16x32_bf16 v[136:139], v[100:103], v[132:135], v[136:139]
	v_mfma_f32_16x16x32_bf16 v[140:143], v[124:127], v[132:135], v[140:143]
	v_mfma_f32_16x16x32_bf16 v[144:147], v[100:103], v[164:167], v[144:147]
	v_mfma_f32_16x16x32_bf16 v[148:151], v[124:127], v[164:167], v[148:151]
	v_mfma_f32_16x16x32_bf16 v[152:155], v[100:103], v[176:179], v[152:155]
	v_mfma_f32_16x16x32_bf16 v[156:159], v[124:127], v[176:179], v[156:159]
	v_mfma_f32_16x16x32_bf16 v[8:11], v[100:103], v[184:187], v[8:11]
	v_mfma_f32_16x16x32_bf16 v[12:15], v[124:127], v[184:187], v[12:15]
	s_barrier
	s_add_i32 s50, s50, s30
	v_lshl_add_u64 v[96:97], v[212:213], 0, s[94:95]
	s_mov_b32 m0, s50
	s_add_i32 s49, s50, 0x2000
	global_load_lds_dwordx4 v[96:97], off
	v_lshl_add_u64 v[96:97], v[214:215], 0, s[94:95]
	s_mov_b32 m0, s49
	s_nop 0
	global_load_lds_dwordx4 v[96:97], off
	s_waitcnt vmcnt(6)
	s_barrier
	v_mfma_f32_16x16x32_bf16 v[16:19], v[188:191], v[128:131], v[16:19]
	v_mfma_f32_16x16x32_bf16 v[20:23], v[196:199], v[128:131], v[20:23]
	v_mfma_f32_16x16x32_bf16 v[52:55], v[188:191], v[160:163], v[52:55]
	v_mfma_f32_16x16x32_bf16 v[96:99], v[196:199], v[160:163], v[108:111]
	v_mfma_f32_16x16x32_bf16 v[100:103], v[188:191], v[172:175], v[112:115]
	v_mfma_f32_16x16x32_bf16 v[108:111], v[196:199], v[172:175], v[116:119]
	v_mfma_f32_16x16x32_bf16 v[88:91], v[188:191], v[180:183], v[88:91]
	v_mfma_f32_16x16x32_bf16 v[92:95], v[196:199], v[180:183], v[92:95]
	v_mfma_f32_16x16x32_bf16 v[16:19], v[192:195], v[132:135], v[16:19]
	v_mfma_f32_16x16x32_bf16 v[20:23], v[200:203], v[132:135], v[20:23]
	v_mfma_f32_16x16x32_bf16 v[52:55], v[192:195], v[164:167], v[52:55]
	v_mfma_f32_16x16x32_bf16 v[96:99], v[200:203], v[164:167], v[96:99]
	v_mfma_f32_16x16x32_bf16 v[100:103], v[192:195], v[176:179], v[100:103]
	v_mfma_f32_16x16x32_bf16 v[108:111], v[200:203], v[176:179], v[108:111]
	v_mfma_f32_16x16x32_bf16 v[88:91], v[192:195], v[184:187], v[88:91]
	v_mfma_f32_16x16x32_bf16 v[92:95], v[200:203], v[184:187], v[92:95]
	s_barrier
	ds_read_b128 v[112:115], v216
	ds_read_b128 v[116:119], v216 offset:1024
	ds_read_b128 v[120:123], v216 offset:2048
	ds_read_b128 v[124:127], v216 offset:3072
	s_mov_b32 m0, s36
	v_lshl_add_u64 v[2:3], v[2:3], 0, s[94:95]
	ds_read_b128 v[128:131], v7
	ds_read_b128 v[132:135], v7 offset:1024
	ds_read_b128 v[160:163], v7 offset:2048
	ds_read_b128 v[164:167], v7 offset:3072
	ds_read_b128 v[172:175], v7 offset:4096
	ds_read_b128 v[176:179], v7 offset:5120
	ds_read_b128 v[180:183], v7 offset:6144
	ds_read_b128 v[184:187], v7 offset:7168
	global_load_lds_dwordx4 v[2:3], off
	v_lshl_add_u64 v[2:3], v[4:5], 0, s[94:95]
	s_mov_b32 m0, s7
	s_nop 0
	global_load_lds_dwordx4 v[2:3], off
	s_waitcnt lgkmcnt(8)
	s_barrier
	s_waitcnt lgkmcnt(0)
	s_waitcnt lgkmcnt(0)
	v_mfma_f32_16x16x32_bf16 v[2:5], v[112:115], v[128:131], v[56:59]
	v_mfma_f32_16x16x32_bf16 v[56:59], v[120:123], v[128:131], v[60:63]
	v_mfma_f32_16x16x32_bf16 v[60:63], v[112:115], v[160:163], v[64:67]
	v_mfma_f32_16x16x32_bf16 v[64:67], v[120:123], v[160:163], v[68:71]
	v_mfma_f32_16x16x32_bf16 v[68:71], v[112:115], v[172:175], v[72:75]
	v_mfma_f32_16x16x32_bf16 v[72:75], v[120:123], v[172:175], v[76:79]
	v_mfma_f32_16x16x32_bf16 v[76:79], v[112:115], v[180:183], v[80:83]
	v_mfma_f32_16x16x32_bf16 v[80:83], v[120:123], v[180:183], v[84:87]
	v_mfma_f32_16x16x32_bf16 v[2:5], v[116:119], v[132:135], v[2:5]
	v_mfma_f32_16x16x32_bf16 v[56:59], v[124:127], v[132:135], v[56:59]
	v_mfma_f32_16x16x32_bf16 v[60:63], v[116:119], v[164:167], v[60:63]
	v_mfma_f32_16x16x32_bf16 v[64:67], v[124:127], v[164:167], v[64:67]
	v_mfma_f32_16x16x32_bf16 v[68:71], v[116:119], v[176:179], v[68:71]
	v_mfma_f32_16x16x32_bf16 v[72:75], v[124:127], v[176:179], v[72:75]
	v_mfma_f32_16x16x32_bf16 v[76:79], v[116:119], v[184:187], v[76:79]
	v_mfma_f32_16x16x32_bf16 v[80:83], v[124:127], v[184:187], v[80:83]
	s_barrier
	s_mov_b32 m0, s37
	v_lshl_add_u64 v[200:201], s[44:45], 0, v[168:169]
	ds_read_b128 v[84:87], v217
	ds_read_b128 v[188:191], v217 offset:1024
	ds_read_b128 v[192:195], v217 offset:2048
	ds_read_b128 v[196:199], v217 offset:3072
	global_load_lds_dwordx4 v[200:201], off
	v_lshl_add_u64 v[202:203], s[44:45], 0, v[0:1]
	s_mov_b32 m0, s13
	s_nop 0
	global_load_lds_dwordx4 v[202:203], off
	s_barrier
	s_waitcnt lgkmcnt(0)
	s_waitcnt lgkmcnt(0)
	v_mfma_f32_16x16x32_bf16 v[104:107], v[84:87], v[128:131], v[104:107]
	v_mfma_f32_16x16x32_bf16 v[24:27], v[192:195], v[128:131], v[24:27]
	v_mfma_f32_16x16x32_bf16 v[28:31], v[84:87], v[160:163], v[28:31]
	v_mfma_f32_16x16x32_bf16 v[32:35], v[192:195], v[160:163], v[32:35]
	v_mfma_f32_16x16x32_bf16 v[36:39], v[84:87], v[172:175], v[36:39]
	v_mfma_f32_16x16x32_bf16 v[40:43], v[192:195], v[172:175], v[40:43]
	v_mfma_f32_16x16x32_bf16 v[44:47], v[84:87], v[180:183], v[44:47]
	v_mfma_f32_16x16x32_bf16 v[48:51], v[192:195], v[180:183], v[48:51]
	v_mfma_f32_16x16x32_bf16 v[104:107], v[188:191], v[132:135], v[104:107]
	v_mfma_f32_16x16x32_bf16 v[24:27], v[196:199], v[132:135], v[24:27]
	v_mfma_f32_16x16x32_bf16 v[28:31], v[188:191], v[164:167], v[28:31]
	v_mfma_f32_16x16x32_bf16 v[32:35], v[196:199], v[164:167], v[32:35]
	v_mfma_f32_16x16x32_bf16 v[36:39], v[188:191], v[176:179], v[36:39]
	v_mfma_f32_16x16x32_bf16 v[40:43], v[196:199], v[176:179], v[40:43]
	v_mfma_f32_16x16x32_bf16 v[44:47], v[188:191], v[184:187], v[44:47]
	v_mfma_f32_16x16x32_bf16 v[48:51], v[196:199], v[184:187], v[48:51]
	s_mov_b32 m0, s31
	v_lshl_add_u64 v[204:205], s[42:43], 0, v[168:169]
	s_barrier
	ds_read_b128 v[128:131], v7 offset:16384
	ds_read_b128 v[132:135], v7 offset:17408
	ds_read_b128 v[160:163], v7 offset:18432
	ds_read_b128 v[164:167], v7 offset:19456
	ds_read_b128 v[172:175], v7 offset:20480
	ds_read_b128 v[176:179], v7 offset:21504
	ds_read_b128 v[180:183], v7 offset:22528
	ds_read_b128 v[184:187], v7 offset:23552
	global_load_lds_dwordx4 v[204:205], off
	v_lshl_add_u64 v[206:207], s[42:43], 0, v[0:1]
	s_mov_b32 m0, s34
	s_nop 0
	global_load_lds_dwordx4 v[206:207], off
	s_barrier
	s_waitcnt lgkmcnt(0)
	s_waitcnt lgkmcnt(0)
	v_mfma_f32_16x16x32_bf16 v[136:139], v[112:115], v[128:131], v[136:139]
	v_mfma_f32_16x16x32_bf16 v[140:143], v[120:123], v[128:131], v[140:143]
	v_mfma_f32_16x16x32_bf16 v[144:147], v[112:115], v[160:163], v[144:147]
	v_mfma_f32_16x16x32_bf16 v[148:151], v[120:123], v[160:163], v[148:151]
	v_mfma_f32_16x16x32_bf16 v[152:155], v[112:115], v[172:175], v[152:155]
	v_mfma_f32_16x16x32_bf16 v[156:159], v[120:123], v[172:175], v[156:159]
	v_mfma_f32_16x16x32_bf16 v[8:11], v[112:115], v[180:183], v[8:11]
	v_mfma_f32_16x16x32_bf16 v[12:15], v[120:123], v[180:183], v[12:15]
	v_mfma_f32_16x16x32_bf16 v[136:139], v[116:119], v[132:135], v[136:139]
	v_mfma_f32_16x16x32_bf16 v[140:143], v[124:127], v[132:135], v[140:143]
	v_mfma_f32_16x16x32_bf16 v[144:147], v[116:119], v[164:167], v[144:147]
	v_mfma_f32_16x16x32_bf16 v[148:151], v[124:127], v[164:167], v[148:151]
	v_mfma_f32_16x16x32_bf16 v[152:155], v[116:119], v[176:179], v[152:155]
	v_mfma_f32_16x16x32_bf16 v[156:159], v[124:127], v[176:179], v[156:159]
	v_mfma_f32_16x16x32_bf16 v[8:11], v[116:119], v[184:187], v[8:11]
	v_mfma_f32_16x16x32_bf16 v[12:15], v[124:127], v[184:187], v[12:15]
	s_barrier
	s_add_u32 s36, s44, s10
	s_addc_u32 s37, s45, 0
	s_mov_b32 m0, s51
	v_lshl_add_u64 v[208:209], s[36:37], 0, v[168:169]
	global_load_lds_dwordx4 v[208:209], off
	v_lshl_add_u64 v[210:211], s[36:37], 0, v[0:1]
	s_mov_b32 m0, s47
	s_nop 0
	global_load_lds_dwordx4 v[210:211], off
	s_waitcnt vmcnt(6)
	s_barrier
	v_mfma_f32_16x16x32_bf16 v[16:19], v[84:87], v[128:131], v[16:19]
	v_mfma_f32_16x16x32_bf16 v[20:23], v[192:195], v[128:131], v[20:23]
	v_mfma_f32_16x16x32_bf16 v[52:55], v[84:87], v[160:163], v[52:55]
	v_mfma_f32_16x16x32_bf16 v[96:99], v[192:195], v[160:163], v[96:99]
	v_mfma_f32_16x16x32_bf16 v[100:103], v[84:87], v[172:175], v[100:103]
	v_mfma_f32_16x16x32_bf16 v[108:111], v[192:195], v[172:175], v[108:111]
	v_mfma_f32_16x16x32_bf16 v[84:87], v[84:87], v[180:183], v[88:91]
	v_mfma_f32_16x16x32_bf16 v[88:91], v[192:195], v[180:183], v[92:95]
	v_mfma_f32_16x16x32_bf16 v[16:19], v[188:191], v[132:135], v[16:19]
	v_mfma_f32_16x16x32_bf16 v[20:23], v[196:199], v[132:135], v[20:23]
	v_mfma_f32_16x16x32_bf16 v[52:55], v[188:191], v[164:167], v[52:55]
	v_mfma_f32_16x16x32_bf16 v[96:99], v[196:199], v[164:167], v[96:99]
	v_mfma_f32_16x16x32_bf16 v[100:103], v[188:191], v[176:179], v[100:103]
	v_mfma_f32_16x16x32_bf16 v[108:111], v[196:199], v[176:179], v[108:111]
	v_mfma_f32_16x16x32_bf16 v[84:87], v[188:191], v[184:187], v[84:87]
	v_mfma_f32_16x16x32_bf16 v[88:91], v[196:199], v[184:187], v[88:91]
	s_barrier
	ds_read_b128 v[92:95], v218
	ds_read_b128 v[112:115], v218 offset:1024
	ds_read_b128 v[116:119], v218 offset:2048
	ds_read_b128 v[120:123], v218 offset:3072
	s_add_u32 s36, s42, s10
	s_addc_u32 s37, s43, 0
	s_mov_b32 m0, s35
	v_lshl_add_u64 v[184:185], s[36:37], 0, v[168:169]
	ds_read_b128 v[124:127], v7 offset:32768
	ds_read_b128 v[128:131], v7 offset:33792
	ds_read_b128 v[132:135], v7 offset:34816
	ds_read_b128 v[160:163], v7 offset:35840
	ds_read_b128 v[164:167], v7 offset:36864
	ds_read_b128 v[172:175], v7 offset:37888
	ds_read_b128 v[176:179], v7 offset:38912
	ds_read_b128 v[180:183], v7 offset:39936
	global_load_lds_dwordx4 v[184:185], off
	v_lshl_add_u64 v[184:185], s[36:37], 0, v[0:1]
	s_mov_b32 m0, s52
	s_nop 0
	global_load_lds_dwordx4 v[184:185], off
	s_waitcnt lgkmcnt(8)
	s_barrier
	s_waitcnt lgkmcnt(0)
	s_waitcnt lgkmcnt(0)
	v_mfma_f32_16x16x32_bf16 v[2:5], v[92:95], v[124:127], v[2:5]
	v_mfma_f32_16x16x32_bf16 v[56:59], v[116:119], v[124:127], v[56:59]
	v_mfma_f32_16x16x32_bf16 v[60:63], v[92:95], v[132:135], v[60:63]
	v_mfma_f32_16x16x32_bf16 v[64:67], v[116:119], v[132:135], v[64:67]
	v_mfma_f32_16x16x32_bf16 v[68:71], v[92:95], v[164:167], v[68:71]
	v_mfma_f32_16x16x32_bf16 v[72:75], v[116:119], v[164:167], v[72:75]
	v_mfma_f32_16x16x32_bf16 v[76:79], v[92:95], v[176:179], v[76:79]
	v_mfma_f32_16x16x32_bf16 v[80:83], v[116:119], v[176:179], v[80:83]
	v_mfma_f32_16x16x32_bf16 v[2:5], v[112:115], v[128:131], v[2:5]
	v_mfma_f32_16x16x32_bf16 v[56:59], v[120:123], v[128:131], v[56:59]
	v_mfma_f32_16x16x32_bf16 v[60:63], v[112:115], v[160:163], v[60:63]
	v_mfma_f32_16x16x32_bf16 v[64:67], v[120:123], v[160:163], v[64:67]
	v_mfma_f32_16x16x32_bf16 v[68:71], v[112:115], v[172:175], v[68:71]
	v_mfma_f32_16x16x32_bf16 v[72:75], v[120:123], v[172:175], v[72:75]
	v_mfma_f32_16x16x32_bf16 v[76:79], v[112:115], v[180:183], v[76:79]
	v_mfma_f32_16x16x32_bf16 v[80:83], v[120:123], v[180:183], v[80:83]
	s_barrier
	s_mov_b32 m0, s63
	v_lshl_add_u64 v[200:201], v[200:201], 0, s[88:89]
	ds_read_b128 v[184:187], v219
	ds_read_b128 v[188:191], v219 offset:1024
	ds_read_b128 v[192:195], v219 offset:2048
	ds_read_b128 v[196:199], v219 offset:3072
	global_load_lds_dwordx4 v[200:201], off
	v_lshl_add_u64 v[200:201], v[202:203], 0, s[88:89]
	s_mov_b32 m0, s48
	s_nop 0
	global_load_lds_dwordx4 v[200:201], off
	s_barrier
	s_waitcnt lgkmcnt(0)
	s_waitcnt lgkmcnt(0)
	v_mfma_f32_16x16x32_bf16 v[104:107], v[184:187], v[124:127], v[104:107]
	v_mfma_f32_16x16x32_bf16 v[24:27], v[192:195], v[124:127], v[24:27]
	v_mfma_f32_16x16x32_bf16 v[28:31], v[184:187], v[132:135], v[28:31]
	v_mfma_f32_16x16x32_bf16 v[32:35], v[192:195], v[132:135], v[32:35]
	v_mfma_f32_16x16x32_bf16 v[36:39], v[184:187], v[164:167], v[36:39]
	v_mfma_f32_16x16x32_bf16 v[40:43], v[192:195], v[164:167], v[40:43]
	v_mfma_f32_16x16x32_bf16 v[44:47], v[184:187], v[176:179], v[44:47]
	v_mfma_f32_16x16x32_bf16 v[48:51], v[192:195], v[176:179], v[48:51]
	v_mfma_f32_16x16x32_bf16 v[104:107], v[188:191], v[128:131], v[104:107]
	v_mfma_f32_16x16x32_bf16 v[24:27], v[196:199], v[128:131], v[24:27]
	v_mfma_f32_16x16x32_bf16 v[28:31], v[188:191], v[160:163], v[28:31]
	v_mfma_f32_16x16x32_bf16 v[32:35], v[196:199], v[160:163], v[32:35]
	v_mfma_f32_16x16x32_bf16 v[36:39], v[188:191], v[172:175], v[36:39]
	v_mfma_f32_16x16x32_bf16 v[40:43], v[196:199], v[172:175], v[40:43]
	v_mfma_f32_16x16x32_bf16 v[44:47], v[188:191], v[180:183], v[44:47]
	v_mfma_f32_16x16x32_bf16 v[48:51], v[196:199], v[180:183], v[48:51]
	s_mov_b32 m0, s58
	v_lshl_add_u64 v[200:201], v[204:205], 0, s[88:89]
	s_barrier
	ds_read_b128 v[124:127], v7 offset:49152
	ds_read_b128 v[128:131], v7 offset:50176
	ds_read_b128 v[132:135], v7 offset:51200
	ds_read_b128 v[160:163], v7 offset:52224
	ds_read_b128 v[164:167], v7 offset:53248
	ds_read_b128 v[172:175], v7 offset:54272
	ds_read_b128 v[176:179], v7 offset:55296
	ds_read_b128 v[180:183], v7 offset:56320
	global_load_lds_dwordx4 v[200:201], off
	v_lshl_add_u64 v[200:201], v[206:207], 0, s[88:89]
	s_mov_b32 m0, s59
	s_nop 0
	global_load_lds_dwordx4 v[200:201], off
	s_barrier
	s_waitcnt lgkmcnt(0)
	s_waitcnt lgkmcnt(0)
	v_mfma_f32_16x16x32_bf16 v[136:139], v[92:95], v[124:127], v[136:139]
	v_mfma_f32_16x16x32_bf16 v[140:143], v[116:119], v[124:127], v[140:143]
	v_mfma_f32_16x16x32_bf16 v[144:147], v[92:95], v[132:135], v[144:147]
	v_mfma_f32_16x16x32_bf16 v[148:151], v[116:119], v[132:135], v[148:151]
	v_mfma_f32_16x16x32_bf16 v[152:155], v[92:95], v[164:167], v[152:155]
	v_mfma_f32_16x16x32_bf16 v[156:159], v[116:119], v[164:167], v[156:159]
	v_mfma_f32_16x16x32_bf16 v[8:11], v[92:95], v[176:179], v[8:11]
	v_mfma_f32_16x16x32_bf16 v[12:15], v[116:119], v[176:179], v[12:15]
	v_mfma_f32_16x16x32_bf16 v[136:139], v[112:115], v[128:131], v[136:139]
	v_mfma_f32_16x16x32_bf16 v[140:143], v[120:123], v[128:131], v[140:143]
	v_mfma_f32_16x16x32_bf16 v[144:147], v[112:115], v[160:163], v[144:147]
	v_mfma_f32_16x16x32_bf16 v[148:151], v[120:123], v[160:163], v[148:151]
	v_mfma_f32_16x16x32_bf16 v[152:155], v[112:115], v[172:175], v[152:155]
	v_mfma_f32_16x16x32_bf16 v[156:159], v[120:123], v[172:175], v[156:159]
	v_mfma_f32_16x16x32_bf16 v[8:11], v[112:115], v[180:183], v[8:11]
	v_mfma_f32_16x16x32_bf16 v[12:15], v[120:123], v[180:183], v[12:15]
	s_barrier
	s_mov_b32 m0, s50
	v_lshl_add_u64 v[92:93], v[208:209], 0, s[88:89]
	global_load_lds_dwordx4 v[92:93], off
	v_lshl_add_u64 v[92:93], v[210:211], 0, s[88:89]
	s_mov_b32 m0, s49
	s_nop 0
	global_load_lds_dwordx4 v[92:93], off
	s_waitcnt vmcnt(6)
	s_barrier
	v_mfma_f32_16x16x32_bf16 v[16:19], v[184:187], v[124:127], v[16:19]
	v_mfma_f32_16x16x32_bf16 v[20:23], v[192:195], v[124:127], v[20:23]
	v_mfma_f32_16x16x32_bf16 v[52:55], v[184:187], v[132:135], v[52:55]
	v_mfma_f32_16x16x32_bf16 v[92:95], v[192:195], v[132:135], v[96:99]
	v_mfma_f32_16x16x32_bf16 v[96:99], v[184:187], v[164:167], v[100:103]
	v_mfma_f32_16x16x32_bf16 v[100:103], v[192:195], v[164:167], v[108:111]
	v_mfma_f32_16x16x32_bf16 v[84:87], v[184:187], v[176:179], v[84:87]
	v_mfma_f32_16x16x32_bf16 v[88:91], v[192:195], v[176:179], v[88:91]
	v_mfma_f32_16x16x32_bf16 v[16:19], v[188:191], v[128:131], v[16:19]
	v_mfma_f32_16x16x32_bf16 v[20:23], v[196:199], v[128:131], v[20:23]
	v_mfma_f32_16x16x32_bf16 v[52:55], v[188:191], v[160:163], v[52:55]
	v_mfma_f32_16x16x32_bf16 v[92:95], v[196:199], v[160:163], v[92:95]
	v_mfma_f32_16x16x32_bf16 v[96:99], v[188:191], v[172:175], v[96:99]
	v_mfma_f32_16x16x32_bf16 v[100:103], v[196:199], v[172:175], v[100:103]
	v_mfma_f32_16x16x32_bf16 v[84:87], v[188:191], v[180:183], v[84:87]
	v_mfma_f32_16x16x32_bf16 v[88:91], v[196:199], v[180:183], v[88:91]
	s_ashr_i32 s7, s6, 31
	s_ashr_i32 s13, s12, 31
	s_lshl_b64 s[6:7], s[6:7], 22
	s_add_u32 s36, s53, s6
	s_addc_u32 s37, s54, s7
	s_lshl_b64 s[6:7], s[12:13], 20
	v_mov_b32_e32 v109, v171
	s_add_u32 s6, s36, s6
	s_barrier
	s_addc_u32 s7, s37, s7
	s_lshl_b32 s12, s57, 8
	v_lshrrev_b32_e32 v108, 2, v109
	v_and_or_b32 v108, v108, 12, s12
	v_or_b32_e32 v108, s56, v108
	v_and_or_b32 v110, v109, 15, s55
	v_ashrrev_i32_e32 v109, 31, v108
	v_ashrrev_i32_e32 v111, 31, v110
	v_lshl_add_u64 v[108:109], v[108:109], 2, s[6:7]
	v_lshlrev_b64 v[112:113], 12, v[110:111]
	v_lshl_add_u64 v[112:113], v[108:109], 0, v[112:113]
	global_store_dwordx4 v[112:113], v[2:5], off
	global_store_dwordx4 v[112:113], v[56:59], off offset:64
	global_store_dwordx4 v[112:113], v[104:107], off offset:512
	global_store_dwordx4 v[112:113], v[24:27], off offset:576
	v_or_b32_e32 v2, 16, v110
	v_ashrrev_i32_e32 v3, 31, v2
	v_lshlrev_b64 v[2:3], 12, v[2:3]
	v_lshl_add_u64 v[2:3], v[108:109], 0, v[2:3]
	global_store_dwordx4 v[2:3], v[60:63], off
	global_store_dwordx4 v[2:3], v[64:67], off offset:64
	global_store_dwordx4 v[2:3], v[28:31], off offset:512
	global_store_dwordx4 v[2:3], v[32:35], off offset:576
	v_or_b32_e32 v2, 32, v110
	v_ashrrev_i32_e32 v3, 31, v2
	v_lshlrev_b64 v[2:3], 12, v[2:3]
	v_lshl_add_u64 v[2:3], v[108:109], 0, v[2:3]
	global_store_dwordx4 v[2:3], v[68:71], off
	global_store_dwordx4 v[2:3], v[72:75], off offset:64
	global_store_dwordx4 v[2:3], v[36:39], off offset:512
	global_store_dwordx4 v[2:3], v[40:43], off offset:576
	v_or_b32_e32 v2, 48, v110
	v_ashrrev_i32_e32 v3, 31, v2
	v_lshlrev_b64 v[2:3], 12, v[2:3]
	v_lshl_add_u64 v[2:3], v[108:109], 0, v[2:3]
	s_mov_b64 s[6:7], 0x80000
	global_store_dwordx4 v[2:3], v[76:79], off
	global_store_dwordx4 v[2:3], v[80:83], off offset:64
	global_store_dwordx4 v[2:3], v[44:47], off offset:512
	global_store_dwordx4 v[2:3], v[48:51], off offset:576
	v_lshl_add_u64 v[2:3], v[112:113], 0, s[6:7]
	s_mov_b32 s6, 0x80000
	v_add_co_u32_e32 v4, vcc, s6, v112
	s_mov_b64 s[6:7], 0x90000
	s_nop 0
	v_addc_co_u32_e32 v5, vcc, 0, v113, vcc
	global_store_dwordx4 v[4:5], v[136:139], off
	global_store_dwordx4 v[2:3], v[140:143], off offset:64
	global_store_dwordx4 v[2:3], v[16:19], off offset:512
	global_store_dwordx4 v[2:3], v[20:23], off offset:576
	v_lshl_add_u64 v[2:3], v[112:113], 0, s[6:7]
	s_mov_b32 s6, 0x90000
	v_add_co_u32_e32 v4, vcc, s6, v112
	s_mov_b64 s[6:7], 0xa0000
	s_nop 0
	v_addc_co_u32_e32 v5, vcc, 0, v113, vcc
	global_store_dwordx4 v[4:5], v[144:147], off
	global_store_dwordx4 v[2:3], v[148:151], off offset:64
	global_store_dwordx4 v[2:3], v[52:55], off offset:512
	global_store_dwordx4 v[2:3], v[92:95], off offset:576
	v_lshl_add_u64 v[2:3], v[112:113], 0, s[6:7]
	s_mov_b32 s6, 0xa0000
	v_add_co_u32_e32 v4, vcc, s6, v112
	s_mov_b64 s[6:7], 0xb0000
	s_nop 0
	v_addc_co_u32_e32 v5, vcc, 0, v113, vcc
	global_store_dwordx4 v[4:5], v[152:155], off
	global_store_dwordx4 v[2:3], v[156:159], off offset:64
	global_store_dwordx4 v[2:3], v[96:99], off offset:512
	global_store_dwordx4 v[2:3], v[100:103], off offset:576
	v_add_co_u32_e32 v4, vcc, 0xb0000, v112
	v_lshl_add_u64 v[2:3], v[112:113], 0, s[6:7]
	s_nop 0
	v_addc_co_u32_e32 v5, vcc, 0, v113, vcc
	global_store_dwordx4 v[4:5], v[8:11], off
	global_store_dwordx4 v[2:3], v[12:15], off offset:64
	global_store_dwordx4 v[2:3], v[84:87], off offset:512
	global_store_dwordx4 v[2:3], v[88:91], off offset:576
	s_add_i32 s60, s60, s96
	s_andn2_b64 vcc, exec, s[40:41]
	s_mov_b32 s6, s46
	s_mov_b32 s57, s62
	s_mov_b32 s12, s61
	s_mov_b64 s[48:49], s[44:45]
	s_mov_b64 s[50:51], s[42:43]
	s_cbranch_vccz .LBB0_728
